# hyena: make_spec radix-8 passes and the fft_conv radix-16 middle (dif16, f16 spectrum multiply, dit16) rewritten with packed-f32 2-instruction complex multiplies, spectrum LDS reads issued early
# speedup vs baseline: 1.0312x; 1.0119x over previous
; #define LAS __attribute__((address_space(3)))
; __device__ __forceinline__ int otid() { int t = threadIdx.x; asm volatile("" : "+v"(t)); return t; }
; __device__ __forceinline__ cf twc(cf ws, int k16) { if (k16 == 0) return ws; if (k16 == 4) return cf{ws.y, -ws.x}; return cmul(ws, cf{c16(k16), -s16(k16)}); }
; template <int LR> __device__ __forceinline__ void dif_reg(cf (&x)[1 << LR], cf w) {
;     constexpr int R = 1 << LR; cf ws = w;
; #pragma unroll
;     for (int s = 0; s < LR; ++s) { const int half = R >> (s + 1);
; #pragma unroll
;         for (int m0 = 0; m0 < R; m0 += 2 * half)
; #pragma unroll
;             for (int mm = 0; mm < half; ++mm) { const int ia = m0 + mm, ib = ia + half; const cf a = x[ia], b = x[ib];
;                 x[ia] = cf{a.x + b.x, a.y + b.y}; const cf d{a.x - b.x, a.y - b.y};
;                 x[ib] = cmul(d, twc(ws, (mm << s) * (16 / R))); }
;         ws = cmul(ws, ws); }
; }
; template <int LR, bool INV> __device__ __forceinline__ void fft_pass(ldsf2 buf, int base, int stride, int twi) {
;     constexpr int R = 1 << LR; cf x[R];
;     const v2f wv = ((ldsf2)((LAS unsigned char*)buf + 139264))[twi];
; #pragma unroll
;     for (int m = 0; m < R; ++m) { const v2f v = buf[base + m * stride]; x[m] = cf{v.x, v.y}; }
;     const cf w{wv.x, wv.y};
;     if (INV) dit_reg<LR>(x, w); else dif_reg<LR>(x, w);
; #pragma unroll
;     for (int m = 0; m < R; ++m) buf[base + m * stride] = mkv2(x[m].x, x[m].y);
; }
; __device__ __forceinline__ void wave_lds_fence() { asm volatile("s_waitcnt lgkmcnt(0)" ::: "memory"); }
; __device__ __forceinline__ void fft_fwd_abc(ldsf2 buf) {
;     const int tid = otid(); const int wv = tid >> 6, l = tid & 63;
; #pragma unroll 1
;     for (int u = 0; u < 2; ++u) { const int bf = tid + NT * u; fft_pass<3, false>(buf, bf + (bf >> 4), 1088, bf); }
.LBB0_334:
	v_cndmask_b32_e64 v3, 0, 1, s[10:11]
	v_add_u32_e32 v4, s0, v2
	v_cmp_ne_u32_e32 vcc, 1, v3
	v_ashrrev_i32_e32 v3, 4, v4
	v_lshl_add_u32 v4, v4, 3, 0
	v_add_u32_e32 v5, 0x22000, v4
	v_lshl_add_u32 v3, v3, 3, v4
	ds_read_b64 v[28:29], v5
	ds_read2st64_b64 v[4:7], v3 offset1:17
	ds_read2st64_b64 v[8:11], v3 offset0:68 offset1:85
	ds_read2st64_b64 v[12:15], v3 offset0:34 offset1:51
	ds_read2st64_b64 v[24:27], v3 offset0:102 offset1:119
	s_waitcnt lgkmcnt(4)
	v_pk_add_f32 v[30:31], v[28:29], v[28:29] op_sel:[0,1] op_sel_hi:[1,0] neg_lo:[0,0] neg_hi:[0,1]
	v_pk_mul_f32 v[32:33], v[30:31], s[16:17] op_sel:[0,0] op_sel_hi:[1,0]
	v_pk_mul_f32 v[34:35], v[30:31], s[16:17] op_sel:[1,0] op_sel_hi:[0,0] neg_lo:[0,0] neg_hi:[1,0]
	v_pk_mul_f32 v[36:37], v[28:29], v[28:29] op_sel:[1,1] op_sel_hi:[1,0]
	v_pk_fma_f32 v[36:37], v[28:29], v[28:29], v[36:37] op_sel:[0,0,0] op_sel_hi:[0,1,1] neg_lo:[0,0,1] neg_hi:[0,0,0]
	v_pk_mul_f32 v[38:39], v[36:37], v[36:37] op_sel:[1,1] op_sel_hi:[1,0]
	v_pk_fma_f32 v[38:39], v[36:37], v[36:37], v[38:39] op_sel:[0,0,0] op_sel_hi:[0,1,1] neg_lo:[0,0,1] neg_hi:[0,0,0]
	s_waitcnt lgkmcnt(0)
	v_pk_add_f32 v[40:41], v[4:5], v[8:9] neg_lo:[0,1] neg_hi:[0,1]
	v_pk_add_f32 v[42:43], v[6:7], v[10:11] neg_lo:[0,1] neg_hi:[0,1]
	v_pk_add_f32 v[44:45], v[12:13], v[24:25] neg_lo:[0,1] neg_hi:[0,1]
	v_pk_add_f32 v[46:47], v[14:15], v[26:27] neg_lo:[0,1] neg_hi:[0,1]
	v_pk_add_f32 v[4:5], v[4:5], v[8:9]
	v_pk_add_f32 v[6:7], v[6:7], v[10:11]
	v_pk_add_f32 v[12:13], v[12:13], v[24:25]
	v_pk_add_f32 v[14:15], v[14:15], v[26:27]
	v_pk_mul_f32 v[8:9], v[40:41], v[28:29] op_sel:[1,1] op_sel_hi:[1,0]
	v_pk_mul_f32 v[10:11], v[42:43], v[32:33] op_sel:[1,1] op_sel_hi:[1,0]
	v_pk_mul_f32 v[24:25], v[44:45], v[28:29] op_sel:[1,0] op_sel_hi:[1,1]
	v_pk_mul_f32 v[26:27], v[46:47], v[34:35] op_sel:[1,1] op_sel_hi:[1,0]
	v_pk_fma_f32 v[8:9], v[40:41], v[28:29], v[8:9] op_sel:[0,0,0] op_sel_hi:[0,1,1] neg_lo:[0,0,1] neg_hi:[0,0,0]
	v_pk_fma_f32 v[10:11], v[42:43], v[32:33], v[10:11] op_sel:[0,0,0] op_sel_hi:[0,1,1] neg_lo:[0,0,1] neg_hi:[0,0,0]
	v_pk_fma_f32 v[24:25], v[44:45], v[28:29], v[24:25] op_sel:[0,1,0] op_sel_hi:[0,0,1] neg_lo:[0,0,0] neg_hi:[0,1,0]
	v_pk_fma_f32 v[26:27], v[46:47], v[34:35], v[26:27] op_sel:[0,0,0] op_sel_hi:[0,1,1] neg_lo:[0,0,1] neg_hi:[0,0,0]
	v_pk_add_f32 v[40:41], v[4:5], v[12:13] neg_lo:[0,1] neg_hi:[0,1]
	v_pk_add_f32 v[42:43], v[6:7], v[14:15] neg_lo:[0,1] neg_hi:[0,1]
	v_pk_add_f32 v[44:45], v[8:9], v[24:25] neg_lo:[0,1] neg_hi:[0,1]
	v_pk_add_f32 v[46:47], v[10:11], v[26:27] neg_lo:[0,1] neg_hi:[0,1]
	v_pk_add_f32 v[4:5], v[4:5], v[12:13]
	v_pk_add_f32 v[6:7], v[6:7], v[14:15]
	v_pk_add_f32 v[8:9], v[8:9], v[24:25]
	v_pk_add_f32 v[10:11], v[10:11], v[26:27]
	v_pk_mul_f32 v[12:13], v[40:41], v[36:37] op_sel:[1,1] op_sel_hi:[1,0]
	v_pk_mul_f32 v[14:15], v[42:43], v[36:37] op_sel:[1,0] op_sel_hi:[1,1]
	v_pk_mul_f32 v[24:25], v[44:45], v[36:37] op_sel:[1,1] op_sel_hi:[1,0]
	v_pk_mul_f32 v[26:27], v[46:47], v[36:37] op_sel:[1,0] op_sel_hi:[1,1]
	v_pk_fma_f32 v[12:13], v[40:41], v[36:37], v[12:13] op_sel:[0,0,0] op_sel_hi:[0,1,1] neg_lo:[0,0,1] neg_hi:[0,0,0]
	v_pk_fma_f32 v[14:15], v[42:43], v[36:37], v[14:15] op_sel:[0,1,0] op_sel_hi:[0,0,1] neg_lo:[0,0,0] neg_hi:[0,1,0]
	v_pk_fma_f32 v[24:25], v[44:45], v[36:37], v[24:25] op_sel:[0,0,0] op_sel_hi:[0,1,1] neg_lo:[0,0,1] neg_hi:[0,0,0]
	v_pk_fma_f32 v[26:27], v[46:47], v[36:37], v[26:27] op_sel:[0,1,0] op_sel_hi:[0,0,1] neg_lo:[0,0,0] neg_hi:[0,1,0]
	v_pk_add_f32 v[40:41], v[4:5], v[6:7] neg_lo:[0,1] neg_hi:[0,1]
	v_pk_add_f32 v[42:43], v[12:13], v[14:15] neg_lo:[0,1] neg_hi:[0,1]
	v_pk_add_f32 v[44:45], v[8:9], v[10:11] neg_lo:[0,1] neg_hi:[0,1]
	v_pk_add_f32 v[46:47], v[24:25], v[26:27] neg_lo:[0,1] neg_hi:[0,1]
	v_pk_add_f32 v[4:5], v[4:5], v[6:7]
	v_pk_add_f32 v[12:13], v[12:13], v[14:15]
	v_pk_add_f32 v[8:9], v[8:9], v[10:11]
	v_pk_add_f32 v[24:25], v[24:25], v[26:27]
	v_pk_mul_f32 v[6:7], v[40:41], v[38:39] op_sel:[1,1] op_sel_hi:[1,0]
	v_pk_mul_f32 v[14:15], v[42:43], v[38:39] op_sel:[1,1] op_sel_hi:[1,0]
	v_pk_mul_f32 v[10:11], v[44:45], v[38:39] op_sel:[1,1] op_sel_hi:[1,0]
	v_pk_mul_f32 v[26:27], v[46:47], v[38:39] op_sel:[1,1] op_sel_hi:[1,0]
	v_pk_fma_f32 v[6:7], v[40:41], v[38:39], v[6:7] op_sel:[0,0,0] op_sel_hi:[0,1,1] neg_lo:[0,0,1] neg_hi:[0,0,0]
	v_pk_fma_f32 v[14:15], v[42:43], v[38:39], v[14:15] op_sel:[0,0,0] op_sel_hi:[0,1,1] neg_lo:[0,0,1] neg_hi:[0,0,0]
	v_pk_fma_f32 v[10:11], v[44:45], v[38:39], v[10:11] op_sel:[0,0,0] op_sel_hi:[0,1,1] neg_lo:[0,0,1] neg_hi:[0,0,0]
	v_pk_fma_f32 v[26:27], v[46:47], v[38:39], v[26:27] op_sel:[0,0,0] op_sel_hi:[0,1,1] neg_lo:[0,0,1] neg_hi:[0,0,0]
	ds_write2st64_b64 v3, v[4:5], v[6:7] offset1:17
	ds_write2st64_b64 v3, v[12:13], v[14:15] offset0:34 offset1:51
	ds_write2st64_b64 v3, v[8:9], v[10:11] offset0:68 offset1:85
	ds_write2st64_b64 v3, v[24:25], v[26:27] offset0:102 offset1:119
	s_movk_i32 s0, 0x200
	s_mov_b64 s[10:11], 0
	s_cbranch_vccz .LBB0_334
	s_waitcnt lgkmcnt(0)
	s_barrier
	v_lshlrev_b32_e32 v4, 4, v2
	v_and_b32_e32 v3, 63, v2
	v_and_b32_e32 v4, 0xfffffc00, v4
	s_mov_b32 s0, 0
	s_mov_b64 s[10:11], -1
; #define LAS __attribute__((address_space(3)))
; __device__ __forceinline__ int otid() { int t = threadIdx.x; asm volatile("" : "+v"(t)); return t; }
; __device__ __forceinline__ cf twc(cf ws, int k16) { if (k16 == 0) return ws; if (k16 == 4) return cf{ws.y, -ws.x}; return cmul(ws, cf{c16(k16), -s16(k16)}); }
; __device__ __forceinline__ void lds_barrier() { asm volatile("s_waitcnt lgkmcnt(0)\n\ts_barrier" ::: "memory"); }
; template <int LR> __device__ __forceinline__ void dif_reg(cf (&x)[1 << LR], cf w) {
;     constexpr int R = 1 << LR; cf ws = w;
; #pragma unroll
;     for (int s = 0; s < LR; ++s) { const int half = R >> (s + 1);
; #pragma unroll
;         for (int m0 = 0; m0 < R; m0 += 2 * half)
; #pragma unroll
;             for (int mm = 0; mm < half; ++mm) { const int ia = m0 + mm, ib = ia + half; const cf a = x[ia], b = x[ib];
;                 x[ia] = cf{a.x + b.x, a.y + b.y}; const cf d{a.x - b.x, a.y - b.y};
;                 x[ib] = cmul(d, twc(ws, (mm << s) * (16 / R))); }
;         ws = cmul(ws, ws); }
; }
; template <int LR, bool INV> __device__ __forceinline__ void fft_pass(ldsf2 buf, int base, int stride, int twi) {
;     constexpr int R = 1 << LR; cf x[R];
;     const v2f wv = ((ldsf2)((LAS unsigned char*)buf + 139264))[twi];
; #pragma unroll
;     for (int m = 0; m < R; ++m) { const v2f v = buf[base + m * stride]; x[m] = cf{v.x, v.y}; }
;     const cf w{wv.x, wv.y};
;     if (INV) dit_reg<LR>(x, w); else dif_reg<LR>(x, w);
; #pragma unroll
;     for (int m = 0; m < R; ++m) buf[base + m * stride] = mkv2(x[m].x, x[m].y);
; }
; __device__ __forceinline__ void wave_lds_fence() { asm volatile("s_waitcnt lgkmcnt(0)" ::: "memory"); }
; __device__ __forceinline__ void fft_fwd_abc(ldsf2 buf) {
;     const int tid = otid(); const int wv = tid >> 6, l = tid & 63;
; #pragma unroll 1
;     for (int u = 0; u < 2; ++u) { const int bf = tid + NT * u; fft_pass<3, false>(buf, bf + (bf >> 4), 1088, bf); }
;     lds_barrier();
; #pragma unroll 1
;     for (int u = 0; u < 2; ++u) { const int o = l + 64 * u, e0 = wv * 1024 + o; fft_pass<3, false>(buf, e0 + (e0 >> 4), 136, o * 8); }
.LBB0_336:
	v_cndmask_b32_e64 v5, 0, 1, s[10:11]
	v_or_b32_e32 v6, s0, v3
	v_cmp_ne_u32_e32 vcc, 1, v5
	v_or_b32_e32 v5, v6, v4
	v_lshl_add_u32 v6, v6, 6, 0
	v_ashrrev_i32_e32 v7, 4, v5
	v_add_u32_e32 v6, 0x22000, v6
	v_lshlrev_b32_e32 v5, 3, v5
	ds_read_b64 v[14:15], v6
	v_lshlrev_b32_e32 v6, 3, v7
	v_add3_u32 v5, 0, v5, v6
	v_add_u32_e32 v53, 0x800, v5
	ds_read2_b64 v[6:9], v5 offset1:136
	v_add_u32_e32 v58, 0x1000, v5
	v_add_u32_e32 v59, 0x1800, v5
	ds_read2_b64 v[10:13], v53 offset0:16 offset1:152
	ds_read2_b64 v[24:27], v58 offset0:32 offset1:168
	ds_read2_b64 v[28:31], v59 offset0:48 offset1:184
	s_waitcnt lgkmcnt(4)
	v_pk_add_f32 v[32:33], v[14:15], v[14:15] op_sel:[0,1] op_sel_hi:[1,0] neg_lo:[0,0] neg_hi:[0,1]
	v_pk_mul_f32 v[34:35], v[32:33], s[16:17] op_sel:[0,0] op_sel_hi:[1,0]
	v_pk_mul_f32 v[36:37], v[32:33], s[16:17] op_sel:[1,0] op_sel_hi:[0,0] neg_lo:[0,0] neg_hi:[1,0]
	v_pk_mul_f32 v[38:39], v[14:15], v[14:15] op_sel:[1,1] op_sel_hi:[1,0]
	v_pk_fma_f32 v[38:39], v[14:15], v[14:15], v[38:39] op_sel:[0,0,0] op_sel_hi:[0,1,1] neg_lo:[0,0,1] neg_hi:[0,0,0]
	v_pk_mul_f32 v[40:41], v[38:39], v[38:39] op_sel:[1,1] op_sel_hi:[1,0]
	v_pk_fma_f32 v[40:41], v[38:39], v[38:39], v[40:41] op_sel:[0,0,0] op_sel_hi:[0,1,1] neg_lo:[0,0,1] neg_hi:[0,0,0]
	s_waitcnt lgkmcnt(0)
	v_pk_add_f32 v[42:43], v[6:7], v[24:25] neg_lo:[0,1] neg_hi:[0,1]
	v_pk_add_f32 v[44:45], v[8:9], v[26:27] neg_lo:[0,1] neg_hi:[0,1]
	v_pk_add_f32 v[46:47], v[10:11], v[28:29] neg_lo:[0,1] neg_hi:[0,1]
	v_pk_add_f32 v[48:49], v[12:13], v[30:31] neg_lo:[0,1] neg_hi:[0,1]
	v_pk_add_f32 v[6:7], v[6:7], v[24:25]
	v_pk_add_f32 v[8:9], v[8:9], v[26:27]
	v_pk_add_f32 v[10:11], v[10:11], v[28:29]
	v_pk_add_f32 v[12:13], v[12:13], v[30:31]
	v_pk_mul_f32 v[24:25], v[42:43], v[14:15] op_sel:[1,1] op_sel_hi:[1,0]
	v_pk_mul_f32 v[26:27], v[44:45], v[34:35] op_sel:[1,1] op_sel_hi:[1,0]
	v_pk_mul_f32 v[28:29], v[46:47], v[14:15] op_sel:[1,0] op_sel_hi:[1,1]
	v_pk_mul_f32 v[30:31], v[48:49], v[36:37] op_sel:[1,1] op_sel_hi:[1,0]
	v_pk_fma_f32 v[24:25], v[42:43], v[14:15], v[24:25] op_sel:[0,0,0] op_sel_hi:[0,1,1] neg_lo:[0,0,1] neg_hi:[0,0,0]
	v_pk_fma_f32 v[26:27], v[44:45], v[34:35], v[26:27] op_sel:[0,0,0] op_sel_hi:[0,1,1] neg_lo:[0,0,1] neg_hi:[0,0,0]
	v_pk_fma_f32 v[28:29], v[46:47], v[14:15], v[28:29] op_sel:[0,1,0] op_sel_hi:[0,0,1] neg_lo:[0,0,0] neg_hi:[0,1,0]
	v_pk_fma_f32 v[30:31], v[48:49], v[36:37], v[30:31] op_sel:[0,0,0] op_sel_hi:[0,1,1] neg_lo:[0,0,1] neg_hi:[0,0,0]
	v_pk_add_f32 v[42:43], v[6:7], v[10:11] neg_lo:[0,1] neg_hi:[0,1]
	v_pk_add_f32 v[44:45], v[8:9], v[12:13] neg_lo:[0,1] neg_hi:[0,1]
	v_pk_add_f32 v[46:47], v[24:25], v[28:29] neg_lo:[0,1] neg_hi:[0,1]
	v_pk_add_f32 v[48:49], v[26:27], v[30:31] neg_lo:[0,1] neg_hi:[0,1]
	v_pk_add_f32 v[6:7], v[6:7], v[10:11]
	v_pk_add_f32 v[8:9], v[8:9], v[12:13]
	v_pk_add_f32 v[24:25], v[24:25], v[28:29]
	v_pk_add_f32 v[26:27], v[26:27], v[30:31]
	v_pk_mul_f32 v[10:11], v[42:43], v[38:39] op_sel:[1,1] op_sel_hi:[1,0]
	v_pk_mul_f32 v[12:13], v[44:45], v[38:39] op_sel:[1,0] op_sel_hi:[1,1]
	v_pk_mul_f32 v[28:29], v[46:47], v[38:39] op_sel:[1,1] op_sel_hi:[1,0]
	v_pk_mul_f32 v[30:31], v[48:49], v[38:39] op_sel:[1,0] op_sel_hi:[1,1]
	v_pk_fma_f32 v[10:11], v[42:43], v[38:39], v[10:11] op_sel:[0,0,0] op_sel_hi:[0,1,1] neg_lo:[0,0,1] neg_hi:[0,0,0]
	v_pk_fma_f32 v[12:13], v[44:45], v[38:39], v[12:13] op_sel:[0,1,0] op_sel_hi:[0,0,1] neg_lo:[0,0,0] neg_hi:[0,1,0]
	v_pk_fma_f32 v[28:29], v[46:47], v[38:39], v[28:29] op_sel:[0,0,0] op_sel_hi:[0,1,1] neg_lo:[0,0,1] neg_hi:[0,0,0]
	v_pk_fma_f32 v[30:31], v[48:49], v[38:39], v[30:31] op_sel:[0,1,0] op_sel_hi:[0,0,1] neg_lo:[0,0,0] neg_hi:[0,1,0]
	v_pk_add_f32 v[42:43], v[6:7], v[8:9] neg_lo:[0,1] neg_hi:[0,1]
	v_pk_add_f32 v[44:45], v[10:11], v[12:13] neg_lo:[0,1] neg_hi:[0,1]
	v_pk_add_f32 v[46:47], v[24:25], v[26:27] neg_lo:[0,1] neg_hi:[0,1]
	v_pk_add_f32 v[48:49], v[28:29], v[30:31] neg_lo:[0,1] neg_hi:[0,1]
	v_pk_add_f32 v[6:7], v[6:7], v[8:9]
	v_pk_add_f32 v[10:11], v[10:11], v[12:13]
	v_pk_add_f32 v[24:25], v[24:25], v[26:27]
	v_pk_add_f32 v[28:29], v[28:29], v[30:31]
	v_pk_mul_f32 v[8:9], v[42:43], v[40:41] op_sel:[1,1] op_sel_hi:[1,0]
	v_pk_mul_f32 v[12:13], v[44:45], v[40:41] op_sel:[1,1] op_sel_hi:[1,0]
	v_pk_mul_f32 v[26:27], v[46:47], v[40:41] op_sel:[1,1] op_sel_hi:[1,0]
	v_pk_mul_f32 v[30:31], v[48:49], v[40:41] op_sel:[1,1] op_sel_hi:[1,0]
	v_pk_fma_f32 v[8:9], v[42:43], v[40:41], v[8:9] op_sel:[0,0,0] op_sel_hi:[0,1,1] neg_lo:[0,0,1] neg_hi:[0,0,0]
	v_pk_fma_f32 v[12:13], v[44:45], v[40:41], v[12:13] op_sel:[0,0,0] op_sel_hi:[0,1,1] neg_lo:[0,0,1] neg_hi:[0,0,0]
	v_pk_fma_f32 v[26:27], v[46:47], v[40:41], v[26:27] op_sel:[0,0,0] op_sel_hi:[0,1,1] neg_lo:[0,0,1] neg_hi:[0,0,0]
	v_pk_fma_f32 v[30:31], v[48:49], v[40:41], v[30:31] op_sel:[0,0,0] op_sel_hi:[0,1,1] neg_lo:[0,0,1] neg_hi:[0,0,0]
	ds_write2_b64 v5, v[6:7], v[8:9] offset1:136
	ds_write2_b64 v53, v[10:11], v[12:13] offset0:16 offset1:152
	ds_write2_b64 v58, v[24:25], v[26:27] offset0:32 offset1:168
	ds_write2_b64 v59, v[28:29], v[30:31] offset0:48 offset1:184
	s_mov_b32 s0, 64
	s_mov_b64 s[10:11], 0
	s_cbranch_vccz .LBB0_336
	v_and_b32_e32 v2, 15, v2
	s_waitcnt lgkmcnt(0)
	v_lshlrev_b32_e32 v3, 3, v3
	v_lshlrev_b32_e32 v5, 9, v2
	v_and_or_b32 v3, v3, s90, v4
	v_add_u32_e32 v4, 0, v5
	v_lshl_add_u32 v2, v2, 3, 0
	s_mov_b32 s0, 0
	s_mov_b64 s[10:11], -1
	v_add_u32_e32 v4, 0x22000, v4
; #define LAS __attribute__((address_space(3)))
; __device__ __forceinline__ int otid() { int t = threadIdx.x; asm volatile("" : "+v"(t)); return t; }
; __device__ __forceinline__ cf twc(cf ws, int k16) { if (k16 == 0) return ws; if (k16 == 4) return cf{ws.y, -ws.x}; return cmul(ws, cf{c16(k16), -s16(k16)}); }
; __device__ __forceinline__ void lds_barrier() { asm volatile("s_waitcnt lgkmcnt(0)\n\ts_barrier" ::: "memory"); }
; template <int LR> __device__ __forceinline__ void dif_reg(cf (&x)[1 << LR], cf w) {
;     constexpr int R = 1 << LR; cf ws = w;
; #pragma unroll
;     for (int s = 0; s < LR; ++s) { const int half = R >> (s + 1);
; #pragma unroll
;         for (int m0 = 0; m0 < R; m0 += 2 * half)
; #pragma unroll
;             for (int mm = 0; mm < half; ++mm) { const int ia = m0 + mm, ib = ia + half; const cf a = x[ia], b = x[ib];
;                 x[ia] = cf{a.x + b.x, a.y + b.y}; const cf d{a.x - b.x, a.y - b.y};
;                 x[ib] = cmul(d, twc(ws, (mm << s) * (16 / R))); }
;         ws = cmul(ws, ws); }
; }
; template <int LR, bool INV> __device__ __forceinline__ void fft_pass(ldsf2 buf, int base, int stride, int twi) {
;     constexpr int R = 1 << LR; cf x[R];
;     const v2f wv = ((ldsf2)((LAS unsigned char*)buf + 139264))[twi];
; #pragma unroll
;     for (int m = 0; m < R; ++m) { const v2f v = buf[base + m * stride]; x[m] = cf{v.x, v.y}; }
;     const cf w{wv.x, wv.y};
;     if (INV) dit_reg<LR>(x, w); else dif_reg<LR>(x, w);
; #pragma unroll
;     for (int m = 0; m < R; ++m) buf[base + m * stride] = mkv2(x[m].x, x[m].y);
; }
; __device__ __forceinline__ void wave_lds_fence() { asm volatile("s_waitcnt lgkmcnt(0)" ::: "memory"); }
; __device__ __forceinline__ void fft_fwd_abc(ldsf2 buf) {
;     const int tid = otid(); const int wv = tid >> 6, l = tid & 63;
; #pragma unroll 1
;     for (int u = 0; u < 2; ++u) { const int bf = tid + NT * u; fft_pass<3, false>(buf, bf + (bf >> 4), 1088, bf); }
;     lds_barrier();
; #pragma unroll 1
;     for (int u = 0; u < 2; ++u) { const int o = l + 64 * u, e0 = wv * 1024 + o; fft_pass<3, false>(buf, e0 + (e0 >> 4), 136, o * 8); }
;     wave_lds_fence();
; #pragma unroll 1
;     for (int u = 0; u < 2; ++u) { const int j = l + 64 * u, o = j & 15, e0 = wv * 1024 + (j >> 4) * 128 + o; fft_pass<3, false>(buf, e0 + (e0 >> 4), 17, o * 64); }
.LBB0_338:
	v_or_b32_e32 v5, s0, v3
	ds_read_b64 v[14:15], v4
	v_lshlrev_b32_e32 v6, 3, v5
	v_ashrrev_i32_e32 v5, 1, v5
	v_add3_u32 v5, v2, v6, v5
	ds_read2_b64 v[6:9], v5 offset1:17
	ds_read2_b64 v[10:13], v5 offset0:34 offset1:51
	ds_read2_b64 v[24:27], v5 offset0:68 offset1:85
	ds_read2_b64 v[28:31], v5 offset0:102 offset1:119
	s_waitcnt lgkmcnt(4)
	v_pk_add_f32 v[32:33], v[14:15], v[14:15] op_sel:[0,1] op_sel_hi:[1,0] neg_lo:[0,0] neg_hi:[0,1]
	v_pk_mul_f32 v[34:35], v[32:33], s[16:17] op_sel:[0,0] op_sel_hi:[1,0]
	v_pk_mul_f32 v[36:37], v[32:33], s[16:17] op_sel:[1,0] op_sel_hi:[0,0] neg_lo:[0,0] neg_hi:[1,0]
	v_pk_mul_f32 v[38:39], v[14:15], v[14:15] op_sel:[1,1] op_sel_hi:[1,0]
	v_pk_fma_f32 v[38:39], v[14:15], v[14:15], v[38:39] op_sel:[0,0,0] op_sel_hi:[0,1,1] neg_lo:[0,0,1] neg_hi:[0,0,0]
	v_pk_mul_f32 v[40:41], v[38:39], v[38:39] op_sel:[1,1] op_sel_hi:[1,0]
	v_pk_fma_f32 v[40:41], v[38:39], v[38:39], v[40:41] op_sel:[0,0,0] op_sel_hi:[0,1,1] neg_lo:[0,0,1] neg_hi:[0,0,0]
	s_waitcnt lgkmcnt(0)
	v_pk_add_f32 v[42:43], v[6:7], v[24:25] neg_lo:[0,1] neg_hi:[0,1]
	v_pk_add_f32 v[44:45], v[8:9], v[26:27] neg_lo:[0,1] neg_hi:[0,1]
	v_pk_add_f32 v[46:47], v[10:11], v[28:29] neg_lo:[0,1] neg_hi:[0,1]
	v_pk_add_f32 v[48:49], v[12:13], v[30:31] neg_lo:[0,1] neg_hi:[0,1]
	v_pk_add_f32 v[6:7], v[6:7], v[24:25]
	v_pk_add_f32 v[8:9], v[8:9], v[26:27]
	v_pk_add_f32 v[10:11], v[10:11], v[28:29]
	v_pk_add_f32 v[12:13], v[12:13], v[30:31]
	v_pk_mul_f32 v[24:25], v[42:43], v[14:15] op_sel:[1,1] op_sel_hi:[1,0]
	v_pk_mul_f32 v[26:27], v[44:45], v[34:35] op_sel:[1,1] op_sel_hi:[1,0]
	v_pk_mul_f32 v[28:29], v[46:47], v[14:15] op_sel:[1,0] op_sel_hi:[1,1]
	v_pk_mul_f32 v[30:31], v[48:49], v[36:37] op_sel:[1,1] op_sel_hi:[1,0]
	v_pk_fma_f32 v[24:25], v[42:43], v[14:15], v[24:25] op_sel:[0,0,0] op_sel_hi:[0,1,1] neg_lo:[0,0,1] neg_hi:[0,0,0]
	v_pk_fma_f32 v[26:27], v[44:45], v[34:35], v[26:27] op_sel:[0,0,0] op_sel_hi:[0,1,1] neg_lo:[0,0,1] neg_hi:[0,0,0]
	v_pk_fma_f32 v[28:29], v[46:47], v[14:15], v[28:29] op_sel:[0,1,0] op_sel_hi:[0,0,1] neg_lo:[0,0,0] neg_hi:[0,1,0]
	v_pk_fma_f32 v[30:31], v[48:49], v[36:37], v[30:31] op_sel:[0,0,0] op_sel_hi:[0,1,1] neg_lo:[0,0,1] neg_hi:[0,0,0]
	v_pk_add_f32 v[42:43], v[6:7], v[10:11] neg_lo:[0,1] neg_hi:[0,1]
	v_pk_add_f32 v[44:45], v[8:9], v[12:13] neg_lo:[0,1] neg_hi:[0,1]
	v_pk_add_f32 v[46:47], v[24:25], v[28:29] neg_lo:[0,1] neg_hi:[0,1]
	v_pk_add_f32 v[48:49], v[26:27], v[30:31] neg_lo:[0,1] neg_hi:[0,1]
	v_pk_add_f32 v[6:7], v[6:7], v[10:11]
	v_pk_add_f32 v[8:9], v[8:9], v[12:13]
	v_pk_add_f32 v[24:25], v[24:25], v[28:29]
	v_pk_add_f32 v[26:27], v[26:27], v[30:31]
	v_pk_mul_f32 v[10:11], v[42:43], v[38:39] op_sel:[1,1] op_sel_hi:[1,0]
	v_pk_mul_f32 v[12:13], v[44:45], v[38:39] op_sel:[1,0] op_sel_hi:[1,1]
	v_pk_mul_f32 v[28:29], v[46:47], v[38:39] op_sel:[1,1] op_sel_hi:[1,0]
	v_pk_mul_f32 v[30:31], v[48:49], v[38:39] op_sel:[1,0] op_sel_hi:[1,1]
	v_pk_fma_f32 v[10:11], v[42:43], v[38:39], v[10:11] op_sel:[0,0,0] op_sel_hi:[0,1,1] neg_lo:[0,0,1] neg_hi:[0,0,0]
	v_pk_fma_f32 v[12:13], v[44:45], v[38:39], v[12:13] op_sel:[0,1,0] op_sel_hi:[0,0,1] neg_lo:[0,0,0] neg_hi:[0,1,0]
	v_pk_fma_f32 v[28:29], v[46:47], v[38:39], v[28:29] op_sel:[0,0,0] op_sel_hi:[0,1,1] neg_lo:[0,0,1] neg_hi:[0,0,0]
	v_pk_fma_f32 v[30:31], v[48:49], v[38:39], v[30:31] op_sel:[0,1,0] op_sel_hi:[0,0,1] neg_lo:[0,0,0] neg_hi:[0,1,0]
	v_pk_add_f32 v[42:43], v[6:7], v[8:9] neg_lo:[0,1] neg_hi:[0,1]
	v_pk_add_f32 v[44:45], v[10:11], v[12:13] neg_lo:[0,1] neg_hi:[0,1]
	v_pk_add_f32 v[46:47], v[24:25], v[26:27] neg_lo:[0,1] neg_hi:[0,1]
	v_pk_add_f32 v[48:49], v[28:29], v[30:31] neg_lo:[0,1] neg_hi:[0,1]
	v_pk_add_f32 v[6:7], v[6:7], v[8:9]
	v_pk_add_f32 v[10:11], v[10:11], v[12:13]
	v_pk_add_f32 v[24:25], v[24:25], v[26:27]
	v_pk_add_f32 v[28:29], v[28:29], v[30:31]
	v_pk_mul_f32 v[8:9], v[42:43], v[40:41] op_sel:[1,1] op_sel_hi:[1,0]
	v_pk_mul_f32 v[12:13], v[44:45], v[40:41] op_sel:[1,1] op_sel_hi:[1,0]
	v_pk_mul_f32 v[26:27], v[46:47], v[40:41] op_sel:[1,1] op_sel_hi:[1,0]
	v_pk_mul_f32 v[30:31], v[48:49], v[40:41] op_sel:[1,1] op_sel_hi:[1,0]
	v_pk_fma_f32 v[8:9], v[42:43], v[40:41], v[8:9] op_sel:[0,0,0] op_sel_hi:[0,1,1] neg_lo:[0,0,1] neg_hi:[0,0,0]
	v_pk_fma_f32 v[12:13], v[44:45], v[40:41], v[12:13] op_sel:[0,0,0] op_sel_hi:[0,1,1] neg_lo:[0,0,1] neg_hi:[0,0,0]
	v_pk_fma_f32 v[26:27], v[46:47], v[40:41], v[26:27] op_sel:[0,0,0] op_sel_hi:[0,1,1] neg_lo:[0,0,1] neg_hi:[0,0,0]
	v_pk_fma_f32 v[30:31], v[48:49], v[40:41], v[30:31] op_sel:[0,0,0] op_sel_hi:[0,1,1] neg_lo:[0,0,1] neg_hi:[0,0,0]
	ds_write2_b64 v5, v[6:7], v[8:9] offset1:17
	ds_write2_b64 v5, v[10:11], v[12:13] offset0:34 offset1:51
	ds_write2_b64 v5, v[24:25], v[26:27] offset0:68 offset1:85
	ds_write2_b64 v5, v[28:29], v[30:31] offset0:102 offset1:119
	s_movk_i32 s0, 0x200
	s_and_b64 vcc, exec, s[10:11]
	s_mov_b64 s[10:11], 0
	s_cbranch_vccnz .LBB0_338
; __device__ __forceinline__ cf twc(cf ws, int k16) { if (k16 == 0) return ws; if (k16 == 4) return cf{ws.y, -ws.x}; return cmul(ws, cf{c16(k16), -s16(k16)}); }
; __device__ __forceinline__ void lds_barrier() { asm volatile("s_waitcnt lgkmcnt(0)\n\ts_barrier" ::: "memory"); }
; template <int LR> __device__ __forceinline__ void dif_reg(cf (&x)[1 << LR], cf w) {
;     constexpr int R = 1 << LR; cf ws = w;
; #pragma unroll
;     for (int s = 0; s < LR; ++s) { const int half = R >> (s + 1);
; #pragma unroll
;         for (int m0 = 0; m0 < R; m0 += 2 * half)
; #pragma unroll
;             for (int mm = 0; mm < half; ++mm) { const int ia = m0 + mm, ib = ia + half; const cf a = x[ia], b = x[ib];
;                 x[ia] = cf{a.x + b.x, a.y + b.y}; const cf d{a.x - b.x, a.y - b.y};
;                 x[ib] = cmul(d, twc(ws, (mm << s) * (16 / R))); }
;         ws = cmul(ws, ws); }
; }
; __device__ __forceinline__ void make_spec(ldsf2 buf, LAS unsigned* spec, const float* __restrict__ kfrow) {
;     ...
;     cf x[16];
; #pragma unroll
;     for (int m = 0; m < 16; ++m) { const v2f v = buf[tid * 17 + m]; x[m] = cf{v.x, v.y}; }
;     dif_reg<4>(x, cf{1.0f, 0.0f});
; #pragma unroll
;     for (int m = 0; m < 16; ++m) { h2_t hv; hv.x = (_Float16)x[m].x; hv.y = (_Float16)x[m].y; spec[tid * 17 + m] = __builtin_bit_cast(unsigned, hv); }
;     lds_barrier();
	s_waitcnt lgkmcnt(0)
	ds_read2_b64 v[2:5], v1 offset1:1
	ds_read2_b64 v[6:9], v1 offset0:2 offset1:3
	ds_read2_b64 v[10:13], v1 offset0:4 offset1:5
	ds_read2_b64 v[24:27], v1 offset0:6 offset1:7
	ds_read2_b64 v[28:31], v1 offset0:8 offset1:9
	ds_read2_b64 v[32:35], v1 offset0:10 offset1:11
	ds_read2_b64 v[36:39], v1 offset0:12 offset1:13
	ds_read2_b64 v[40:43], v1 offset0:14 offset1:15
	s_movk_i32 s0, 0x44
	v_mul_lo_u32 v0, v0, s0
	v_add_u32_e32 v0, 0, v0
	v_add_u32_e32 v70, 0x11000, v0
	s_waitcnt lgkmcnt(3)
	v_pk_add_f32 v[0:1], v[2:3], v[28:29]
	v_pk_add_f32 v[14:15], v[4:5], v[30:31]
	s_waitcnt lgkmcnt(2)
	v_pk_add_f32 v[44:45], v[6:7], v[32:33]
	v_pk_add_f32 v[46:47], v[8:9], v[34:35]
	s_waitcnt lgkmcnt(1)
	v_pk_add_f32 v[48:49], v[10:11], v[36:37]
	v_pk_add_f32 v[50:51], v[12:13], v[38:39]
	s_waitcnt lgkmcnt(0)
	v_pk_add_f32 v[52:53], v[24:25], v[40:41]
	v_pk_add_f32 v[54:55], v[26:27], v[42:43]
	v_pk_add_f32 v[56:57], v[0:1], v[48:49]
	v_pk_add_f32 v[58:59], v[14:15], v[50:51]
	v_pk_add_f32 v[60:61], v[44:45], v[52:53]
	v_pk_add_f32 v[62:63], v[46:47], v[54:55]
	v_pk_add_f32 v[64:65], v[56:57], v[60:61]
	v_pk_add_f32 v[66:67], v[58:59], v[62:63]
	v_pk_add_f32 v[56:57], v[56:57], v[60:61] neg_lo:[0,1] neg_hi:[0,1]
	v_pk_add_f32 v[68:69], v[64:65], v[66:67]
	v_pk_add_f32 v[64:65], v[64:65], v[66:67] neg_lo:[0,1] neg_hi:[0,1]
	v_cvt_pk_f16_f32 v71, v68, v69
	v_pk_mul_f32 v[66:67], v[64:65], 0 op_sel_hi:[1,0]
	v_pk_mul_f32 v[60:61], v[56:57], 0 op_sel_hi:[1,0]
	v_pk_add_f32 v[68:69], v[64:65], v[66:67] op_sel:[0,1] op_sel_hi:[1,0] neg_lo:[0,1] neg_hi:[0,1]
	v_pk_add_f32 v[64:65], v[64:65], v[66:67] op_sel:[0,1] op_sel_hi:[1,0]
	v_pk_add_f32 v[0:1], v[0:1], v[48:49] neg_lo:[0,1] neg_hi:[0,1]
	v_cvt_pk_f16_f32 v64, v68, v65
	ds_write2_b32 v70, v71, v64 offset1:1
	v_pk_add_f32 v[64:65], v[56:57], v[60:61] op_sel:[0,1] op_sel_hi:[1,0] neg_lo:[0,1] neg_hi:[0,1]
	v_pk_add_f32 v[56:57], v[56:57], v[60:61] op_sel:[0,1] op_sel_hi:[1,0]
	v_pk_mul_f32 v[48:49], v[0:1], 0 op_sel_hi:[1,0]
	v_mov_b32_e32 v65, v57
	v_pk_add_f32 v[56:57], v[58:59], v[62:63] neg_lo:[0,1] neg_hi:[0,1]
	s_mov_b32 s0, s87
	v_pk_fma_f32 v[58:59], v[56:57], 0, v[56:57] op_sel:[0,0,1] op_sel_hi:[1,0,0]
	v_pk_fma_f32 v[56:57], v[56:57], 0, v[56:57] op_sel:[0,0,1] op_sel_hi:[1,0,0] neg_lo:[0,0,1] neg_hi:[0,0,1]
	s_mov_b32 s1, s16
	v_mov_b32_e32 v59, v57
	v_pk_add_f32 v[56:57], v[64:65], v[58:59]
	s_mov_b32 s17, s87
	v_cvt_pk_f16_f32 v62, v56, v57
	v_pk_add_f32 v[56:57], v[64:65], v[58:59] neg_lo:[0,1] neg_hi:[0,1]
	s_mov_b32 s10, s5
	v_pk_mul_f32 v[58:59], v[56:57], 0 op_sel_hi:[1,0]
	s_mov_b32 s14, s13
	v_pk_add_f32 v[60:61], v[56:57], v[58:59] op_sel:[0,1] op_sel_hi:[1,0] neg_lo:[0,1] neg_hi:[0,1]
	v_pk_add_f32 v[56:57], v[56:57], v[58:59] op_sel:[0,1] op_sel_hi:[1,0]
	v_mov_b32_e32 v58, v51
	v_cvt_pk_f16_f32 v56, v60, v57
	ds_write2_b32 v70, v62, v56 offset0:2 offset1:3
	v_pk_add_f32 v[56:57], v[0:1], v[48:49] op_sel:[0,1] op_sel_hi:[1,0] neg_lo:[0,1] neg_hi:[0,1]
	v_pk_add_f32 v[0:1], v[0:1], v[48:49] op_sel:[0,1] op_sel_hi:[1,0]
	v_mov_b32_e32 v48, v54
	v_mov_b32_e32 v57, v1
	v_pk_add_f32 v[0:1], v[44:45], v[52:53] neg_lo:[0,1] neg_hi:[0,1]
	v_mov_b32_e32 v49, v51
	v_pk_fma_f32 v[44:45], v[0:1], 0, v[0:1] op_sel:[0,0,1] op_sel_hi:[1,0,0]
	v_pk_fma_f32 v[0:1], v[0:1], 0, v[0:1] op_sel:[0,0,1] op_sel_hi:[1,0,0] neg_lo:[0,0,1] neg_hi:[0,0,1]
	v_mov_b32_e32 v52, v50
	v_mov_b32_e32 v45, v1
	v_mov_b32_e32 v0, v46
	v_mov_b32_e32 v1, v15
	v_pk_add_f32 v[0:1], v[0:1], v[48:49] neg_lo:[0,1] neg_hi:[0,1]
	v_mov_b32_e32 v48, v14
	v_mov_b32_e32 v49, v46
	v_mov_b32_e32 v53, v54
	v_pk_add_f32 v[48:49], v[48:49], v[52:53] neg_lo:[0,1] neg_hi:[0,1]
	v_mov_b32_e32 v52, v15
	v_mov_b32_e32 v53, v47
	v_mov_b32_e32 v59, v55
	v_pk_mov_b32 v[14:15], v[46:47], v[14:15] op_sel:[1,0]
	v_pk_mov_b32 v[46:47], v[54:55], v[50:51] op_sel:[1,0]
	v_pk_add_f32 v[52:53], v[52:53], v[58:59] neg_lo:[0,1] neg_hi:[0,1]
	v_pk_add_f32 v[14:15], v[14:15], v[46:47] neg_lo:[0,1] neg_hi:[0,1]
	v_pk_mul_f32 v[46:47], v[52:53], s[16:17]
	v_pk_mul_f32 v[14:15], v[14:15], s[0:1]
	s_mov_b32 s15, s4
	v_pk_fma_f32 v[0:1], v[0:1], s[0:1], v[14:15] neg_lo:[0,0,1] neg_hi:[0,0,1]
	v_pk_fma_f32 v[14:15], v[48:49], s[16:17], v[46:47]
	v_pk_add_f32 v[46:47], v[56:57], v[44:45]
	v_pk_add_f32 v[48:49], v[14:15], v[0:1]
	v_pk_add_f32 v[44:45], v[56:57], v[44:45] neg_lo:[0,1] neg_hi:[0,1]
	v_pk_add_f32 v[50:51], v[46:47], v[48:49]
	v_pk_add_f32 v[46:47], v[46:47], v[48:49] neg_lo:[0,1] neg_hi:[0,1]
	v_cvt_pk_f16_f32 v52, v50, v51
	v_pk_mul_f32 v[48:49], v[46:47], 0 op_sel_hi:[1,0]
	s_mov_b32 s35, s5
	v_pk_add_f32 v[50:51], v[46:47], v[48:49] op_sel:[0,1] op_sel_hi:[1,0] neg_lo:[0,1] neg_hi:[0,1]
	v_pk_add_f32 v[46:47], v[46:47], v[48:49] op_sel:[0,1] op_sel_hi:[1,0]
	s_add_i32 s30, s46, 0x400
	v_cvt_pk_f16_f32 v46, v50, v47
	ds_write2_b32 v70, v52, v46 offset0:4 offset1:5
	v_pk_mul_f32 v[46:47], v[44:45], 0 op_sel_hi:[1,0]
	s_ashr_i32 s31, s30, 31
	v_pk_add_f32 v[48:49], v[44:45], v[46:47] op_sel:[0,1] op_sel_hi:[1,0] neg_lo:[0,1] neg_hi:[0,1]
	v_pk_add_f32 v[44:45], v[44:45], v[46:47] op_sel:[0,1] op_sel_hi:[1,0]
	s_nop 0
	v_mov_b32_e32 v49, v45
	v_mov_b32_e32 v44, v14
	v_mov_b32_e32 v45, v1
	v_mov_b32_e32 v1, v15
	v_pk_add_f32 v[0:1], v[44:45], v[0:1] neg_lo:[0,1] neg_hi:[0,1]
	s_nop 0
	v_pk_fma_f32 v[14:15], v[0:1], 0, v[0:1] op_sel:[0,0,1] op_sel_hi:[1,0,0]
	v_pk_fma_f32 v[0:1], v[0:1], 0, v[0:1] op_sel:[0,0,1] op_sel_hi:[1,0,0] neg_lo:[0,0,1] neg_hi:[0,0,1]
	s_nop 0
	v_mov_b32_e32 v15, v1
	v_pk_add_f32 v[0:1], v[48:49], v[14:15]
	s_nop 0
	v_cvt_pk_f16_f32 v46, v0, v1
	v_pk_add_f32 v[0:1], v[48:49], v[14:15] neg_lo:[0,1] neg_hi:[0,1]
; __device__ __forceinline__ cf twc(cf ws, int k16) { if (k16 == 0) return ws; if (k16 == 4) return cf{ws.y, -ws.x}; return cmul(ws, cf{c16(k16), -s16(k16)}); }
; __device__ __forceinline__ void lds_barrier() { asm volatile("s_waitcnt lgkmcnt(0)\n\ts_barrier" ::: "memory"); }
; template <int LR> __device__ __forceinline__ void dif_reg(cf (&x)[1 << LR], cf w) {
;     constexpr int R = 1 << LR; cf ws = w;
; #pragma unroll
;     for (int s = 0; s < LR; ++s) { const int half = R >> (s + 1);
; #pragma unroll
;         for (int m0 = 0; m0 < R; m0 += 2 * half)
; #pragma unroll
;             for (int mm = 0; mm < half; ++mm) { const int ia = m0 + mm, ib = ia + half; const cf a = x[ia], b = x[ib];
;                 x[ia] = cf{a.x + b.x, a.y + b.y}; const cf d{a.x - b.x, a.y - b.y};
;                 x[ib] = cmul(d, twc(ws, (mm << s) * (16 / R))); }
;         ws = cmul(ws, ws); }
; }
; __device__ __forceinline__ void make_spec(ldsf2 buf, LAS unsigned* spec, const float* __restrict__ kfrow) {
;     ...
;     cf x[16];
; #pragma unroll
;     for (int m = 0; m < 16; ++m) { const v2f v = buf[tid * 17 + m]; x[m] = cf{v.x, v.y}; }
;     dif_reg<4>(x, cf{1.0f, 0.0f});
; #pragma unroll
;     for (int m = 0; m < 16; ++m) { h2_t hv; hv.x = (_Float16)x[m].x; hv.y = (_Float16)x[m].y; spec[tid * 17 + m] = __builtin_bit_cast(unsigned, hv); }
;     lds_barrier();
	s_nop 0
	v_pk_mul_f32 v[14:15], v[0:1], 0 op_sel_hi:[1,0]
	s_nop 0
	v_pk_add_f32 v[44:45], v[0:1], v[14:15] op_sel:[0,1] op_sel_hi:[1,0] neg_lo:[0,1] neg_hi:[0,1]
	v_pk_add_f32 v[0:1], v[0:1], v[14:15] op_sel:[0,1] op_sel_hi:[1,0]
	s_nop 0
	v_cvt_pk_f16_f32 v0, v44, v1
	ds_write2_b32 v70, v46, v0 offset0:6 offset1:7
	v_pk_add_f32 v[0:1], v[2:3], v[28:29] neg_lo:[0,1] neg_hi:[0,1]
	s_nop 0
	v_pk_mul_f32 v[2:3], v[0:1], 0 op_sel_hi:[1,0]
	s_nop 0
	v_pk_add_f32 v[14:15], v[0:1], v[2:3] op_sel:[0,1] op_sel_hi:[1,0] neg_lo:[0,1] neg_hi:[0,1]
	v_pk_add_f32 v[0:1], v[0:1], v[2:3] op_sel:[0,1] op_sel_hi:[1,0]
	v_pk_add_f32 v[2:3], v[4:5], v[30:31] neg_lo:[0,1] neg_hi:[0,1]
	v_pk_mov_b32 v[0:1], v[0:1], v[14:15] op_sel:[1,0]
	v_pk_mul_f32 v[4:5], v[2:3], s[4:5] op_sel_hi:[1,0]
	s_nop 0
	v_pk_fma_f32 v[14:15], v[2:3], s[10:11], v[4:5] op_sel:[0,0,1] op_sel_hi:[1,0,0]
	v_pk_fma_f32 v[2:3], v[2:3], s[10:11], v[4:5] op_sel:[0,0,1] op_sel_hi:[1,0,0] neg_lo:[1,0,0] neg_hi:[1,0,0]
	v_pk_add_f32 v[4:5], v[8:9], v[34:35] neg_lo:[0,1] neg_hi:[0,1]
	v_mov_b32_e32 v34, v40
	v_pk_mul_f32 v[8:9], v[4:5], s[10:11] op_sel_hi:[1,0]
	v_mov_b32_e32 v35, v32
	v_pk_fma_f32 v[28:29], v[4:5], s[4:5], v[8:9] op_sel:[0,0,1] op_sel_hi:[1,0,0]
	v_pk_fma_f32 v[4:5], v[4:5], s[4:5], v[8:9] op_sel:[0,0,1] op_sel_hi:[1,0,0] neg_lo:[1,0,0] neg_hi:[1,0,0]
	v_pk_add_f32 v[8:9], v[10:11], v[36:37] neg_lo:[0,1] neg_hi:[0,1]
	v_mov_b32_e32 v36, v41
	v_pk_mul_f32 v[10:11], v[8:9], 0 op_sel_hi:[1,0]
	v_mov_b32_e32 v37, v33
	v_pk_add_f32 v[30:31], v[10:11], v[8:9] op_sel:[1,0] op_sel_hi:[0,1]
	v_pk_add_f32 v[8:9], v[10:11], v[8:9] op_sel:[1,0] op_sel_hi:[0,1] neg_lo:[0,1] neg_hi:[0,1]
	v_pk_add_f32 v[10:11], v[12:13], v[38:39] neg_lo:[0,1] neg_hi:[0,1]
	v_mov_b32_e32 v9, v31
	v_pk_mul_f32 v[12:13], v[10:11], s[10:11] op_sel_hi:[1,0]
	v_pk_mov_b32 v[30:31], v[32:33], v[40:41] op_sel:[1,0]
	v_pk_fma_f32 v[10:11], v[10:11], s[14:15], v[12:13] op_sel:[0,0,1] op_sel_hi:[1,1,0] neg_lo:[0,0,1] neg_hi:[0,0,1]
	v_pk_mov_b32 v[12:13], v[6:7], v[24:25] op_sel:[1,0]
	v_mov_b32_e32 v33, v41
	v_pk_add_f32 v[12:13], v[12:13], v[30:31] neg_lo:[0,1] neg_hi:[0,1]
	v_mov_b32_e32 v30, v24
	v_mov_b32_e32 v31, v6
	v_pk_add_f32 v[30:31], v[30:31], v[34:35] neg_lo:[0,1] neg_hi:[0,1]
	v_mov_b32_e32 v34, v25
	v_mov_b32_e32 v35, v7
	v_mov_b32_e32 v7, v25
	v_pk_add_f32 v[34:35], v[34:35], v[36:37] neg_lo:[0,1] neg_hi:[0,1]
	v_pk_add_f32 v[6:7], v[6:7], v[32:33] neg_lo:[0,1] neg_hi:[0,1]
	v_pk_mul_f32 v[24:25], v[34:35], s[0:1]
	v_pk_mul_f32 v[6:7], v[6:7], s[16:17]
	v_mov_b32_e32 v3, v15
	v_pk_fma_f32 v[6:7], v[12:13], s[16:17], v[6:7] neg_lo:[0,0,1] neg_hi:[0,0,1]
	v_pk_fma_f32 v[12:13], v[30:31], s[0:1], v[24:25]
	v_pk_add_f32 v[24:25], v[26:27], v[42:43] neg_lo:[0,1] neg_hi:[0,1]
	v_mov_b32_e32 v28, v4
	v_pk_mul_f32 v[26:27], v[24:25], s[4:5] op_sel_hi:[1,0]
	v_pk_add_f32 v[30:31], v[2:3], v[10:11]
	v_pk_fma_f32 v[24:25], v[24:25], s[34:35], v[26:27] op_sel:[0,0,1] op_sel_hi:[1,1,0] neg_lo:[0,0,1] neg_hi:[0,0,1]
	v_pk_add_f32 v[26:27], v[0:1], v[8:9]
	v_pk_add_f32 v[32:33], v[12:13], v[6:7]
	v_pk_add_f32 v[34:35], v[28:29], v[24:25]
	v_pk_add_f32 v[36:37], v[26:27], v[32:33]
	v_pk_add_f32 v[38:39], v[30:31], v[34:35]
	v_pk_add_f32 v[26:27], v[26:27], v[32:33] neg_lo:[0,1] neg_hi:[0,1]
	v_pk_add_f32 v[40:41], v[36:37], v[38:39]
	v_pk_add_f32 v[36:37], v[36:37], v[38:39] neg_lo:[0,1] neg_hi:[0,1]
	v_pk_mov_b32 v[40:41], v[40:41], v[40:41] op_sel:[1,0]
	v_pk_mul_f32 v[38:39], v[36:37], 0 op_sel_hi:[1,0]
	v_cvt_pk_f16_f32 v3, v40, v41
	v_pk_add_f32 v[40:41], v[36:37], v[38:39] op_sel:[0,1] op_sel_hi:[1,0] neg_lo:[0,1] neg_hi:[0,1]
	v_pk_add_f32 v[36:37], v[36:37], v[38:39] op_sel:[0,1] op_sel_hi:[1,0]
	v_pk_mul_f32 v[32:33], v[26:27], 0 op_sel_hi:[1,0]
	v_pk_mov_b32 v[36:37], v[40:41], v[36:37] op_sel:[1,0]
	v_pk_add_f32 v[30:31], v[30:31], v[34:35] neg_lo:[0,1] neg_hi:[0,1]
	v_cvt_pk_f16_f32 v28, v36, v37
	v_pk_add_f32 v[36:37], v[26:27], v[32:33] op_sel:[0,1] op_sel_hi:[1,0] neg_lo:[0,1] neg_hi:[0,1]
	v_pk_add_f32 v[26:27], v[26:27], v[32:33] op_sel:[0,1] op_sel_hi:[1,0]
	v_pk_mul_f32 v[32:33], v[30:31], 0 op_sel_hi:[1,0]
	v_pk_mov_b32 v[26:27], v[36:37], v[26:27] op_sel:[1,0]
	v_pk_add_f32 v[34:35], v[32:33], v[30:31] op_sel:[1,0] op_sel_hi:[0,1]
	v_pk_add_f32 v[30:31], v[32:33], v[30:31] op_sel:[1,0] op_sel_hi:[0,1] neg_lo:[0,1] neg_hi:[0,1]
	v_mov_b32_e32 v35, v31
	v_pk_add_f32 v[30:31], v[26:27], v[34:35]
	v_pk_add_f32 v[26:27], v[26:27], v[34:35] neg_lo:[0,1] neg_hi:[0,1]
	ds_write2_b32 v70, v3, v28 offset0:8 offset1:9
	v_cvt_pk_f16_f32 v3, v30, v31
	v_pk_mul_f32 v[30:31], v[26:27], 0 op_sel_hi:[1,0]
	v_pk_add_f32 v[0:1], v[0:1], v[8:9] neg_lo:[0,1] neg_hi:[0,1]
; #define LAS __attribute__((address_space(3)))
; __device__ __forceinline__ int otid() { int t = threadIdx.x; asm volatile("" : "+v"(t)); return t; }
; __device__ __forceinline__ void lds_barrier() { asm volatile("s_waitcnt lgkmcnt(0)\n\ts_barrier" ::: "memory"); }
; __device__ __forceinline__ void make_spec(ldsf2 buf, LAS unsigned* spec, const float* __restrict__ kfrow) {
;     const int tid = otid();
; #pragma unroll
;     for (int q = 0; q < 4; ++q) { const float4 v = *(const float4*)(kfrow + tid * 16 + q * 4);
;         buf[tid * 17 + q * 4 + 0] = mkv2(v.x, 0.f); buf[tid * 17 + q * 4 + 1] = mkv2(v.y, 0.f); buf[tid * 17 + q * 4 + 2] = mkv2(v.z, 0.f); buf[tid * 17 + q * 4 + 3] = mkv2(v.w, 0.f); }
;     __syncthreads();
;     fft_fwd_abc(buf);
;     cf x[16];
; #pragma unroll
;     for (int m = 0; m < 16; ++m) { const v2f v = buf[tid * 17 + m]; x[m] = cf{v.x, v.y}; }
;     dif_reg<4>(x, cf{1.0f, 0.0f});
; #pragma unroll
;     for (int m = 0; m < 16; ++m) { h2_t hv; hv.x = (_Float16)x[m].x; hv.y = (_Float16)x[m].y; spec[tid * 17 + m] = __builtin_bit_cast(unsigned, hv); }
;     lds_barrier();
	v_pk_add_f32 v[32:33], v[26:27], v[30:31] op_sel:[0,1] op_sel_hi:[1,0] neg_lo:[0,1] neg_hi:[0,1]
	v_pk_add_f32 v[26:27], v[26:27], v[30:31] op_sel:[0,1] op_sel_hi:[1,0]
	v_pk_mul_f32 v[8:9], v[0:1], 0 op_sel_hi:[1,0]
	v_cvt_pk_f16_f32 v26, v32, v27
	ds_write2_b32 v70, v3, v26 offset0:10 offset1:11
	v_pk_add_f32 v[26:27], v[0:1], v[8:9] op_sel:[0,1] op_sel_hi:[1,0] neg_lo:[0,1] neg_hi:[0,1]
	v_pk_add_f32 v[0:1], v[0:1], v[8:9] op_sel:[0,1] op_sel_hi:[1,0]
	v_pk_mov_b32 v[8:9], v[12:13], v[6:7] op_sel:[1,0]
	v_pk_mov_b32 v[6:7], v[6:7], v[12:13] op_sel:[1,0]
	v_mov_b32_e32 v3, v29
	v_pk_add_f32 v[6:7], v[8:9], v[6:7] neg_lo:[0,1] neg_hi:[0,1]
	v_pk_mov_b32 v[4:5], v[14:15], v[4:5] op_sel:[1,0]
	v_pk_fma_f32 v[8:9], v[6:7], 0, v[6:7] op_sel:[0,0,1] op_sel_hi:[1,0,0]
	v_pk_fma_f32 v[6:7], v[6:7], 0, v[6:7] op_sel:[0,0,1] op_sel_hi:[1,0,0] neg_lo:[0,0,1] neg_hi:[0,0,1]
	v_pk_mov_b32 v[0:1], v[26:27], v[0:1] op_sel:[1,0]
	v_mov_b32_e32 v9, v7
	v_mov_b32_e32 v6, v10
	v_mov_b32_e32 v7, v25
	v_pk_add_f32 v[2:3], v[2:3], v[6:7] neg_lo:[0,1] neg_hi:[0,1]
	v_pk_mov_b32 v[6:7], v[10:11], v[24:25] op_sel:[1,0]
	v_pk_mul_f32 v[2:3], v[2:3], s[16:17]
	v_pk_add_f32 v[4:5], v[4:5], v[6:7] neg_lo:[0,1] neg_hi:[0,1]
	s_lshl_b64 s[0:1], s[30:31], 15
	v_pk_fma_f32 v[6:7], v[4:5], s[16:17], v[2:3] neg_lo:[1,0,0] neg_hi:[1,0,0]
	v_pk_fma_f32 v[2:3], v[4:5], s[16:17], v[2:3]
	v_pk_mov_b32 v[10:11], v[6:7], v[6:7] op_sel:[1,0]
	v_pk_add_f32 v[4:5], v[0:1], v[8:9]
	v_pk_add_f32 v[6:7], v[2:3], v[6:7] op_sel:[0,1] op_sel_hi:[1,0]
	v_pk_add_f32 v[0:1], v[0:1], v[8:9] neg_lo:[0,1] neg_hi:[0,1]
	v_pk_add_f32 v[12:13], v[4:5], v[6:7]
	v_pk_add_f32 v[4:5], v[4:5], v[6:7] neg_lo:[0,1] neg_hi:[0,1]
	v_cvt_pk_f16_f32 v14, v12, v13
	v_pk_mul_f32 v[6:7], v[4:5], 0 op_sel_hi:[1,0]
	v_readlane_b32 s10, v252, 40
	v_pk_add_f32 v[12:13], v[4:5], v[6:7] op_sel:[0,1] op_sel_hi:[1,0] neg_lo:[0,1] neg_hi:[0,1]
	v_pk_add_f32 v[4:5], v[4:5], v[6:7] op_sel:[0,1] op_sel_hi:[1,0]
	v_readlane_b32 s11, v252, 41
	v_cvt_pk_f16_f32 v4, v12, v5
	ds_write2_b32 v70, v14, v4 offset0:12 offset1:13
	v_pk_mul_f32 v[4:5], v[0:1], 0 op_sel_hi:[1,0]
	s_add_u32 s0, s10, s0
	v_pk_add_f32 v[6:7], v[0:1], v[4:5] op_sel:[0,1] op_sel_hi:[1,0] neg_lo:[0,1] neg_hi:[0,1]
	v_pk_add_f32 v[0:1], v[0:1], v[4:5] op_sel:[0,1] op_sel_hi:[1,0]
	s_addc_u32 s1, s11, s1
	v_mov_b32_e32 v7, v1
	v_mov_b32_e32 v0, v2
	v_mov_b32_e32 v1, v11
	v_mov_b32_e32 v11, v3
	v_pk_add_f32 v[0:1], v[0:1], v[10:11] neg_lo:[0,1] neg_hi:[0,1]
	s_mov_b64 s[10:11], -1
	v_pk_fma_f32 v[2:3], v[0:1], 0, v[0:1] op_sel:[0,0,1] op_sel_hi:[1,0,0]
	v_pk_fma_f32 v[0:1], v[0:1], 0, v[0:1] op_sel:[0,0,1] op_sel_hi:[1,0,0] neg_lo:[0,0,1] neg_hi:[0,0,1]
	s_nop 0
	v_mov_b32_e32 v3, v1
	v_pk_add_f32 v[0:1], v[6:7], v[2:3]
	s_nop 0
	v_cvt_pk_f16_f32 v8, v0, v1
	v_pk_add_f32 v[0:1], v[6:7], v[2:3] neg_lo:[0,1] neg_hi:[0,1]
	s_nop 0
	v_pk_mul_f32 v[2:3], v[0:1], 0 op_sel_hi:[1,0]
	s_nop 0
	v_pk_add_f32 v[4:5], v[0:1], v[2:3] op_sel:[0,1] op_sel_hi:[1,0] neg_lo:[0,1] neg_hi:[0,1]
	v_pk_add_f32 v[0:1], v[0:1], v[2:3] op_sel:[0,1] op_sel_hi:[1,0]
	s_nop 0
	v_cvt_pk_f16_f32 v0, v4, v1
	ds_write2_b32 v70, v8, v0 offset0:14 offset1:15
	v_mov_b32_e32 v0, v195
	s_waitcnt lgkmcnt(0)
	s_barrier
	s_nop 0
	v_lshlrev_b32_e32 v2, 4, v0
	v_ashrrev_i32_e32 v3, 31, v2
	v_lshl_add_u64 v[14:15], v[2:3], 2, s[0:1]
	global_load_dwordx4 v[2:5], v[14:15], off
	global_load_dwordx4 v[6:9], v[14:15], off offset:16
	global_load_dwordx4 v[10:13], v[14:15], off offset:32
	global_load_dwordx4 v[24:27], v[14:15], off offset:48
	s_movk_i32 s0, 0x88
	v_mul_lo_u32 v1, v0, s0
	v_add_u32_e32 v1, 0, v1
	s_mov_b32 s0, 0
	s_waitcnt vmcnt(3)
	v_mov_b32_e32 v192, v2
	v_mov_b32_e32 v2, v3
	v_mov_b32_e32 v3, v193
	ds_write2_b64 v1, v[192:193], v[2:3] offset1:1
	v_mov_b32_e32 v192, v4
	v_mov_b32_e32 v2, v5
	ds_write2_b64 v1, v[192:193], v[2:3] offset0:2 offset1:3
	s_waitcnt vmcnt(2)
	v_mov_b32_e32 v192, v6
	v_mov_b32_e32 v2, v7
	ds_write2_b64 v1, v[192:193], v[2:3] offset0:4 offset1:5
	v_mov_b32_e32 v192, v8
	v_mov_b32_e32 v2, v9
	ds_write2_b64 v1, v[192:193], v[2:3] offset0:6 offset1:7
	s_waitcnt vmcnt(1)
	v_mov_b32_e32 v192, v10
	v_mov_b32_e32 v2, v11
	ds_write2_b64 v1, v[192:193], v[2:3] offset0:8 offset1:9
	v_mov_b32_e32 v192, v12
	v_mov_b32_e32 v2, v13
	ds_write2_b64 v1, v[192:193], v[2:3] offset0:10 offset1:11
	s_waitcnt vmcnt(0)
	v_mov_b32_e32 v192, v24
	v_mov_b32_e32 v2, v25
	ds_write2_b64 v1, v[192:193], v[2:3] offset0:12 offset1:13
	v_mov_b32_e32 v192, v26
	v_mov_b32_e32 v2, v27
	ds_write2_b64 v1, v[192:193], v[2:3] offset0:14 offset1:15
	v_mov_b32_e32 v2, v195
	s_waitcnt lgkmcnt(0)
	s_barrier

; #define LAS __attribute__((address_space(3)))
; __device__ __forceinline__ int otid() { int t = threadIdx.x; asm volatile("" : "+v"(t)); return t; }
; __device__ __forceinline__ cf twc(cf ws, int k16) { if (k16 == 0) return ws; if (k16 == 4) return cf{ws.y, -ws.x}; return cmul(ws, cf{c16(k16), -s16(k16)}); }
; __device__ __forceinline__ void lds_barrier() { asm volatile("s_waitcnt lgkmcnt(0)\n\ts_barrier" ::: "memory"); }
; template <int LR> __device__ __forceinline__ void dif_reg(cf (&x)[1 << LR], cf w) {
;     constexpr int R = 1 << LR; cf ws = w;
; #pragma unroll
;     for (int s = 0; s < LR; ++s) { const int half = R >> (s + 1);
; #pragma unroll
;         for (int m0 = 0; m0 < R; m0 += 2 * half)
; #pragma unroll
;             for (int mm = 0; mm < half; ++mm) { const int ia = m0 + mm, ib = ia + half; const cf a = x[ia], b = x[ib];
;                 x[ia] = cf{a.x + b.x, a.y + b.y}; const cf d{a.x - b.x, a.y - b.y};
;                 x[ib] = cmul(d, twc(ws, (mm << s) * (16 / R))); }
;         ws = cmul(ws, ws); }
; }
; template <int LR, bool INV> __device__ __forceinline__ void fft_pass(ldsf2 buf, int base, int stride, int twi) {
;     constexpr int R = 1 << LR; cf x[R];
;     const v2f wv = ((ldsf2)((LAS unsigned char*)buf + 139264))[twi];
; #pragma unroll
;     for (int m = 0; m < R; ++m) { const v2f v = buf[base + m * stride]; x[m] = cf{v.x, v.y}; }
;     const cf w{wv.x, wv.y};
;     if (INV) dit_reg<LR>(x, w); else dif_reg<LR>(x, w);
; #pragma unroll
;     for (int m = 0; m < R; ++m) buf[base + m * stride] = mkv2(x[m].x, x[m].y);
; }
; __device__ __forceinline__ void wave_lds_fence() { asm volatile("s_waitcnt lgkmcnt(0)" ::: "memory"); }
; __device__ __forceinline__ void fft_fwd_abc(ldsf2 buf) {
;     const int tid = otid(); const int wv = tid >> 6, l = tid & 63;
; #pragma unroll 1
;     for (int u = 0; u < 2; ++u) { const int bf = tid + NT * u; fft_pass<3, false>(buf, bf + (bf >> 4), 1088, bf); }
;     lds_barrier();
; #pragma unroll 1
;     for (int u = 0; u < 2; ++u) { const int o = l + 64 * u, e0 = wv * 1024 + o; fft_pass<3, false>(buf, e0 + (e0 >> 4), 136, o * 8); }
;     wave_lds_fence();
; #pragma unroll 1
;     for (int u = 0; u < 2; ++u) { const int j = l + 64 * u, o = j & 15, e0 = wv * 1024 + (j >> 4) * 128 + o; fft_pass<3, false>(buf, e0 + (e0 >> 4), 17, o * 64); }
.LBB0_344:
	v_or_b32_e32 v5, s0, v3
	ds_read_b64 v[14:15], v4
	v_lshlrev_b32_e32 v6, 3, v5
	v_ashrrev_i32_e32 v5, 1, v5
	v_add3_u32 v5, v2, v6, v5
	ds_read2_b64 v[6:9], v5 offset1:17
	ds_read2_b64 v[10:13], v5 offset0:34 offset1:51
	ds_read2_b64 v[24:27], v5 offset0:68 offset1:85
	ds_read2_b64 v[28:31], v5 offset0:102 offset1:119
	s_waitcnt lgkmcnt(4)
	v_pk_add_f32 v[32:33], v[14:15], v[14:15] op_sel:[0,1] op_sel_hi:[1,0] neg_lo:[0,0] neg_hi:[0,1]
	v_pk_mul_f32 v[34:35], v[32:33], s[16:17] op_sel:[0,0] op_sel_hi:[1,0]
	v_pk_mul_f32 v[36:37], v[32:33], s[16:17] op_sel:[1,0] op_sel_hi:[0,0] neg_lo:[0,0] neg_hi:[1,0]
	v_pk_mul_f32 v[38:39], v[14:15], v[14:15] op_sel:[1,1] op_sel_hi:[1,0]
	v_pk_fma_f32 v[38:39], v[14:15], v[14:15], v[38:39] op_sel:[0,0,0] op_sel_hi:[0,1,1] neg_lo:[0,0,1] neg_hi:[0,0,0]
	v_pk_mul_f32 v[40:41], v[38:39], v[38:39] op_sel:[1,1] op_sel_hi:[1,0]
	v_pk_fma_f32 v[40:41], v[38:39], v[38:39], v[40:41] op_sel:[0,0,0] op_sel_hi:[0,1,1] neg_lo:[0,0,1] neg_hi:[0,0,0]
	s_waitcnt lgkmcnt(0)
	v_pk_add_f32 v[42:43], v[6:7], v[24:25] neg_lo:[0,1] neg_hi:[0,1]
	v_pk_add_f32 v[44:45], v[8:9], v[26:27] neg_lo:[0,1] neg_hi:[0,1]
	v_pk_add_f32 v[46:47], v[10:11], v[28:29] neg_lo:[0,1] neg_hi:[0,1]
	v_pk_add_f32 v[48:49], v[12:13], v[30:31] neg_lo:[0,1] neg_hi:[0,1]
	v_pk_add_f32 v[6:7], v[6:7], v[24:25]
	v_pk_add_f32 v[8:9], v[8:9], v[26:27]
	v_pk_add_f32 v[10:11], v[10:11], v[28:29]
	v_pk_add_f32 v[12:13], v[12:13], v[30:31]
	v_pk_mul_f32 v[24:25], v[42:43], v[14:15] op_sel:[1,1] op_sel_hi:[1,0]
	v_pk_mul_f32 v[26:27], v[44:45], v[34:35] op_sel:[1,1] op_sel_hi:[1,0]
	v_pk_mul_f32 v[28:29], v[46:47], v[14:15] op_sel:[1,0] op_sel_hi:[1,1]
	v_pk_mul_f32 v[30:31], v[48:49], v[36:37] op_sel:[1,1] op_sel_hi:[1,0]
	v_pk_fma_f32 v[24:25], v[42:43], v[14:15], v[24:25] op_sel:[0,0,0] op_sel_hi:[0,1,1] neg_lo:[0,0,1] neg_hi:[0,0,0]
	v_pk_fma_f32 v[26:27], v[44:45], v[34:35], v[26:27] op_sel:[0,0,0] op_sel_hi:[0,1,1] neg_lo:[0,0,1] neg_hi:[0,0,0]
	v_pk_fma_f32 v[28:29], v[46:47], v[14:15], v[28:29] op_sel:[0,1,0] op_sel_hi:[0,0,1] neg_lo:[0,0,0] neg_hi:[0,1,0]
	v_pk_fma_f32 v[30:31], v[48:49], v[36:37], v[30:31] op_sel:[0,0,0] op_sel_hi:[0,1,1] neg_lo:[0,0,1] neg_hi:[0,0,0]
	v_pk_add_f32 v[42:43], v[6:7], v[10:11] neg_lo:[0,1] neg_hi:[0,1]
	v_pk_add_f32 v[44:45], v[8:9], v[12:13] neg_lo:[0,1] neg_hi:[0,1]
	v_pk_add_f32 v[46:47], v[24:25], v[28:29] neg_lo:[0,1] neg_hi:[0,1]
	v_pk_add_f32 v[48:49], v[26:27], v[30:31] neg_lo:[0,1] neg_hi:[0,1]
	v_pk_add_f32 v[6:7], v[6:7], v[10:11]
	v_pk_add_f32 v[8:9], v[8:9], v[12:13]
	v_pk_add_f32 v[24:25], v[24:25], v[28:29]
	v_pk_add_f32 v[26:27], v[26:27], v[30:31]
	v_pk_mul_f32 v[10:11], v[42:43], v[38:39] op_sel:[1,1] op_sel_hi:[1,0]
	v_pk_mul_f32 v[12:13], v[44:45], v[38:39] op_sel:[1,0] op_sel_hi:[1,1]
	v_pk_mul_f32 v[28:29], v[46:47], v[38:39] op_sel:[1,1] op_sel_hi:[1,0]
	v_pk_mul_f32 v[30:31], v[48:49], v[38:39] op_sel:[1,0] op_sel_hi:[1,1]
	v_pk_fma_f32 v[10:11], v[42:43], v[38:39], v[10:11] op_sel:[0,0,0] op_sel_hi:[0,1,1] neg_lo:[0,0,1] neg_hi:[0,0,0]
	v_pk_fma_f32 v[12:13], v[44:45], v[38:39], v[12:13] op_sel:[0,1,0] op_sel_hi:[0,0,1] neg_lo:[0,0,0] neg_hi:[0,1,0]
	v_pk_fma_f32 v[28:29], v[46:47], v[38:39], v[28:29] op_sel:[0,0,0] op_sel_hi:[0,1,1] neg_lo:[0,0,1] neg_hi:[0,0,0]
	v_pk_fma_f32 v[30:31], v[48:49], v[38:39], v[30:31] op_sel:[0,1,0] op_sel_hi:[0,0,1] neg_lo:[0,0,0] neg_hi:[0,1,0]
	v_pk_add_f32 v[42:43], v[6:7], v[8:9] neg_lo:[0,1] neg_hi:[0,1]
	v_pk_add_f32 v[44:45], v[10:11], v[12:13] neg_lo:[0,1] neg_hi:[0,1]
	v_pk_add_f32 v[46:47], v[24:25], v[26:27] neg_lo:[0,1] neg_hi:[0,1]
	v_pk_add_f32 v[48:49], v[28:29], v[30:31] neg_lo:[0,1] neg_hi:[0,1]
	v_pk_add_f32 v[6:7], v[6:7], v[8:9]
	v_pk_add_f32 v[10:11], v[10:11], v[12:13]
	v_pk_add_f32 v[24:25], v[24:25], v[26:27]
	v_pk_add_f32 v[28:29], v[28:29], v[30:31]
	v_pk_mul_f32 v[8:9], v[42:43], v[40:41] op_sel:[1,1] op_sel_hi:[1,0]
	v_pk_mul_f32 v[12:13], v[44:45], v[40:41] op_sel:[1,1] op_sel_hi:[1,0]
	v_pk_mul_f32 v[26:27], v[46:47], v[40:41] op_sel:[1,1] op_sel_hi:[1,0]
	v_pk_mul_f32 v[30:31], v[48:49], v[40:41] op_sel:[1,1] op_sel_hi:[1,0]
	v_pk_fma_f32 v[8:9], v[42:43], v[40:41], v[8:9] op_sel:[0,0,0] op_sel_hi:[0,1,1] neg_lo:[0,0,1] neg_hi:[0,0,0]
	v_pk_fma_f32 v[12:13], v[44:45], v[40:41], v[12:13] op_sel:[0,0,0] op_sel_hi:[0,1,1] neg_lo:[0,0,1] neg_hi:[0,0,0]
	v_pk_fma_f32 v[26:27], v[46:47], v[40:41], v[26:27] op_sel:[0,0,0] op_sel_hi:[0,1,1] neg_lo:[0,0,1] neg_hi:[0,0,0]
	v_pk_fma_f32 v[30:31], v[48:49], v[40:41], v[30:31] op_sel:[0,0,0] op_sel_hi:[0,1,1] neg_lo:[0,0,1] neg_hi:[0,0,0]
	ds_write2_b64 v5, v[6:7], v[8:9] offset1:17
	ds_write2_b64 v5, v[10:11], v[12:13] offset0:34 offset1:51
	ds_write2_b64 v5, v[24:25], v[26:27] offset0:68 offset1:85
	ds_write2_b64 v5, v[28:29], v[30:31] offset0:102 offset1:119
	s_movk_i32 s0, 0x200
	s_and_b64 vcc, exec, s[10:11]
	s_mov_b64 s[10:11], 0
	s_cbranch_vccnz .LBB0_344
; __device__ __forceinline__ cf twc(cf ws, int k16) { if (k16 == 0) return ws; if (k16 == 4) return cf{ws.y, -ws.x}; return cmul(ws, cf{c16(k16), -s16(k16)}); }
; __device__ __forceinline__ void lds_barrier() { asm volatile("s_waitcnt lgkmcnt(0)\n\ts_barrier" ::: "memory"); }
; template <int LR> __device__ __forceinline__ void dif_reg(cf (&x)[1 << LR], cf w) {
;     constexpr int R = 1 << LR; cf ws = w;
; #pragma unroll
;     for (int s = 0; s < LR; ++s) { const int half = R >> (s + 1);
; #pragma unroll
;         for (int m0 = 0; m0 < R; m0 += 2 * half)
; #pragma unroll
;             for (int mm = 0; mm < half; ++mm) { const int ia = m0 + mm, ib = ia + half; const cf a = x[ia], b = x[ib];
;                 x[ia] = cf{a.x + b.x, a.y + b.y}; const cf d{a.x - b.x, a.y - b.y};
;                 x[ib] = cmul(d, twc(ws, (mm << s) * (16 / R))); }
;         ws = cmul(ws, ws); }
; }
; __device__ __forceinline__ void make_spec(ldsf2 buf, LAS unsigned* spec, const float* __restrict__ kfrow) {
;     ...
;     cf x[16];
; #pragma unroll
;     for (int m = 0; m < 16; ++m) { const v2f v = buf[tid * 17 + m]; x[m] = cf{v.x, v.y}; }
;     dif_reg<4>(x, cf{1.0f, 0.0f});
; #pragma unroll
;     for (int m = 0; m < 16; ++m) { h2_t hv; hv.x = (_Float16)x[m].x; hv.y = (_Float16)x[m].y; spec[tid * 17 + m] = __builtin_bit_cast(unsigned, hv); }
;     lds_barrier();
	s_waitcnt lgkmcnt(0)
	ds_read2_b64 v[2:5], v1 offset1:1
	ds_read2_b64 v[6:9], v1 offset0:2 offset1:3
	ds_read2_b64 v[10:13], v1 offset0:4 offset1:5
	ds_read2_b64 v[24:27], v1 offset0:6 offset1:7
	ds_read2_b64 v[28:31], v1 offset0:8 offset1:9
	ds_read2_b64 v[32:35], v1 offset0:10 offset1:11
	ds_read2_b64 v[36:39], v1 offset0:12 offset1:13
	ds_read2_b64 v[40:43], v1 offset0:14 offset1:15
	s_movk_i32 s0, 0x44
	v_mul_lo_u32 v0, v0, s0
	v_add_u32_e32 v0, 0, v0
	v_add_u32_e32 v70, 0x19800, v0
	s_waitcnt lgkmcnt(3)
	v_pk_add_f32 v[0:1], v[2:3], v[28:29]
	v_pk_add_f32 v[14:15], v[4:5], v[30:31]
	s_waitcnt lgkmcnt(2)
	v_pk_add_f32 v[44:45], v[6:7], v[32:33]
	v_pk_add_f32 v[46:47], v[8:9], v[34:35]
	s_waitcnt lgkmcnt(1)
	v_pk_add_f32 v[48:49], v[10:11], v[36:37]
	v_pk_add_f32 v[50:51], v[12:13], v[38:39]
	s_waitcnt lgkmcnt(0)
	v_pk_add_f32 v[52:53], v[24:25], v[40:41]
	v_pk_add_f32 v[54:55], v[26:27], v[42:43]
	v_pk_add_f32 v[56:57], v[0:1], v[48:49]
	v_pk_add_f32 v[58:59], v[14:15], v[50:51]
	v_pk_add_f32 v[60:61], v[44:45], v[52:53]
	v_pk_add_f32 v[62:63], v[46:47], v[54:55]
	v_pk_add_f32 v[64:65], v[56:57], v[60:61]
	v_pk_add_f32 v[66:67], v[58:59], v[62:63]
	v_pk_add_f32 v[56:57], v[56:57], v[60:61] neg_lo:[0,1] neg_hi:[0,1]
	v_pk_add_f32 v[68:69], v[64:65], v[66:67]
	v_pk_add_f32 v[64:65], v[64:65], v[66:67] neg_lo:[0,1] neg_hi:[0,1]
	v_cvt_pk_f16_f32 v71, v68, v69
	v_pk_mul_f32 v[66:67], v[64:65], 0 op_sel_hi:[1,0]
	v_pk_mul_f32 v[60:61], v[56:57], 0 op_sel_hi:[1,0]
	v_pk_add_f32 v[68:69], v[64:65], v[66:67] op_sel:[0,1] op_sel_hi:[1,0] neg_lo:[0,1] neg_hi:[0,1]
	v_pk_add_f32 v[64:65], v[64:65], v[66:67] op_sel:[0,1] op_sel_hi:[1,0]
	v_pk_add_f32 v[0:1], v[0:1], v[48:49] neg_lo:[0,1] neg_hi:[0,1]
	v_cvt_pk_f16_f32 v64, v68, v65
	ds_write2_b32 v70, v71, v64 offset1:1
	v_pk_add_f32 v[64:65], v[56:57], v[60:61] op_sel:[0,1] op_sel_hi:[1,0] neg_lo:[0,1] neg_hi:[0,1]
	v_pk_add_f32 v[56:57], v[56:57], v[60:61] op_sel:[0,1] op_sel_hi:[1,0]
	v_pk_mul_f32 v[48:49], v[0:1], 0 op_sel_hi:[1,0]
	v_mov_b32_e32 v65, v57
	v_pk_add_f32 v[56:57], v[58:59], v[62:63] neg_lo:[0,1] neg_hi:[0,1]
	s_mov_b32 s0, s87
	v_pk_fma_f32 v[58:59], v[56:57], 0, v[56:57] op_sel:[0,0,1] op_sel_hi:[1,0,0]
	v_pk_fma_f32 v[56:57], v[56:57], 0, v[56:57] op_sel:[0,0,1] op_sel_hi:[1,0,0] neg_lo:[0,0,1] neg_hi:[0,0,1]
	s_mov_b32 s1, s16
	v_mov_b32_e32 v59, v57
	v_pk_add_f32 v[56:57], v[64:65], v[58:59]
	s_mov_b32 s17, s87
	v_cvt_pk_f16_f32 v62, v56, v57
	v_pk_add_f32 v[56:57], v[64:65], v[58:59] neg_lo:[0,1] neg_hi:[0,1]
	s_mov_b32 s10, s5
	v_pk_mul_f32 v[58:59], v[56:57], 0 op_sel_hi:[1,0]
	s_mov_b32 s14, s13
	v_pk_add_f32 v[60:61], v[56:57], v[58:59] op_sel:[0,1] op_sel_hi:[1,0] neg_lo:[0,1] neg_hi:[0,1]
	v_pk_add_f32 v[56:57], v[56:57], v[58:59] op_sel:[0,1] op_sel_hi:[1,0]
	v_mov_b32_e32 v58, v51
	v_cvt_pk_f16_f32 v56, v60, v57
	ds_write2_b32 v70, v62, v56 offset0:2 offset1:3
	v_pk_add_f32 v[56:57], v[0:1], v[48:49] op_sel:[0,1] op_sel_hi:[1,0] neg_lo:[0,1] neg_hi:[0,1]
	v_pk_add_f32 v[0:1], v[0:1], v[48:49] op_sel:[0,1] op_sel_hi:[1,0]
	v_mov_b32_e32 v48, v54
	v_mov_b32_e32 v57, v1
	v_pk_add_f32 v[0:1], v[44:45], v[52:53] neg_lo:[0,1] neg_hi:[0,1]
	v_mov_b32_e32 v49, v51
	v_pk_fma_f32 v[44:45], v[0:1], 0, v[0:1] op_sel:[0,0,1] op_sel_hi:[1,0,0]
	v_pk_fma_f32 v[0:1], v[0:1], 0, v[0:1] op_sel:[0,0,1] op_sel_hi:[1,0,0] neg_lo:[0,0,1] neg_hi:[0,0,1]
	v_mov_b32_e32 v52, v50
	v_mov_b32_e32 v45, v1
	v_mov_b32_e32 v0, v46
	v_mov_b32_e32 v1, v15
	v_pk_add_f32 v[0:1], v[0:1], v[48:49] neg_lo:[0,1] neg_hi:[0,1]
	v_mov_b32_e32 v48, v14
	v_mov_b32_e32 v49, v46
	v_mov_b32_e32 v53, v54
	v_pk_add_f32 v[48:49], v[48:49], v[52:53] neg_lo:[0,1] neg_hi:[0,1]
	v_mov_b32_e32 v52, v15
	v_mov_b32_e32 v53, v47
	v_mov_b32_e32 v59, v55
	v_pk_mov_b32 v[14:15], v[46:47], v[14:15] op_sel:[1,0]
	v_pk_mov_b32 v[46:47], v[54:55], v[50:51] op_sel:[1,0]
	v_pk_add_f32 v[52:53], v[52:53], v[58:59] neg_lo:[0,1] neg_hi:[0,1]
	v_pk_add_f32 v[14:15], v[14:15], v[46:47] neg_lo:[0,1] neg_hi:[0,1]
	v_pk_mul_f32 v[46:47], v[52:53], s[16:17]
	v_pk_mul_f32 v[14:15], v[14:15], s[0:1]
	s_mov_b32 s15, s4
	v_pk_fma_f32 v[0:1], v[0:1], s[0:1], v[14:15] neg_lo:[0,0,1] neg_hi:[0,0,1]
	v_pk_fma_f32 v[14:15], v[48:49], s[16:17], v[46:47]
	v_pk_add_f32 v[46:47], v[56:57], v[44:45]
	v_pk_add_f32 v[48:49], v[14:15], v[0:1]
	v_pk_add_f32 v[44:45], v[56:57], v[44:45] neg_lo:[0,1] neg_hi:[0,1]
	v_pk_add_f32 v[50:51], v[46:47], v[48:49]
	v_pk_add_f32 v[46:47], v[46:47], v[48:49] neg_lo:[0,1] neg_hi:[0,1]
	v_cvt_pk_f16_f32 v52, v50, v51
	v_pk_mul_f32 v[48:49], v[46:47], 0 op_sel_hi:[1,0]
	s_mov_b32 s35, s5
	v_pk_add_f32 v[50:51], v[46:47], v[48:49] op_sel:[0,1] op_sel_hi:[1,0] neg_lo:[0,1] neg_hi:[0,1]
	v_pk_add_f32 v[46:47], v[46:47], v[48:49] op_sel:[0,1] op_sel_hi:[1,0]
	s_mov_b32 s48, 0
	v_cvt_pk_f16_f32 v46, v50, v47
	ds_write2_b32 v70, v52, v46 offset0:4 offset1:5
	v_pk_mul_f32 v[46:47], v[44:45], 0 op_sel_hi:[1,0]
	s_mov_b32 s49, s48
	v_pk_add_f32 v[48:49], v[44:45], v[46:47] op_sel:[0,1] op_sel_hi:[1,0] neg_lo:[0,1] neg_hi:[0,1]
	v_pk_add_f32 v[44:45], v[44:45], v[46:47] op_sel:[0,1] op_sel_hi:[1,0]
	s_mov_b32 s50, s48
	v_mov_b32_e32 v49, v45
	v_mov_b32_e32 v44, v14
	v_mov_b32_e32 v45, v1
	v_mov_b32_e32 v1, v15
	v_pk_add_f32 v[0:1], v[44:45], v[0:1] neg_lo:[0,1] neg_hi:[0,1]
	s_mov_b32 s51, s48
	v_pk_fma_f32 v[14:15], v[0:1], 0, v[0:1] op_sel:[0,0,1] op_sel_hi:[1,0,0]
	v_pk_fma_f32 v[0:1], v[0:1], 0, v[0:1] op_sel:[0,0,1] op_sel_hi:[1,0,0] neg_lo:[0,0,1] neg_hi:[0,0,1]
	s_mov_b32 s53, s48
	v_mov_b32_e32 v15, v1
	v_pk_add_f32 v[0:1], v[48:49], v[14:15]
	s_nop 0
	v_cvt_pk_f16_f32 v46, v0, v1
	v_pk_add_f32 v[0:1], v[48:49], v[14:15] neg_lo:[0,1] neg_hi:[0,1]
; __device__ __forceinline__ cf twc(cf ws, int k16) { if (k16 == 0) return ws; if (k16 == 4) return cf{ws.y, -ws.x}; return cmul(ws, cf{c16(k16), -s16(k16)}); }
; __device__ __forceinline__ void lds_barrier() { asm volatile("s_waitcnt lgkmcnt(0)\n\ts_barrier" ::: "memory"); }
; template <int LR> __device__ __forceinline__ void dif_reg(cf (&x)[1 << LR], cf w) {
;     constexpr int R = 1 << LR; cf ws = w;
; #pragma unroll
;     for (int s = 0; s < LR; ++s) { const int half = R >> (s + 1);
; #pragma unroll
;         for (int m0 = 0; m0 < R; m0 += 2 * half)
; #pragma unroll
;             for (int mm = 0; mm < half; ++mm) { const int ia = m0 + mm, ib = ia + half; const cf a = x[ia], b = x[ib];
;                 x[ia] = cf{a.x + b.x, a.y + b.y}; const cf d{a.x - b.x, a.y - b.y};
;                 x[ib] = cmul(d, twc(ws, (mm << s) * (16 / R))); }
;         ws = cmul(ws, ws); }
; }
; __device__ __forceinline__ void make_spec(ldsf2 buf, LAS unsigned* spec, const float* __restrict__ kfrow) {
;     ...
;     cf x[16];
; #pragma unroll
;     for (int m = 0; m < 16; ++m) { const v2f v = buf[tid * 17 + m]; x[m] = cf{v.x, v.y}; }
;     dif_reg<4>(x, cf{1.0f, 0.0f});
; #pragma unroll
;     for (int m = 0; m < 16; ++m) { h2_t hv; hv.x = (_Float16)x[m].x; hv.y = (_Float16)x[m].y; spec[tid * 17 + m] = __builtin_bit_cast(unsigned, hv); }
;     lds_barrier();
	s_nop 0
	v_pk_mul_f32 v[14:15], v[0:1], 0 op_sel_hi:[1,0]
	s_nop 0
	v_pk_add_f32 v[44:45], v[0:1], v[14:15] op_sel:[0,1] op_sel_hi:[1,0] neg_lo:[0,1] neg_hi:[0,1]
	v_pk_add_f32 v[0:1], v[0:1], v[14:15] op_sel:[0,1] op_sel_hi:[1,0]
	s_nop 0
	v_cvt_pk_f16_f32 v0, v44, v1
	ds_write2_b32 v70, v46, v0 offset0:6 offset1:7
	v_pk_add_f32 v[0:1], v[2:3], v[28:29] neg_lo:[0,1] neg_hi:[0,1]
	s_nop 0
	v_pk_mul_f32 v[2:3], v[0:1], 0 op_sel_hi:[1,0]
	s_nop 0
	v_pk_add_f32 v[14:15], v[0:1], v[2:3] op_sel:[0,1] op_sel_hi:[1,0] neg_lo:[0,1] neg_hi:[0,1]
	v_pk_add_f32 v[0:1], v[0:1], v[2:3] op_sel:[0,1] op_sel_hi:[1,0]
	v_pk_add_f32 v[2:3], v[4:5], v[30:31] neg_lo:[0,1] neg_hi:[0,1]
	v_pk_mov_b32 v[0:1], v[0:1], v[14:15] op_sel:[1,0]
	v_pk_mul_f32 v[4:5], v[2:3], s[4:5] op_sel_hi:[1,0]
	s_nop 0
	v_pk_fma_f32 v[14:15], v[2:3], s[10:11], v[4:5] op_sel:[0,0,1] op_sel_hi:[1,0,0]
	v_pk_fma_f32 v[2:3], v[2:3], s[10:11], v[4:5] op_sel:[0,0,1] op_sel_hi:[1,0,0] neg_lo:[1,0,0] neg_hi:[1,0,0]
	v_pk_add_f32 v[4:5], v[8:9], v[34:35] neg_lo:[0,1] neg_hi:[0,1]
	v_mov_b32_e32 v34, v40
	v_pk_mul_f32 v[8:9], v[4:5], s[10:11] op_sel_hi:[1,0]
	v_mov_b32_e32 v35, v32
	v_pk_fma_f32 v[28:29], v[4:5], s[4:5], v[8:9] op_sel:[0,0,1] op_sel_hi:[1,0,0]
	v_pk_fma_f32 v[4:5], v[4:5], s[4:5], v[8:9] op_sel:[0,0,1] op_sel_hi:[1,0,0] neg_lo:[1,0,0] neg_hi:[1,0,0]
	v_pk_add_f32 v[8:9], v[10:11], v[36:37] neg_lo:[0,1] neg_hi:[0,1]
	v_mov_b32_e32 v36, v41
	v_pk_mul_f32 v[10:11], v[8:9], 0 op_sel_hi:[1,0]
	v_mov_b32_e32 v37, v33
	v_pk_add_f32 v[30:31], v[10:11], v[8:9] op_sel:[1,0] op_sel_hi:[0,1]
	v_pk_add_f32 v[8:9], v[10:11], v[8:9] op_sel:[1,0] op_sel_hi:[0,1] neg_lo:[0,1] neg_hi:[0,1]
	v_pk_add_f32 v[10:11], v[12:13], v[38:39] neg_lo:[0,1] neg_hi:[0,1]
	v_mov_b32_e32 v9, v31
	v_pk_mul_f32 v[12:13], v[10:11], s[10:11] op_sel_hi:[1,0]
	v_pk_mov_b32 v[30:31], v[32:33], v[40:41] op_sel:[1,0]
	v_pk_fma_f32 v[10:11], v[10:11], s[14:15], v[12:13] op_sel:[0,0,1] op_sel_hi:[1,1,0] neg_lo:[0,0,1] neg_hi:[0,0,1]
	v_pk_mov_b32 v[12:13], v[6:7], v[24:25] op_sel:[1,0]
	v_mov_b32_e32 v33, v41
	v_pk_add_f32 v[12:13], v[12:13], v[30:31] neg_lo:[0,1] neg_hi:[0,1]
	v_mov_b32_e32 v30, v24
	v_mov_b32_e32 v31, v6
	v_pk_add_f32 v[30:31], v[30:31], v[34:35] neg_lo:[0,1] neg_hi:[0,1]
	v_mov_b32_e32 v34, v25
	v_mov_b32_e32 v35, v7
	v_mov_b32_e32 v7, v25
	v_pk_add_f32 v[34:35], v[34:35], v[36:37] neg_lo:[0,1] neg_hi:[0,1]
	v_pk_add_f32 v[6:7], v[6:7], v[32:33] neg_lo:[0,1] neg_hi:[0,1]
	v_pk_mul_f32 v[24:25], v[34:35], s[0:1]
	v_pk_mul_f32 v[6:7], v[6:7], s[16:17]
	v_mov_b32_e32 v3, v15
	v_pk_fma_f32 v[6:7], v[12:13], s[16:17], v[6:7] neg_lo:[0,0,1] neg_hi:[0,0,1]
	v_pk_fma_f32 v[12:13], v[30:31], s[0:1], v[24:25]
	v_pk_add_f32 v[24:25], v[26:27], v[42:43] neg_lo:[0,1] neg_hi:[0,1]
	v_mov_b32_e32 v28, v4
	v_pk_mul_f32 v[26:27], v[24:25], s[4:5] op_sel_hi:[1,0]
	v_pk_add_f32 v[30:31], v[2:3], v[10:11]
	v_pk_fma_f32 v[24:25], v[24:25], s[34:35], v[26:27] op_sel:[0,0,1] op_sel_hi:[1,1,0] neg_lo:[0,0,1] neg_hi:[0,0,1]
	v_pk_add_f32 v[26:27], v[0:1], v[8:9]
	v_pk_add_f32 v[32:33], v[12:13], v[6:7]
	v_pk_add_f32 v[34:35], v[28:29], v[24:25]
	v_pk_add_f32 v[36:37], v[26:27], v[32:33]
	v_pk_add_f32 v[38:39], v[30:31], v[34:35]
	v_pk_add_f32 v[26:27], v[26:27], v[32:33] neg_lo:[0,1] neg_hi:[0,1]
	v_pk_add_f32 v[40:41], v[36:37], v[38:39]
	v_pk_add_f32 v[36:37], v[36:37], v[38:39] neg_lo:[0,1] neg_hi:[0,1]
	v_pk_mov_b32 v[40:41], v[40:41], v[40:41] op_sel:[1,0]
	v_pk_mul_f32 v[38:39], v[36:37], 0 op_sel_hi:[1,0]
	v_cvt_pk_f16_f32 v3, v40, v41
	v_pk_add_f32 v[40:41], v[36:37], v[38:39] op_sel:[0,1] op_sel_hi:[1,0] neg_lo:[0,1] neg_hi:[0,1]
	v_pk_add_f32 v[36:37], v[36:37], v[38:39] op_sel:[0,1] op_sel_hi:[1,0]
	v_pk_mul_f32 v[32:33], v[26:27], 0 op_sel_hi:[1,0]
	v_pk_mov_b32 v[36:37], v[40:41], v[36:37] op_sel:[1,0]
	v_pk_add_f32 v[30:31], v[30:31], v[34:35] neg_lo:[0,1] neg_hi:[0,1]
	v_cvt_pk_f16_f32 v28, v36, v37
	v_pk_add_f32 v[36:37], v[26:27], v[32:33] op_sel:[0,1] op_sel_hi:[1,0] neg_lo:[0,1] neg_hi:[0,1]
	v_pk_add_f32 v[26:27], v[26:27], v[32:33] op_sel:[0,1] op_sel_hi:[1,0]
	v_pk_mul_f32 v[32:33], v[30:31], 0 op_sel_hi:[1,0]
	v_pk_mov_b32 v[26:27], v[36:37], v[26:27] op_sel:[1,0]
	v_pk_add_f32 v[34:35], v[32:33], v[30:31] op_sel:[1,0] op_sel_hi:[0,1]
	v_pk_add_f32 v[30:31], v[32:33], v[30:31] op_sel:[1,0] op_sel_hi:[0,1] neg_lo:[0,1] neg_hi:[0,1]
	v_mov_b32_e32 v35, v31
	v_pk_add_f32 v[30:31], v[26:27], v[34:35]
	v_pk_add_f32 v[26:27], v[26:27], v[34:35] neg_lo:[0,1] neg_hi:[0,1]
	ds_write2_b32 v70, v3, v28 offset0:8 offset1:9
	v_cvt_pk_f16_f32 v3, v30, v31
	v_pk_mul_f32 v[30:31], v[26:27], 0 op_sel_hi:[1,0]
	v_pk_add_f32 v[0:1], v[0:1], v[8:9] neg_lo:[0,1] neg_hi:[0,1]
	v_pk_add_f32 v[32:33], v[26:27], v[30:31] op_sel:[0,1] op_sel_hi:[1,0] neg_lo:[0,1] neg_hi:[0,1]
	v_pk_add_f32 v[26:27], v[26:27], v[30:31] op_sel:[0,1] op_sel_hi:[1,0]
; __device__ __forceinline__ void lds_barrier() { asm volatile("s_waitcnt lgkmcnt(0)\n\ts_barrier" ::: "memory"); }
; __device__ __forceinline__ void make_spec(ldsf2 buf, LAS unsigned* spec, const float* __restrict__ kfrow) {
;     ...
;     dif_reg<4>(x, cf{1.0f, 0.0f});
; #pragma unroll
;     for (int m = 0; m < 16; ++m) { h2_t hv; hv.x = (_Float16)x[m].x; hv.y = (_Float16)x[m].y; spec[tid * 17 + m] = __builtin_bit_cast(unsigned, hv); }
;     lds_barrier();
; __device__ void ph_hyena_fft(const Params& P, int j, const bf16_t* __restrict__ projAT, const float* __restrict__ kf, bf16_t* __restrict__ yaT, unsigned char* lds_raw) {
;     ...
;         const float wv0 = cw[c], wv1 = cw[3072 + c], wv2 = cw[6144 + c], bv = cb[c];
;         const float wa0 = cw[1024 + c], wa1 = cw[3072 + 1024 + c], wa2 = cw[6144 + 1024 + c], ba = cb[1024 + c];
;         const float wb0 = cw[2048 + c], wb1 = cw[3072 + 2048 + c], wb2 = cw[6144 + 2048 + c], bb = cb[2048 + c];
;         const float sk0 = skip[c], sk1 = skip[1024 + c];
;         const bf16_t* vrow = projAT + (size_t)c * T_TOK; const bf16_t* x1row = projAT + (size_t)(1024 + c) * T_TOK;
;         const bf16_t* x2row = projAT + (size_t)(2048 + c) * T_TOK; const bf16_t* grow = projAT + (size_t)(3072 + c) * T_TOK;
	v_pk_mul_f32 v[8:9], v[0:1], 0 op_sel_hi:[1,0]
	v_cvt_pk_f16_f32 v26, v32, v27
	ds_write2_b32 v70, v3, v26 offset0:10 offset1:11
	v_pk_add_f32 v[26:27], v[0:1], v[8:9] op_sel:[0,1] op_sel_hi:[1,0] neg_lo:[0,1] neg_hi:[0,1]
	v_pk_add_f32 v[0:1], v[0:1], v[8:9] op_sel:[0,1] op_sel_hi:[1,0]
	v_pk_mov_b32 v[8:9], v[12:13], v[6:7] op_sel:[1,0]
	v_pk_mov_b32 v[6:7], v[6:7], v[12:13] op_sel:[1,0]
	v_mov_b32_e32 v3, v29
	v_pk_add_f32 v[6:7], v[8:9], v[6:7] neg_lo:[0,1] neg_hi:[0,1]
	v_pk_mov_b32 v[4:5], v[14:15], v[4:5] op_sel:[1,0]
	v_pk_fma_f32 v[8:9], v[6:7], 0, v[6:7] op_sel:[0,0,1] op_sel_hi:[1,0,0]
	v_pk_fma_f32 v[6:7], v[6:7], 0, v[6:7] op_sel:[0,0,1] op_sel_hi:[1,0,0] neg_lo:[0,0,1] neg_hi:[0,0,1]
	v_pk_mov_b32 v[0:1], v[26:27], v[0:1] op_sel:[1,0]
	v_mov_b32_e32 v9, v7
	v_mov_b32_e32 v6, v10
	v_mov_b32_e32 v7, v25
	v_pk_add_f32 v[2:3], v[2:3], v[6:7] neg_lo:[0,1] neg_hi:[0,1]
	v_pk_mov_b32 v[6:7], v[10:11], v[24:25] op_sel:[1,0]
	v_pk_mul_f32 v[2:3], v[2:3], s[16:17]
	v_pk_add_f32 v[4:5], v[4:5], v[6:7] neg_lo:[0,1] neg_hi:[0,1]
	s_lshl_b64 s[0:1], s[46:47], 2
	v_pk_fma_f32 v[6:7], v[4:5], s[16:17], v[2:3] neg_lo:[1,0,0] neg_hi:[1,0,0]
	v_pk_fma_f32 v[2:3], v[4:5], s[16:17], v[2:3]
	v_pk_mov_b32 v[10:11], v[6:7], v[6:7] op_sel:[1,0]
	v_pk_add_f32 v[4:5], v[0:1], v[8:9]
	v_pk_add_f32 v[6:7], v[2:3], v[6:7] op_sel:[0,1] op_sel_hi:[1,0]
	v_pk_add_f32 v[0:1], v[0:1], v[8:9] neg_lo:[0,1] neg_hi:[0,1]
	v_pk_add_f32 v[12:13], v[4:5], v[6:7]
	v_pk_add_f32 v[4:5], v[4:5], v[6:7] neg_lo:[0,1] neg_hi:[0,1]
	v_cvt_pk_f16_f32 v14, v12, v13
	v_pk_mul_f32 v[6:7], v[4:5], 0 op_sel_hi:[1,0]
	s_add_u32 s14, s38, s0
	v_pk_add_f32 v[12:13], v[4:5], v[6:7] op_sel:[0,1] op_sel_hi:[1,0] neg_lo:[0,1] neg_hi:[0,1]
	v_pk_add_f32 v[4:5], v[4:5], v[6:7] op_sel:[0,1] op_sel_hi:[1,0]
	s_addc_u32 s15, s39, s1
	v_cvt_pk_f16_f32 v4, v12, v5
	ds_write2_b32 v70, v14, v4 offset0:12 offset1:13
	v_pk_mul_f32 v[4:5], v[0:1], 0 op_sel_hi:[1,0]
	s_lshl_b64 s[10:11], s[46:47], 16
	v_pk_add_f32 v[6:7], v[0:1], v[4:5] op_sel:[0,1] op_sel_hi:[1,0] neg_lo:[0,1] neg_hi:[0,1]
	v_pk_add_f32 v[0:1], v[0:1], v[4:5] op_sel:[0,1] op_sel_hi:[1,0]
	s_add_u32 s26, s54, s0
	v_mov_b32_e32 v7, v1
	v_mov_b32_e32 v0, v2
	v_mov_b32_e32 v1, v11
	v_mov_b32_e32 v11, v3
	v_pk_add_f32 v[0:1], v[0:1], v[10:11] neg_lo:[0,1] neg_hi:[0,1]
	s_addc_u32 s27, s55, s1
	v_pk_fma_f32 v[2:3], v[0:1], 0, v[0:1] op_sel:[0,0,1] op_sel_hi:[1,0,0]
	v_pk_fma_f32 v[0:1], v[0:1], 0, v[0:1] op_sel:[0,0,1] op_sel_hi:[1,0,0] neg_lo:[0,0,1] neg_hi:[0,0,1]
	s_add_u32 s0, s56, s0
	v_mov_b32_e32 v3, v1
	v_pk_add_f32 v[0:1], v[6:7], v[2:3]
	s_addc_u32 s1, s57, s1
	v_cvt_pk_f16_f32 v8, v0, v1
	v_pk_add_f32 v[0:1], v[6:7], v[2:3] neg_lo:[0,1] neg_hi:[0,1]
	s_nop 0
	v_pk_mul_f32 v[2:3], v[0:1], 0 op_sel_hi:[1,0]
	s_nop 0
	v_pk_add_f32 v[4:5], v[0:1], v[2:3] op_sel:[0,1] op_sel_hi:[1,0] neg_lo:[0,1] neg_hi:[0,1]
	v_pk_add_f32 v[0:1], v[0:1], v[2:3] op_sel:[0,1] op_sel_hi:[1,0]
	s_nop 0
	v_cvt_pk_f16_f32 v0, v4, v1
	ds_write2_b32 v70, v8, v0 offset0:14 offset1:15
	s_waitcnt lgkmcnt(0)
	s_barrier
	v_mov_b32_e32 v0, 0x3000
	global_load_dword v25, v193, s[14:15]
	global_load_dword v24, v0, s[14:15]
	v_mov_b32_e32 v0, 0x6000
	global_load_dword v26, v0, s[14:15]
	v_mov_b32_e32 v0, 0x7000
	global_load_dword v28, v193, s[26:27]
	global_load_dword v30, v231, s[14:15]
	global_load_dword v32, v230, s[14:15]
	global_load_dword v34, v0, s[14:15]
	global_load_dword v36, v231, s[26:27]
	global_load_dword v39, v238, s[14:15]
	v_mov_b32_e32 v0, 0x5000
	global_load_dword v38, v0, s[14:15]
	v_mov_b32_e32 v0, 0x8000
	global_load_dword v40, v0, s[14:15]
	global_load_dword v42, v238, s[26:27]
	global_load_dword v44, v193, s[0:1]
	global_load_dword v46, v231, s[0:1]
	s_lshl_b64 s[0:1], s[6:7], 1
	v_readlane_b32 s14, v252, 36
	v_readlane_b32 s15, v252, 37
	s_add_u32 s47, s14, s0
	s_addc_u32 s58, s15, s1
	s_lshl_b64 s[6:7], s[30:31], 16
	s_add_u32 s59, s14, s6
	s_addc_u32 s60, s15, s7
	s_add_u32 s6, s14, s10
	s_addc_u32 s7, s15, s11
	s_add_u32 s61, s6, 0x8000000
	s_addc_u32 s52, s7, 0
	v_lshl_add_u64 v[0:1], v[18:19], 0, s[10:11]
	s_mov_b64 s[6:7], 0xc000000
	v_lshl_add_u64 v[48:49], v[0:1], 0, s[6:7]
	v_lshl_add_u64 v[50:51], v[20:21], 0, s[0:1]
	s_waitcnt vmcnt(13)
	v_mov_b32_e32 v58, v25
	v_mov_b32_e32 v59, v25
	s_waitcnt vmcnt(12)
	v_mov_b32_e32 v60, v24
	s_waitcnt vmcnt(10)
	v_mov_b32_e32 v29, v28
	v_mov_b32_e32 v27, v26
	s_waitcnt vmcnt(6)
	v_mov_b32_e32 v37, v36
	s_waitcnt vmcnt(5)
	v_mov_b32_e32 v52, v39
	v_mov_b32_e32 v53, v39
	s_waitcnt vmcnt(4)
	v_mov_b32_e32 v54, v38
	s_waitcnt vmcnt(3)
	v_mov_b32_e32 v41, v40
	s_waitcnt vmcnt(2)
	v_mov_b32_e32 v43, v42
	s_waitcnt vmcnt(0)
	v_mov_b32_e32 v47, v46
	v_mov_b32_e32 v55, v38
	v_mov_b32_e32 v45, v44
	v_mov_b32_e32 v35, v34
	v_mov_b32_e32 v31, v30
	v_mov_b32_e32 v33, v32
	v_mov_b32_e32 v56, v32
	v_mov_b32_e32 v57, v30
	v_mov_b32_e32 v61, v24

; #define LAS __attribute__((address_space(3)))
; __device__ __forceinline__ cf twc(cf ws, int k16) { if (k16 == 0) return ws; if (k16 == 4) return cf{ws.y, -ws.x}; return cmul(ws, cf{c16(k16), -s16(k16)}); }
; template <int LR> __device__ __forceinline__ void dif_reg(cf (&x)[1 << LR], cf w) {
;     constexpr int R = 1 << LR; cf ws = w;
; #pragma unroll
;     for (int s = 0; s < LR; ++s) { const int half = R >> (s + 1);
; #pragma unroll
;         for (int m0 = 0; m0 < R; m0 += 2 * half)
; #pragma unroll
;             for (int mm = 0; mm < half; ++mm) { const int ia = m0 + mm, ib = ia + half; const cf a = x[ia], b = x[ib];
;                 x[ia] = cf{a.x + b.x, a.y + b.y}; const cf d{a.x - b.x, a.y - b.y};
;                 x[ib] = cmul(d, twc(ws, (mm << s) * (16 / R))); }
;         ws = cmul(ws, ws); }
; }
; template <int LR, bool INV> __device__ __forceinline__ void fft_pass(ldsf2 buf, int base, int stride, int twi) {
;     constexpr int R = 1 << LR; cf x[R];
;     const v2f wv = ((ldsf2)((LAS unsigned char*)buf + 139264))[twi];
; #pragma unroll
;     for (int m = 0; m < R; ++m) { const v2f v = buf[base + m * stride]; x[m] = cf{v.x, v.y}; }
;     const cf w{wv.x, wv.y};
;     if (INV) dit_reg<LR>(x, w); else dif_reg<LR>(x, w);
; #pragma unroll
;     for (int m = 0; m < R; ++m) buf[base + m * stride] = mkv2(x[m].x, x[m].y);
; }
.LBB0_351:
	v_or_b32_e32 v73, s0, v69
	ds_read_b64 v[90:91], v72
	v_lshlrev_b32_e32 v74, 3, v73
	v_ashrrev_i32_e32 v73, 1, v73
	v_add3_u32 v73, v68, v74, v73
	ds_read2_b64 v[74:77], v73 offset1:17
	ds_read2_b64 v[78:81], v73 offset0:34 offset1:51
	ds_read2_b64 v[82:85], v73 offset0:68 offset1:85
	ds_read2_b64 v[86:89], v73 offset0:102 offset1:119
	s_waitcnt lgkmcnt(4)
	v_pk_add_f32 v[92:93], v[90:91], v[90:91] op_sel:[0,1] op_sel_hi:[1,0] neg_lo:[0,0] neg_hi:[0,1]
	v_pk_mul_f32 v[94:95], v[92:93], s[16:17] op_sel:[0,0] op_sel_hi:[1,0]
	v_pk_mul_f32 v[96:97], v[92:93], s[16:17] op_sel:[1,0] op_sel_hi:[0,0] neg_lo:[0,0] neg_hi:[1,0]
	v_pk_mul_f32 v[98:99], v[90:91], v[90:91] op_sel:[1,1] op_sel_hi:[1,0]
	v_pk_fma_f32 v[98:99], v[90:91], v[90:91], v[98:99] op_sel:[0,0,0] op_sel_hi:[0,1,1] neg_lo:[0,0,1] neg_hi:[0,0,0]
	v_pk_mul_f32 v[100:101], v[98:99], v[98:99] op_sel:[1,1] op_sel_hi:[1,0]
	v_pk_fma_f32 v[100:101], v[98:99], v[98:99], v[100:101] op_sel:[0,0,0] op_sel_hi:[0,1,1] neg_lo:[0,0,1] neg_hi:[0,0,0]
	s_waitcnt lgkmcnt(0)
	v_pk_add_f32 v[102:103], v[74:75], v[82:83] neg_lo:[0,1] neg_hi:[0,1]
	v_pk_add_f32 v[104:105], v[76:77], v[84:85] neg_lo:[0,1] neg_hi:[0,1]
	v_pk_add_f32 v[106:107], v[78:79], v[86:87] neg_lo:[0,1] neg_hi:[0,1]
	v_pk_add_f32 v[108:109], v[80:81], v[88:89] neg_lo:[0,1] neg_hi:[0,1]
	v_pk_add_f32 v[74:75], v[74:75], v[82:83]
	v_pk_add_f32 v[76:77], v[76:77], v[84:85]
	v_pk_add_f32 v[78:79], v[78:79], v[86:87]
	v_pk_add_f32 v[80:81], v[80:81], v[88:89]
	v_pk_mul_f32 v[82:83], v[102:103], v[90:91] op_sel:[1,1] op_sel_hi:[1,0]
	v_pk_mul_f32 v[84:85], v[104:105], v[94:95] op_sel:[1,1] op_sel_hi:[1,0]
	v_pk_mul_f32 v[86:87], v[106:107], v[90:91] op_sel:[1,0] op_sel_hi:[1,1]
	v_pk_mul_f32 v[88:89], v[108:109], v[96:97] op_sel:[1,1] op_sel_hi:[1,0]
	v_pk_fma_f32 v[82:83], v[102:103], v[90:91], v[82:83] op_sel:[0,0,0] op_sel_hi:[0,1,1] neg_lo:[0,0,1] neg_hi:[0,0,0]
	v_pk_fma_f32 v[84:85], v[104:105], v[94:95], v[84:85] op_sel:[0,0,0] op_sel_hi:[0,1,1] neg_lo:[0,0,1] neg_hi:[0,0,0]
	v_pk_fma_f32 v[86:87], v[106:107], v[90:91], v[86:87] op_sel:[0,1,0] op_sel_hi:[0,0,1] neg_lo:[0,0,0] neg_hi:[0,1,0]
	v_pk_fma_f32 v[88:89], v[108:109], v[96:97], v[88:89] op_sel:[0,0,0] op_sel_hi:[0,1,1] neg_lo:[0,0,1] neg_hi:[0,0,0]
	v_pk_add_f32 v[102:103], v[74:75], v[78:79] neg_lo:[0,1] neg_hi:[0,1]
	v_pk_add_f32 v[104:105], v[76:77], v[80:81] neg_lo:[0,1] neg_hi:[0,1]
	v_pk_add_f32 v[106:107], v[82:83], v[86:87] neg_lo:[0,1] neg_hi:[0,1]
	v_pk_add_f32 v[108:109], v[84:85], v[88:89] neg_lo:[0,1] neg_hi:[0,1]
	v_pk_add_f32 v[74:75], v[74:75], v[78:79]
	v_pk_add_f32 v[76:77], v[76:77], v[80:81]
	v_pk_add_f32 v[82:83], v[82:83], v[86:87]
	v_pk_add_f32 v[84:85], v[84:85], v[88:89]
	v_pk_mul_f32 v[78:79], v[102:103], v[98:99] op_sel:[1,1] op_sel_hi:[1,0]
	v_pk_mul_f32 v[80:81], v[104:105], v[98:99] op_sel:[1,0] op_sel_hi:[1,1]
	v_pk_mul_f32 v[86:87], v[106:107], v[98:99] op_sel:[1,1] op_sel_hi:[1,0]
	v_pk_mul_f32 v[88:89], v[108:109], v[98:99] op_sel:[1,0] op_sel_hi:[1,1]
	v_pk_fma_f32 v[78:79], v[102:103], v[98:99], v[78:79] op_sel:[0,0,0] op_sel_hi:[0,1,1] neg_lo:[0,0,1] neg_hi:[0,0,0]
	v_pk_fma_f32 v[80:81], v[104:105], v[98:99], v[80:81] op_sel:[0,1,0] op_sel_hi:[0,0,1] neg_lo:[0,0,0] neg_hi:[0,1,0]
	v_pk_fma_f32 v[86:87], v[106:107], v[98:99], v[86:87] op_sel:[0,0,0] op_sel_hi:[0,1,1] neg_lo:[0,0,1] neg_hi:[0,0,0]
	v_pk_fma_f32 v[88:89], v[108:109], v[98:99], v[88:89] op_sel:[0,1,0] op_sel_hi:[0,0,1] neg_lo:[0,0,0] neg_hi:[0,1,0]
	v_pk_add_f32 v[102:103], v[74:75], v[76:77] neg_lo:[0,1] neg_hi:[0,1]
	v_pk_add_f32 v[104:105], v[78:79], v[80:81] neg_lo:[0,1] neg_hi:[0,1]
	v_pk_add_f32 v[106:107], v[82:83], v[84:85] neg_lo:[0,1] neg_hi:[0,1]
	v_pk_add_f32 v[108:109], v[86:87], v[88:89] neg_lo:[0,1] neg_hi:[0,1]
	v_pk_add_f32 v[74:75], v[74:75], v[76:77]
	v_pk_add_f32 v[78:79], v[78:79], v[80:81]
	v_pk_add_f32 v[82:83], v[82:83], v[84:85]
	v_pk_add_f32 v[86:87], v[86:87], v[88:89]
	v_pk_mul_f32 v[76:77], v[102:103], v[100:101] op_sel:[1,1] op_sel_hi:[1,0]
	v_pk_mul_f32 v[80:81], v[104:105], v[100:101] op_sel:[1,1] op_sel_hi:[1,0]
	v_pk_mul_f32 v[84:85], v[106:107], v[100:101] op_sel:[1,1] op_sel_hi:[1,0]
	v_pk_mul_f32 v[88:89], v[108:109], v[100:101] op_sel:[1,1] op_sel_hi:[1,0]
	v_pk_fma_f32 v[76:77], v[102:103], v[100:101], v[76:77] op_sel:[0,0,0] op_sel_hi:[0,1,1] neg_lo:[0,0,1] neg_hi:[0,0,0]
	v_pk_fma_f32 v[80:81], v[104:105], v[100:101], v[80:81] op_sel:[0,0,0] op_sel_hi:[0,1,1] neg_lo:[0,0,1] neg_hi:[0,0,0]
	v_pk_fma_f32 v[84:85], v[106:107], v[100:101], v[84:85] op_sel:[0,0,0] op_sel_hi:[0,1,1] neg_lo:[0,0,1] neg_hi:[0,0,0]
	v_pk_fma_f32 v[88:89], v[108:109], v[100:101], v[88:89] op_sel:[0,0,0] op_sel_hi:[0,1,1] neg_lo:[0,0,1] neg_hi:[0,0,0]
	ds_write2_b64 v73, v[74:75], v[76:77] offset1:17
	ds_write2_b64 v73, v[78:79], v[80:81] offset0:34 offset1:51
	ds_write2_b64 v73, v[82:83], v[84:85] offset0:68 offset1:85
	ds_write2_b64 v73, v[86:87], v[88:89] offset0:102 offset1:119
	s_movk_i32 s0, 0x200
	s_and_b64 vcc, exec, s[6:7]
	s_mov_b64 s[6:7], 0
	s_cbranch_vccnz .LBB0_351
; __device__ __forceinline__ int otid() { int t = threadIdx.x; asm volatile("" : "+v"(t)); return t; }
; __device__ __forceinline__ cf twc(cf ws, int k16) { if (k16 == 0) return ws; if (k16 == 4) return cf{ws.y, -ws.x}; return cmul(ws, cf{c16(k16), -s16(k16)}); }
; template <int LR> __device__ __forceinline__ void dif_reg(cf (&x)[1 << LR], cf w) {
;     constexpr int R = 1 << LR; cf ws = w;
; #pragma unroll
;     for (int s = 0; s < LR; ++s) { const int half = R >> (s + 1);
; #pragma unroll
;         for (int m0 = 0; m0 < R; m0 += 2 * half)
; #pragma unroll
;             for (int mm = 0; mm < half; ++mm) { const int ia = m0 + mm, ib = ia + half; const cf a = x[ia], b = x[ib];
;                 x[ia] = cf{a.x + b.x, a.y + b.y}; const cf d{a.x - b.x, a.y - b.y};
;                 x[ib] = cmul(d, twc(ws, (mm << s) * (16 / R))); }
;         ws = cmul(ws, ws); }
; }
; __device__ __forceinline__ void fft_conv(ldsf2 buf, const LAS unsigned* spec) {
;     ...
;     { const int tid = otid(); cf x[16];
; #pragma unroll
;       for (int m = 0; m < 16; ++m) { const v2f v = buf[tid * 17 + m]; x[m] = cf{v.x, v.y}; }
;       dif_reg<4>(x, cf{1.0f, 0.0f});
; #pragma unroll
;       for (int m = 0; m < 16; ++m) { const h2_t hv = __builtin_bit_cast(h2_t, spec[tid * 17 + m]); x[m] = cmul(x[m], cf{(float)hv.x, (float)hv.y}); }
;       dit_reg<4>(x, cf{1.0f, 0.0f});
	v_mov_b32_e32 v158, v195
	s_movk_i32 s0, 0x88
	s_waitcnt lgkmcnt(0)
	s_mov_b32 s86, s63
	v_mul_lo_u32 v68, v158, s0
	v_add_u32_e32 v147, 0, v68
	ds_read2_b64 v[72:75], v147 offset1:1
	ds_read2_b64 v[76:79], v147 offset0:2 offset1:3
	ds_read2_b64 v[90:93], v147 offset0:4 offset1:5
	ds_read2_b64 v[94:97], v147 offset0:6 offset1:7
	ds_read2_b64 v[98:101], v147 offset0:8 offset1:9
	ds_read2_b64 v[102:105], v147 offset0:10 offset1:11
	ds_read2_b64 v[118:121], v147 offset0:12 offset1:13
	ds_read2_b64 v[126:129], v147 offset0:14 offset1:15
	s_mov_b32 s6, s63
	s_mov_b32 s7, s16
	s_mov_b32 s17, s5
	s_mov_b32 s0, s16
	s_mov_b32 s1, s4
	s_mov_b32 s0, s63
	s_mov_b32 s1, s5
	s_mov_b32 s0, s87
	s_mov_b32 s1, s4
	s_mov_b32 s1, s5
	s_mov_b32 s35, s4
	s_mov_b32 s12, s63
	s_movk_i32 s0, 0x44
	v_mul_lo_u32 v106, v158, s0
	v_add_u32_e32 v106, 0, v106
	v_add_u32_e32 v106, 0x11000, v106
	ds_read2_b32 v[156:157], v106 offset1:1
	ds_read2_b32 v[158:159], v106 offset0:2 offset1:3
	ds_read2_b32 v[160:161], v106 offset0:4 offset1:5
	ds_read2_b32 v[162:163], v106 offset0:6 offset1:7
	ds_read2_b32 v[164:165], v106 offset0:8 offset1:9
	ds_read2_b32 v[134:135], v106 offset0:10 offset1:11
	ds_read2_b32 v[130:131], v106 offset0:12 offset1:13
	ds_read2_b32 v[168:169], v106 offset0:14 offset1:15
	s_mov_b32 s0, s5
	s_mov_b64 s[6:7], -1
	s_mov_b32 s35, s13
	s_mov_b32 s0, s13
	s_waitcnt lgkmcnt(8)
	v_pk_add_f32 v[80:81], v[72:73], v[98:99]
	v_pk_add_f32 v[82:83], v[74:75], v[100:101]
	v_pk_add_f32 v[84:85], v[76:77], v[102:103]
	v_pk_add_f32 v[86:87], v[78:79], v[104:105]
	v_pk_add_f32 v[72:73], v[72:73], v[98:99] neg_lo:[0,1] neg_hi:[0,1]
	v_pk_add_f32 v[74:75], v[74:75], v[100:101] neg_lo:[0,1] neg_hi:[0,1]
	v_pk_add_f32 v[76:77], v[76:77], v[102:103] neg_lo:[0,1] neg_hi:[0,1]
	v_pk_add_f32 v[78:79], v[78:79], v[104:105] neg_lo:[0,1] neg_hi:[0,1]
	v_pk_mul_f32 v[100:101], v[74:75], s[4:5] op_sel:[1,1] op_sel_hi:[1,0] neg_lo:[0,1] neg_hi:[0,0]
	v_pk_mul_f32 v[102:103], v[76:77], s[16:17] op_sel:[1,0] op_sel_hi:[1,0] neg_lo:[0,1] neg_hi:[0,0]
	v_pk_mul_f32 v[104:105], v[78:79], s[4:5] op_sel:[1,0] op_sel_hi:[1,1] neg_lo:[0,1] neg_hi:[0,0]
	v_pk_fma_f32 v[100:101], v[74:75], s[4:5], v[100:101] op_sel:[0,0,0] op_sel_hi:[0,1,1] neg_lo:[0,0,1] neg_hi:[0,1,0]
	v_pk_fma_f32 v[102:103], v[76:77], s[16:17], v[102:103] op_sel:[0,0,0] op_sel_hi:[0,0,1] neg_lo:[0,0,1] neg_hi:[0,1,0]
	v_pk_fma_f32 v[104:105], v[78:79], s[4:5], v[104:105] op_sel:[0,1,0] op_sel_hi:[0,0,1] neg_lo:[0,0,1] neg_hi:[0,1,0]
	v_pk_add_f32 v[88:89], v[90:91], v[118:119]
	v_pk_add_f32 v[108:109], v[92:93], v[120:121]
	v_pk_add_f32 v[110:111], v[94:95], v[126:127]
	v_pk_add_f32 v[112:113], v[96:97], v[128:129]
	v_pk_add_f32 v[90:91], v[90:91], v[118:119] op_sel:[1,1] op_sel_hi:[0,0] neg_lo:[0,1] neg_hi:[1,0]
	v_pk_add_f32 v[92:93], v[92:93], v[120:121] neg_lo:[0,1] neg_hi:[0,1]
	v_pk_add_f32 v[94:95], v[94:95], v[126:127] neg_lo:[0,1] neg_hi:[0,1]
	v_pk_add_f32 v[96:97], v[96:97], v[128:129] neg_lo:[0,1] neg_hi:[0,1]
	v_pk_mul_f32 v[120:121], v[92:93], s[4:5] op_sel:[1,0] op_sel_hi:[1,1] neg_lo:[0,1] neg_hi:[0,1]
	v_pk_mul_f32 v[126:127], v[94:95], s[16:17] op_sel:[1,0] op_sel_hi:[1,0] neg_lo:[0,1] neg_hi:[0,1]
	v_pk_mul_f32 v[128:129], v[96:97], s[4:5] op_sel:[1,1] op_sel_hi:[1,0] neg_lo:[0,1] neg_hi:[0,1]
	v_pk_fma_f32 v[120:121], v[92:93], s[4:5], v[120:121] op_sel:[0,1,0] op_sel_hi:[0,0,1] neg_lo:[0,1,1] neg_hi:[0,1,0]
	v_pk_fma_f32 v[126:127], v[94:95], s[16:17], v[126:127] op_sel:[0,0,0] op_sel_hi:[0,0,1] neg_lo:[0,1,1] neg_hi:[0,1,0]
	v_pk_fma_f32 v[128:129], v[96:97], s[4:5], v[128:129] op_sel:[0,0,0] op_sel_hi:[0,1,1] neg_lo:[0,1,1] neg_hi:[0,1,0]
	v_pk_add_f32 v[114:115], v[80:81], v[88:89]
	v_pk_add_f32 v[116:117], v[82:83], v[108:109]
	v_pk_add_f32 v[122:123], v[84:85], v[110:111]
	v_pk_add_f32 v[124:125], v[86:87], v[112:113]
	v_pk_add_f32 v[80:81], v[80:81], v[88:89] neg_lo:[0,1] neg_hi:[0,1]
	v_pk_add_f32 v[82:83], v[82:83], v[108:109] neg_lo:[0,1] neg_hi:[0,1]
	v_pk_add_f32 v[84:85], v[84:85], v[110:111] op_sel:[1,1] op_sel_hi:[0,0] neg_lo:[0,1] neg_hi:[1,0]
	v_pk_add_f32 v[86:87], v[86:87], v[112:113] neg_lo:[0,1] neg_hi:[0,1]
	v_pk_mul_f32 v[108:109], v[82:83], s[16:17] op_sel:[1,0] op_sel_hi:[1,0] neg_lo:[0,1] neg_hi:[0,0]
	v_pk_mul_f32 v[112:113], v[86:87], s[16:17] op_sel:[1,0] op_sel_hi:[1,0] neg_lo:[0,1] neg_hi:[0,1]
	v_pk_fma_f32 v[108:109], v[82:83], s[16:17], v[108:109] op_sel:[0,0,0] op_sel_hi:[0,0,1] neg_lo:[0,0,1] neg_hi:[0,1,0]
	v_pk_fma_f32 v[112:113], v[86:87], s[16:17], v[112:113] op_sel:[0,0,0] op_sel_hi:[0,0,1] neg_lo:[0,1,1] neg_hi:[0,1,0]
	v_pk_add_f32 v[132:133], v[72:73], v[90:91]
	v_pk_add_f32 v[148:149], v[100:101], v[120:121]
	v_pk_add_f32 v[150:151], v[102:103], v[126:127]
	v_pk_add_f32 v[152:153], v[104:105], v[128:129]
	v_pk_add_f32 v[72:73], v[72:73], v[90:91] neg_lo:[0,1] neg_hi:[0,1]
	v_pk_add_f32 v[100:101], v[100:101], v[120:121] neg_lo:[0,1] neg_hi:[0,1]
	v_pk_add_f32 v[102:103], v[102:103], v[126:127] op_sel:[1,1] op_sel_hi:[0,0] neg_lo:[0,1] neg_hi:[1,0]
	v_pk_add_f32 v[104:105], v[104:105], v[128:129] neg_lo:[0,1] neg_hi:[0,1]
	v_pk_mul_f32 v[120:121], v[100:101], s[16:17] op_sel:[1,0] op_sel_hi:[1,0] neg_lo:[0,1] neg_hi:[0,0]
	v_pk_mul_f32 v[128:129], v[104:105], s[16:17] op_sel:[1,0] op_sel_hi:[1,0] neg_lo:[0,1] neg_hi:[0,1]
	v_pk_fma_f32 v[120:121], v[100:101], s[16:17], v[120:121] op_sel:[0,0,0] op_sel_hi:[0,0,1] neg_lo:[0,0,1] neg_hi:[0,1,0]
	v_pk_fma_f32 v[128:129], v[104:105], s[16:17], v[128:129] op_sel:[0,0,0] op_sel_hi:[0,0,1] neg_lo:[0,1,1] neg_hi:[0,1,0]
	v_pk_add_f32 v[154:155], v[114:115], v[122:123]
	v_pk_add_f32 v[166:167], v[116:117], v[124:125]
; __device__ __forceinline__ cf twc(cf ws, int k16) { if (k16 == 0) return ws; if (k16 == 4) return cf{ws.y, -ws.x}; return cmul(ws, cf{c16(k16), -s16(k16)}); }
; template <int LR> __device__ __forceinline__ void dif_reg(cf (&x)[1 << LR], cf w) {
;     constexpr int R = 1 << LR; cf ws = w;
; #pragma unroll
;     for (int s = 0; s < LR; ++s) { const int half = R >> (s + 1);
; #pragma unroll
;         for (int m0 = 0; m0 < R; m0 += 2 * half)
; #pragma unroll
;             for (int mm = 0; mm < half; ++mm) { const int ia = m0 + mm, ib = ia + half; const cf a = x[ia], b = x[ib];
;                 x[ia] = cf{a.x + b.x, a.y + b.y}; const cf d{a.x - b.x, a.y - b.y};
;                 x[ib] = cmul(d, twc(ws, (mm << s) * (16 / R))); }
;         ws = cmul(ws, ws); }
; }
; __device__ __forceinline__ void fft_conv(ldsf2 buf, const LAS unsigned* spec) {
;     ...
;       dif_reg<4>(x, cf{1.0f, 0.0f});
; #pragma unroll
;       for (int m = 0; m < 16; ++m) { const h2_t hv = __builtin_bit_cast(h2_t, spec[tid * 17 + m]); x[m] = cmul(x[m], cf{(float)hv.x, (float)hv.y}); }
	v_pk_add_f32 v[98:99], v[80:81], v[84:85]
	v_pk_add_f32 v[74:75], v[108:109], v[112:113]
	v_pk_add_f32 v[114:115], v[114:115], v[122:123] neg_lo:[0,1] neg_hi:[0,1]
	v_pk_add_f32 v[116:117], v[116:117], v[124:125] op_sel:[1,1] op_sel_hi:[0,0] neg_lo:[0,1] neg_hi:[1,0]
	v_pk_add_f32 v[80:81], v[80:81], v[84:85] neg_lo:[0,1] neg_hi:[0,1]
	v_pk_add_f32 v[108:109], v[108:109], v[112:113] op_sel:[1,1] op_sel_hi:[0,0] neg_lo:[0,1] neg_hi:[1,0]
	v_pk_add_f32 v[76:77], v[132:133], v[150:151]
	v_pk_add_f32 v[78:79], v[148:149], v[152:153]
	v_pk_add_f32 v[118:119], v[72:73], v[102:103]
	v_pk_add_f32 v[92:93], v[120:121], v[128:129]
	v_pk_add_f32 v[132:133], v[132:133], v[150:151] neg_lo:[0,1] neg_hi:[0,1]
	v_pk_add_f32 v[148:149], v[148:149], v[152:153] op_sel:[1,1] op_sel_hi:[0,0] neg_lo:[0,1] neg_hi:[1,0]
	v_pk_add_f32 v[72:73], v[72:73], v[102:103] neg_lo:[0,1] neg_hi:[0,1]
	v_pk_add_f32 v[120:121], v[120:121], v[128:129] op_sel:[1,1] op_sel_hi:[0,0] neg_lo:[0,1] neg_hi:[1,0]
	v_pk_add_f32 v[94:95], v[154:155], v[166:167]
	v_pk_add_f32 v[96:97], v[114:115], v[116:117]
	v_pk_add_f32 v[88:89], v[98:99], v[74:75]
	v_pk_add_f32 v[82:83], v[80:81], v[108:109]
	v_pk_add_f32 v[154:155], v[154:155], v[166:167] neg_lo:[0,1] neg_hi:[0,1]
	v_pk_add_f32 v[114:115], v[114:115], v[116:117] neg_lo:[0,1] neg_hi:[0,1]
	v_pk_add_f32 v[98:99], v[98:99], v[74:75] neg_lo:[0,1] neg_hi:[0,1]
	v_pk_add_f32 v[80:81], v[80:81], v[108:109] neg_lo:[0,1] neg_hi:[0,1]
	v_pk_add_f32 v[110:111], v[76:77], v[78:79]
	v_pk_add_f32 v[86:87], v[132:133], v[148:149]
	v_pk_add_f32 v[90:91], v[118:119], v[92:93]
	v_pk_add_f32 v[100:101], v[72:73], v[120:121]
	v_pk_add_f32 v[76:77], v[76:77], v[78:79] neg_lo:[0,1] neg_hi:[0,1]
	v_pk_add_f32 v[132:133], v[132:133], v[148:149] neg_lo:[0,1] neg_hi:[0,1]
	v_pk_add_f32 v[118:119], v[118:119], v[92:93] neg_lo:[0,1] neg_hi:[0,1]
	v_pk_add_f32 v[72:73], v[72:73], v[120:121] neg_lo:[0,1] neg_hi:[0,1]
	s_waitcnt lgkmcnt(0)
	v_cvt_f32_f16_e32 v126, v156
	v_cvt_f32_f16_e32 v122, v157
	v_cvt_f32_f16_e32 v84, v158
	v_cvt_f32_f16_e32 v150, v159
	v_cvt_f32_f16_sdwa v127, v156 dst_sel:DWORD dst_unused:UNUSED_PAD src0_sel:WORD_1
	v_cvt_f32_f16_sdwa v123, v157 dst_sel:DWORD dst_unused:UNUSED_PAD src0_sel:WORD_1
	v_cvt_f32_f16_sdwa v85, v158 dst_sel:DWORD dst_unused:UNUSED_PAD src0_sel:WORD_1
	v_cvt_f32_f16_sdwa v151, v159 dst_sel:DWORD dst_unused:UNUSED_PAD src0_sel:WORD_1
	v_pk_mul_f32 v[104:105], v[94:95], v[126:127] op_sel:[1,1] op_sel_hi:[1,0]
	v_pk_mul_f32 v[124:125], v[154:155], v[122:123] op_sel:[1,1] op_sel_hi:[1,0]
	v_pk_mul_f32 v[112:113], v[96:97], v[84:85] op_sel:[1,1] op_sel_hi:[1,0]
	v_pk_mul_f32 v[152:153], v[114:115], v[150:151] op_sel:[1,1] op_sel_hi:[1,0]
	v_pk_fma_f32 v[126:127], v[94:95], v[126:127], v[104:105] op_sel:[0,0,0] op_sel_hi:[0,1,1] neg_lo:[0,0,1] neg_hi:[0,0,0]
	v_pk_fma_f32 v[122:123], v[154:155], v[122:123], v[124:125] op_sel:[0,0,0] op_sel_hi:[0,1,1] neg_lo:[0,0,1] neg_hi:[0,0,0]
	v_pk_fma_f32 v[84:85], v[96:97], v[84:85], v[112:113] op_sel:[0,0,0] op_sel_hi:[0,1,1] neg_lo:[0,0,1] neg_hi:[0,0,0]
	v_pk_fma_f32 v[150:151], v[114:115], v[150:151], v[152:153] op_sel:[0,0,0] op_sel_hi:[0,1,1] neg_lo:[0,0,1] neg_hi:[0,0,0]
	v_cvt_f32_f16_e32 v102, v160
	v_cvt_f32_f16_e32 v166, v161
	v_cvt_f32_f16_e32 v74, v162
	v_cvt_f32_f16_e32 v78, v163
	v_cvt_f32_f16_sdwa v103, v160 dst_sel:DWORD dst_unused:UNUSED_PAD src0_sel:WORD_1
	v_cvt_f32_f16_sdwa v167, v161 dst_sel:DWORD dst_unused:UNUSED_PAD src0_sel:WORD_1
	v_cvt_f32_f16_sdwa v75, v162 dst_sel:DWORD dst_unused:UNUSED_PAD src0_sel:WORD_1
	v_cvt_f32_f16_sdwa v79, v163 dst_sel:DWORD dst_unused:UNUSED_PAD src0_sel:WORD_1
	v_pk_mul_f32 v[128:129], v[88:89], v[102:103] op_sel:[1,1] op_sel_hi:[1,0]
	v_pk_mul_f32 v[116:117], v[98:99], v[166:167] op_sel:[1,1] op_sel_hi:[1,0]
	v_pk_mul_f32 v[108:109], v[82:83], v[74:75] op_sel:[1,1] op_sel_hi:[1,0]
	v_pk_mul_f32 v[148:149], v[80:81], v[78:79] op_sel:[1,1] op_sel_hi:[1,0]
	v_pk_fma_f32 v[102:103], v[88:89], v[102:103], v[128:129] op_sel:[0,0,0] op_sel_hi:[0,1,1] neg_lo:[0,0,1] neg_hi:[0,0,0]
	v_pk_fma_f32 v[166:167], v[98:99], v[166:167], v[116:117] op_sel:[0,0,0] op_sel_hi:[0,1,1] neg_lo:[0,0,1] neg_hi:[0,0,0]
	v_pk_fma_f32 v[74:75], v[82:83], v[74:75], v[108:109] op_sel:[0,0,0] op_sel_hi:[0,1,1] neg_lo:[0,0,1] neg_hi:[0,0,0]
	v_pk_fma_f32 v[78:79], v[80:81], v[78:79], v[148:149] op_sel:[0,0,0] op_sel_hi:[0,1,1] neg_lo:[0,0,1] neg_hi:[0,0,0]
	v_cvt_f32_f16_e32 v92, v164
	v_cvt_f32_f16_e32 v104, v165
	v_cvt_f32_f16_e32 v124, v134
	v_cvt_f32_f16_e32 v112, v135
	v_cvt_f32_f16_sdwa v93, v164 dst_sel:DWORD dst_unused:UNUSED_PAD src0_sel:WORD_1
	v_cvt_f32_f16_sdwa v105, v165 dst_sel:DWORD dst_unused:UNUSED_PAD src0_sel:WORD_1
	v_cvt_f32_f16_sdwa v125, v134 dst_sel:DWORD dst_unused:UNUSED_PAD src0_sel:WORD_1
	v_cvt_f32_f16_sdwa v113, v135 dst_sel:DWORD dst_unused:UNUSED_PAD src0_sel:WORD_1
	v_pk_mul_f32 v[120:121], v[110:111], v[92:93] op_sel:[1,1] op_sel_hi:[1,0]
	v_pk_mul_f32 v[94:95], v[76:77], v[104:105] op_sel:[1,1] op_sel_hi:[1,0]
	v_pk_mul_f32 v[154:155], v[86:87], v[124:125] op_sel:[1,1] op_sel_hi:[1,0]
	v_pk_mul_f32 v[96:97], v[132:133], v[112:113] op_sel:[1,1] op_sel_hi:[1,0]
	v_pk_fma_f32 v[92:93], v[110:111], v[92:93], v[120:121] op_sel:[0,0,0] op_sel_hi:[0,1,1] neg_lo:[0,0,1] neg_hi:[0,0,0]
	v_pk_fma_f32 v[104:105], v[76:77], v[104:105], v[94:95] op_sel:[0,0,0] op_sel_hi:[0,1,1] neg_lo:[0,0,1] neg_hi:[0,0,0]
	v_pk_fma_f32 v[124:125], v[86:87], v[124:125], v[154:155] op_sel:[0,0,0] op_sel_hi:[0,1,1] neg_lo:[0,0,1] neg_hi:[0,0,0]
	v_pk_fma_f32 v[112:113], v[132:133], v[112:113], v[96:97] op_sel:[0,0,0] op_sel_hi:[0,1,1] neg_lo:[0,0,1] neg_hi:[0,0,0]
; __device__ __forceinline__ cf twc(cf ws, int k16) { if (k16 == 0) return ws; if (k16 == 4) return cf{ws.y, -ws.x}; return cmul(ws, cf{c16(k16), -s16(k16)}); }
; template <int LR> __device__ __forceinline__ void dit_reg(cf (&x)[1 << LR], cf w) {
;     constexpr int R = 1 << LR; cf wsv[LR]; wsv[0] = w;
; #pragma unroll
;     for (int s = 1; s < LR; ++s) wsv[s] = cmul(wsv[s - 1], wsv[s - 1]);
; #pragma unroll
;     for (int s = LR - 1; s >= 0; --s) { const int half = R >> (s + 1);
; #pragma unroll
;         for (int m0 = 0; m0 < R; m0 += 2 * half)
; #pragma unroll
;             for (int mm = 0; mm < half; ++mm) { const int ia = m0 + mm, ib = ia + half; const cf a = x[ia];
;                 const cf b = cmulc(x[ib], twc(wsv[s], (mm << s) * (16 / R)));
;                 x[ia] = cf{a.x + b.x, a.y + b.y}; x[ib] = cf{a.x - b.x, a.y - b.y}; } }
; }
; __device__ __forceinline__ void fft_conv(ldsf2 buf, const LAS unsigned* spec) {
;     ...
;       for (int m = 0; m < 16; ++m) { const h2_t hv = __builtin_bit_cast(h2_t, spec[tid * 17 + m]); x[m] = cmul(x[m], cf{(float)hv.x, (float)hv.y}); }
;       dit_reg<4>(x, cf{1.0f, 0.0f});
	v_cvt_f32_f16_e32 v152, v130
	v_cvt_f32_f16_e32 v128, v131
	v_cvt_f32_f16_e32 v116, v168
	v_cvt_f32_f16_e32 v108, v169
	v_cvt_f32_f16_sdwa v153, v130 dst_sel:DWORD dst_unused:UNUSED_PAD src0_sel:WORD_1
	v_cvt_f32_f16_sdwa v129, v131 dst_sel:DWORD dst_unused:UNUSED_PAD src0_sel:WORD_1
	v_cvt_f32_f16_sdwa v117, v168 dst_sel:DWORD dst_unused:UNUSED_PAD src0_sel:WORD_1
	v_cvt_f32_f16_sdwa v109, v169 dst_sel:DWORD dst_unused:UNUSED_PAD src0_sel:WORD_1
	v_pk_mul_f32 v[114:115], v[90:91], v[152:153] op_sel:[1,1] op_sel_hi:[1,0]
	v_pk_mul_f32 v[88:89], v[118:119], v[128:129] op_sel:[1,1] op_sel_hi:[1,0]
	v_pk_mul_f32 v[98:99], v[100:101], v[116:117] op_sel:[1,1] op_sel_hi:[1,0]
	v_pk_mul_f32 v[82:83], v[72:73], v[108:109] op_sel:[1,1] op_sel_hi:[1,0]
	v_pk_fma_f32 v[152:153], v[90:91], v[152:153], v[114:115] op_sel:[0,0,0] op_sel_hi:[0,1,1] neg_lo:[0,0,1] neg_hi:[0,0,0]
	v_pk_fma_f32 v[128:129], v[118:119], v[128:129], v[88:89] op_sel:[0,0,0] op_sel_hi:[0,1,1] neg_lo:[0,0,1] neg_hi:[0,0,0]
	v_pk_fma_f32 v[116:117], v[100:101], v[116:117], v[98:99] op_sel:[0,0,0] op_sel_hi:[0,1,1] neg_lo:[0,0,1] neg_hi:[0,0,0]
	v_pk_fma_f32 v[108:109], v[72:73], v[108:109], v[82:83] op_sel:[0,0,0] op_sel_hi:[0,1,1] neg_lo:[0,0,1] neg_hi:[0,0,0]
	v_pk_add_f32 v[148:149], v[126:127], v[122:123]
	v_pk_add_f32 v[80:81], v[84:85], v[150:151]
	v_pk_add_f32 v[120:121], v[102:103], v[166:167]
	v_pk_add_f32 v[110:111], v[74:75], v[78:79]
	v_pk_add_f32 v[126:127], v[126:127], v[122:123] neg_lo:[0,1] neg_hi:[0,1]
	v_pk_add_f32 v[84:85], v[84:85], v[150:151] neg_lo:[0,1] neg_hi:[0,1]
	v_pk_add_f32 v[102:103], v[102:103], v[166:167] neg_lo:[0,1] neg_hi:[0,1]
	v_pk_add_f32 v[74:75], v[74:75], v[78:79] neg_lo:[0,1] neg_hi:[0,1]
	v_pk_add_f32 v[94:95], v[92:93], v[104:105]
	v_pk_add_f32 v[76:77], v[124:125], v[112:113]
	v_pk_add_f32 v[154:155], v[152:153], v[128:129]
	v_pk_add_f32 v[86:87], v[116:117], v[108:109]
	v_pk_add_f32 v[92:93], v[92:93], v[104:105] neg_lo:[0,1] neg_hi:[0,1]
	v_pk_add_f32 v[124:125], v[124:125], v[112:113] neg_lo:[0,1] neg_hi:[0,1]
	v_pk_add_f32 v[152:153], v[152:153], v[128:129] neg_lo:[0,1] neg_hi:[0,1]
	v_pk_add_f32 v[116:117], v[116:117], v[108:109] neg_lo:[0,1] neg_hi:[0,1]
	v_pk_add_f32 v[96:97], v[148:149], v[80:81]
	v_pk_add_f32 v[132:133], v[126:127], v[84:85] op_sel:[0,1] op_sel_hi:[1,0] neg_lo:[0,1] neg_hi:[0,0]
	v_pk_add_f32 v[114:115], v[120:121], v[110:111]
	v_pk_add_f32 v[90:91], v[102:103], v[74:75] op_sel:[0,1] op_sel_hi:[1,0] neg_lo:[0,1] neg_hi:[0,0]
	v_pk_add_f32 v[148:149], v[148:149], v[80:81] neg_lo:[0,1] neg_hi:[0,1]
	v_pk_add_f32 v[126:127], v[126:127], v[84:85] op_sel:[0,1] op_sel_hi:[1,0] neg_lo:[0,0] neg_hi:[0,1]
	v_pk_add_f32 v[120:121], v[120:121], v[110:111] neg_lo:[0,1] neg_hi:[0,1]
	v_pk_add_f32 v[102:103], v[102:103], v[74:75] op_sel:[0,1] op_sel_hi:[1,0] neg_lo:[0,0] neg_hi:[0,1]
	v_pk_add_f32 v[88:89], v[94:95], v[76:77]
	v_pk_add_f32 v[118:119], v[92:93], v[124:125] op_sel:[0,1] op_sel_hi:[1,0] neg_lo:[0,1] neg_hi:[0,0]
	v_pk_add_f32 v[98:99], v[154:155], v[86:87]
	v_pk_add_f32 v[100:101], v[152:153], v[116:117] op_sel:[0,1] op_sel_hi:[1,0] neg_lo:[0,1] neg_hi:[0,0]
	v_pk_add_f32 v[94:95], v[94:95], v[76:77] neg_lo:[0,1] neg_hi:[0,1]
	v_pk_add_f32 v[92:93], v[92:93], v[124:125] op_sel:[0,1] op_sel_hi:[1,0] neg_lo:[0,0] neg_hi:[0,1]
	v_pk_add_f32 v[154:155], v[154:155], v[86:87] neg_lo:[0,1] neg_hi:[0,1]
	v_pk_add_f32 v[152:153], v[152:153], v[116:117] op_sel:[0,1] op_sel_hi:[1,0] neg_lo:[0,0] neg_hi:[0,1]
	v_pk_add_f32 v[82:83], v[96:97], v[114:115]
	v_pk_mul_f32 v[72:73], v[90:91], s[16:17] op_sel:[1,0] op_sel_hi:[1,0] neg_lo:[0,1] neg_hi:[0,0]
	v_pk_add_f32 v[122:123], v[148:149], v[120:121] op_sel:[0,1] op_sel_hi:[1,0] neg_lo:[0,1] neg_hi:[0,0]
	v_pk_mul_f32 v[150:151], v[102:103], s[16:17] op_sel:[1,0] op_sel_hi:[1,0] neg_lo:[0,1] neg_hi:[0,1]
	v_pk_add_f32 v[96:97], v[96:97], v[114:115] neg_lo:[0,1] neg_hi:[0,1]
	v_pk_fma_f32 v[72:73], v[90:91], s[16:17], v[72:73] op_sel:[0,0,0] op_sel_hi:[0,0,1] neg_lo:[0,0,0] neg_hi:[0,0,0]
	v_pk_add_f32 v[148:149], v[148:149], v[120:121] op_sel:[0,1] op_sel_hi:[1,0] neg_lo:[0,0] neg_hi:[0,1]
	v_pk_fma_f32 v[150:151], v[102:103], s[16:17], v[150:151] op_sel:[0,0,0] op_sel_hi:[0,0,1] neg_lo:[0,1,0] neg_hi:[0,0,0]
	v_pk_add_f32 v[90:91], v[132:133], v[72:73] neg_lo:[0,1] neg_hi:[0,1]
; __device__ __forceinline__ cf twc(cf ws, int k16) { if (k16 == 0) return ws; if (k16 == 4) return cf{ws.y, -ws.x}; return cmul(ws, cf{c16(k16), -s16(k16)}); }
; __device__ __forceinline__ void wave_lds_fence() { asm volatile("s_waitcnt lgkmcnt(0)" ::: "memory"); }
; template <int LR> __device__ __forceinline__ void dit_reg(cf (&x)[1 << LR], cf w) {
;     constexpr int R = 1 << LR; cf wsv[LR]; wsv[0] = w;
; #pragma unroll
;     for (int s = 1; s < LR; ++s) wsv[s] = cmul(wsv[s - 1], wsv[s - 1]);
; #pragma unroll
;     for (int s = LR - 1; s >= 0; --s) { const int half = R >> (s + 1);
; #pragma unroll
;         for (int m0 = 0; m0 < R; m0 += 2 * half)
; #pragma unroll
;             for (int mm = 0; mm < half; ++mm) { const int ia = m0 + mm, ib = ia + half; const cf a = x[ia];
;                 const cf b = cmulc(x[ib], twc(wsv[s], (mm << s) * (16 / R)));
;                 x[ia] = cf{a.x + b.x, a.y + b.y}; x[ib] = cf{a.x - b.x, a.y - b.y}; } }
; }
; __device__ __forceinline__ void fft_conv(ldsf2 buf, const LAS unsigned* spec) {
;     ...
;       dit_reg<4>(x, cf{1.0f, 0.0f});
; #pragma unroll
;       for (int m = 0; m < 16; ++m) buf[tid * 17 + m] = mkv2(x[m].x, x[m].y); }
;     wave_lds_fence();
;     fft_inv_cba(buf);
	v_pk_add_f32 v[102:103], v[126:127], v[150:151] neg_lo:[0,1] neg_hi:[0,1]
	v_pk_add_f32 v[132:133], v[132:133], v[72:73]
	v_pk_add_f32 v[126:127], v[126:127], v[150:151]
	v_pk_add_f32 v[166:167], v[88:89], v[98:99]
	v_pk_mul_f32 v[78:79], v[100:101], s[16:17] op_sel:[1,0] op_sel_hi:[1,0] neg_lo:[0,1] neg_hi:[0,0]
	v_pk_add_f32 v[104:105], v[94:95], v[154:155] op_sel:[0,1] op_sel_hi:[1,0] neg_lo:[0,1] neg_hi:[0,0]
	v_pk_mul_f32 v[112:113], v[152:153], s[16:17] op_sel:[1,0] op_sel_hi:[1,0] neg_lo:[0,1] neg_hi:[0,1]
	v_pk_add_f32 v[88:89], v[88:89], v[98:99] neg_lo:[0,1] neg_hi:[0,1]
	v_pk_fma_f32 v[78:79], v[100:101], s[16:17], v[78:79] op_sel:[0,0,0] op_sel_hi:[0,0,1] neg_lo:[0,0,0] neg_hi:[0,0,0]
	v_pk_add_f32 v[94:95], v[94:95], v[154:155] op_sel:[0,1] op_sel_hi:[1,0] neg_lo:[0,0] neg_hi:[0,1]
	v_pk_fma_f32 v[112:113], v[152:153], s[16:17], v[112:113] op_sel:[0,0,0] op_sel_hi:[0,0,1] neg_lo:[0,1,0] neg_hi:[0,0,0]
	v_pk_add_f32 v[100:101], v[118:119], v[78:79] neg_lo:[0,1] neg_hi:[0,1]
	v_pk_add_f32 v[152:153], v[92:93], v[112:113] neg_lo:[0,1] neg_hi:[0,1]
	v_pk_add_f32 v[118:119], v[118:119], v[78:79]
	v_pk_add_f32 v[92:93], v[92:93], v[112:113]
	v_pk_add_f32 v[128:129], v[82:83], v[166:167]
	v_pk_mul_f32 v[108:109], v[118:119], s[4:5] op_sel:[1,1] op_sel_hi:[1,0] neg_lo:[0,1] neg_hi:[0,0]
	v_pk_mul_f32 v[80:81], v[104:105], s[16:17] op_sel:[1,0] op_sel_hi:[1,0] neg_lo:[0,1] neg_hi:[0,0]
	v_pk_mul_f32 v[84:85], v[92:93], s[4:5] op_sel:[1,0] op_sel_hi:[1,1] neg_lo:[0,1] neg_hi:[0,0]
	v_pk_add_f32 v[82:83], v[82:83], v[166:167] neg_lo:[0,1] neg_hi:[0,1]
	v_pk_fma_f32 v[108:109], v[118:119], s[4:5], v[108:109] op_sel:[0,0,0] op_sel_hi:[0,1,1] neg_lo:[0,0,0] neg_hi:[0,0,0]
	v_pk_fma_f32 v[80:81], v[104:105], s[16:17], v[80:81] op_sel:[0,0,0] op_sel_hi:[0,0,1] neg_lo:[0,0,0] neg_hi:[0,0,0]
	v_pk_fma_f32 v[84:85], v[92:93], s[4:5], v[84:85] op_sel:[0,1,0] op_sel_hi:[0,0,1] neg_lo:[0,0,0] neg_hi:[0,0,0]
	v_pk_add_f32 v[118:119], v[132:133], v[108:109] neg_lo:[0,1] neg_hi:[0,1]
	v_pk_add_f32 v[104:105], v[122:123], v[80:81] neg_lo:[0,1] neg_hi:[0,1]
	v_pk_add_f32 v[92:93], v[126:127], v[84:85] neg_lo:[0,1] neg_hi:[0,1]
	v_pk_add_f32 v[132:133], v[132:133], v[108:109]
	v_pk_add_f32 v[122:123], v[122:123], v[80:81]
	v_pk_add_f32 v[126:127], v[126:127], v[84:85]
	v_pk_add_f32 v[110:111], v[96:97], v[88:89] op_sel:[0,1] op_sel_hi:[1,0] neg_lo:[0,1] neg_hi:[0,0]
	v_pk_mul_f32 v[74:75], v[100:101], s[4:5] op_sel:[1,0] op_sel_hi:[1,1] neg_lo:[0,1] neg_hi:[0,1]
	v_pk_mul_f32 v[76:77], v[94:95], s[16:17] op_sel:[1,0] op_sel_hi:[1,0] neg_lo:[0,1] neg_hi:[0,1]
	v_pk_mul_f32 v[124:125], v[152:153], s[4:5] op_sel:[1,1] op_sel_hi:[1,0] neg_lo:[0,1] neg_hi:[0,1]
	v_pk_add_f32 v[96:97], v[96:97], v[88:89] op_sel:[0,1] op_sel_hi:[1,0] neg_lo:[0,0] neg_hi:[0,1]
	v_pk_fma_f32 v[74:75], v[100:101], s[4:5], v[74:75] op_sel:[0,1,0] op_sel_hi:[0,0,1] neg_lo:[0,1,0] neg_hi:[0,0,0]
	v_pk_fma_f32 v[76:77], v[94:95], s[16:17], v[76:77] op_sel:[0,0,0] op_sel_hi:[0,0,1] neg_lo:[0,1,0] neg_hi:[0,0,0]
	v_pk_fma_f32 v[124:125], v[152:153], s[4:5], v[124:125] op_sel:[0,0,0] op_sel_hi:[0,1,1] neg_lo:[0,1,0] neg_hi:[0,0,0]
	v_pk_add_f32 v[100:101], v[90:91], v[74:75] neg_lo:[0,1] neg_hi:[0,1]
	v_pk_add_f32 v[94:95], v[148:149], v[76:77] neg_lo:[0,1] neg_hi:[0,1]
	v_pk_add_f32 v[152:153], v[102:103], v[124:125] neg_lo:[0,1] neg_hi:[0,1]
	v_pk_add_f32 v[90:91], v[90:91], v[74:75]
	v_pk_add_f32 v[148:149], v[148:149], v[76:77]
	v_pk_add_f32 v[102:103], v[102:103], v[124:125]
	ds_write2_b64 v147, v[128:129], v[132:133] offset1:1
	ds_write2_b64 v147, v[122:123], v[126:127] offset0:2 offset1:3
	ds_write2_b64 v147, v[110:111], v[90:91] offset0:4 offset1:5
	ds_write2_b64 v147, v[148:149], v[102:103] offset0:6 offset1:7
	ds_write2_b64 v147, v[82:83], v[118:119] offset0:8 offset1:9
	ds_write2_b64 v147, v[104:105], v[92:93] offset0:10 offset1:11
	ds_write2_b64 v147, v[96:97], v[100:101] offset0:12 offset1:13
	ds_write2_b64 v147, v[94:95], v[152:153] offset0:14 offset1:15
	v_mov_b32_e32 v68, v195
	s_waitcnt lgkmcnt(0)
	s_mov_b32 s0, 0
	v_and_b32_e32 v73, 15, v68
	v_lshlrev_b32_e32 v72, 4, v68
	v_lshlrev_b32_e32 v75, 9, v73
	v_and_b32_e32 v72, 0xfffffc00, v72
	v_lshlrev_b32_e32 v74, 3, v68
	v_add_u32_e32 v75, 0, v75
	v_and_b32_e32 v69, 63, v68
	v_lshl_add_u32 v73, v73, 3, 0
	v_and_or_b32 v74, v74, s90, v72
	v_add_u32_e32 v75, 0x22000, v75

; #define LAS __attribute__((address_space(3)))
; __device__ __forceinline__ cf twc(cf ws, int k16) { if (k16 == 0) return ws; if (k16 == 4) return cf{ws.y, -ws.x}; return cmul(ws, cf{c16(k16), -s16(k16)}); }
; template <int LR> __device__ __forceinline__ void dif_reg(cf (&x)[1 << LR], cf w) {
;     constexpr int R = 1 << LR; cf ws = w;
; #pragma unroll
;     for (int s = 0; s < LR; ++s) { const int half = R >> (s + 1);
; #pragma unroll
;         for (int m0 = 0; m0 < R; m0 += 2 * half)
; #pragma unroll
;             for (int mm = 0; mm < half; ++mm) { const int ia = m0 + mm, ib = ia + half; const cf a = x[ia], b = x[ib];
;                 x[ia] = cf{a.x + b.x, a.y + b.y}; const cf d{a.x - b.x, a.y - b.y};
;                 x[ib] = cmul(d, twc(ws, (mm << s) * (16 / R))); }
;         ws = cmul(ws, ws); }
; }
; template <int LR, bool INV> __device__ __forceinline__ void fft_pass(ldsf2 buf, int base, int stride, int twi) {
;     constexpr int R = 1 << LR; cf x[R];
;     const v2f wv = ((ldsf2)((LAS unsigned char*)buf + 139264))[twi];
; #pragma unroll
;     for (int m = 0; m < R; ++m) { const v2f v = buf[base + m * stride]; x[m] = cf{v.x, v.y}; }
;     const cf w{wv.x, wv.y};
;     if (INV) dit_reg<LR>(x, w); else dif_reg<LR>(x, w);
; #pragma unroll
;     for (int m = 0; m < R; ++m) buf[base + m * stride] = mkv2(x[m].x, x[m].y);
; }
.LBB0_363:
	v_or_b32_e32 v81, s0, v79
	ds_read_b64 v[98:99], v80
	v_lshlrev_b32_e32 v82, 3, v81
	v_ashrrev_i32_e32 v81, 1, v81
	v_add3_u32 v81, v78, v82, v81
	ds_read2_b64 v[82:85], v81 offset1:17
	ds_read2_b64 v[86:89], v81 offset0:34 offset1:51
	ds_read2_b64 v[90:93], v81 offset0:68 offset1:85
	ds_read2_b64 v[94:97], v81 offset0:102 offset1:119
	s_waitcnt lgkmcnt(4)
	v_pk_add_f32 v[100:101], v[98:99], v[98:99] op_sel:[0,1] op_sel_hi:[1,0] neg_lo:[0,0] neg_hi:[0,1]
	v_pk_mul_f32 v[102:103], v[100:101], s[16:17] op_sel:[0,0] op_sel_hi:[1,0]
	v_pk_mul_f32 v[104:105], v[100:101], s[16:17] op_sel:[1,0] op_sel_hi:[0,0] neg_lo:[0,0] neg_hi:[1,0]
	v_pk_mul_f32 v[106:107], v[98:99], v[98:99] op_sel:[1,1] op_sel_hi:[1,0]
	v_pk_fma_f32 v[106:107], v[98:99], v[98:99], v[106:107] op_sel:[0,0,0] op_sel_hi:[0,1,1] neg_lo:[0,0,1] neg_hi:[0,0,0]
	v_pk_mul_f32 v[108:109], v[106:107], v[106:107] op_sel:[1,1] op_sel_hi:[1,0]
	v_pk_fma_f32 v[108:109], v[106:107], v[106:107], v[108:109] op_sel:[0,0,0] op_sel_hi:[0,1,1] neg_lo:[0,0,1] neg_hi:[0,0,0]
	s_waitcnt lgkmcnt(0)
	v_pk_add_f32 v[110:111], v[82:83], v[90:91] neg_lo:[0,1] neg_hi:[0,1]
	v_pk_add_f32 v[112:113], v[84:85], v[92:93] neg_lo:[0,1] neg_hi:[0,1]
	v_pk_add_f32 v[114:115], v[86:87], v[94:95] neg_lo:[0,1] neg_hi:[0,1]
	v_pk_add_f32 v[116:117], v[88:89], v[96:97] neg_lo:[0,1] neg_hi:[0,1]
	v_pk_add_f32 v[82:83], v[82:83], v[90:91]
	v_pk_add_f32 v[84:85], v[84:85], v[92:93]
	v_pk_add_f32 v[86:87], v[86:87], v[94:95]
	v_pk_add_f32 v[88:89], v[88:89], v[96:97]
	v_pk_mul_f32 v[90:91], v[110:111], v[98:99] op_sel:[1,1] op_sel_hi:[1,0]
	v_pk_mul_f32 v[92:93], v[112:113], v[102:103] op_sel:[1,1] op_sel_hi:[1,0]
	v_pk_mul_f32 v[94:95], v[114:115], v[98:99] op_sel:[1,0] op_sel_hi:[1,1]
	v_pk_mul_f32 v[96:97], v[116:117], v[104:105] op_sel:[1,1] op_sel_hi:[1,0]
	v_pk_fma_f32 v[90:91], v[110:111], v[98:99], v[90:91] op_sel:[0,0,0] op_sel_hi:[0,1,1] neg_lo:[0,0,1] neg_hi:[0,0,0]
	v_pk_fma_f32 v[92:93], v[112:113], v[102:103], v[92:93] op_sel:[0,0,0] op_sel_hi:[0,1,1] neg_lo:[0,0,1] neg_hi:[0,0,0]
	v_pk_fma_f32 v[94:95], v[114:115], v[98:99], v[94:95] op_sel:[0,1,0] op_sel_hi:[0,0,1] neg_lo:[0,0,0] neg_hi:[0,1,0]
	v_pk_fma_f32 v[96:97], v[116:117], v[104:105], v[96:97] op_sel:[0,0,0] op_sel_hi:[0,1,1] neg_lo:[0,0,1] neg_hi:[0,0,0]
	v_pk_add_f32 v[110:111], v[82:83], v[86:87] neg_lo:[0,1] neg_hi:[0,1]
	v_pk_add_f32 v[112:113], v[84:85], v[88:89] neg_lo:[0,1] neg_hi:[0,1]
	v_pk_add_f32 v[114:115], v[90:91], v[94:95] neg_lo:[0,1] neg_hi:[0,1]
	v_pk_add_f32 v[116:117], v[92:93], v[96:97] neg_lo:[0,1] neg_hi:[0,1]
	v_pk_add_f32 v[82:83], v[82:83], v[86:87]
	v_pk_add_f32 v[84:85], v[84:85], v[88:89]
	v_pk_add_f32 v[90:91], v[90:91], v[94:95]
	v_pk_add_f32 v[92:93], v[92:93], v[96:97]
	v_pk_mul_f32 v[86:87], v[110:111], v[106:107] op_sel:[1,1] op_sel_hi:[1,0]
	v_pk_mul_f32 v[88:89], v[112:113], v[106:107] op_sel:[1,0] op_sel_hi:[1,1]
	v_pk_mul_f32 v[94:95], v[114:115], v[106:107] op_sel:[1,1] op_sel_hi:[1,0]
	v_pk_mul_f32 v[96:97], v[116:117], v[106:107] op_sel:[1,0] op_sel_hi:[1,1]
	v_pk_fma_f32 v[86:87], v[110:111], v[106:107], v[86:87] op_sel:[0,0,0] op_sel_hi:[0,1,1] neg_lo:[0,0,1] neg_hi:[0,0,0]
	v_pk_fma_f32 v[88:89], v[112:113], v[106:107], v[88:89] op_sel:[0,1,0] op_sel_hi:[0,0,1] neg_lo:[0,0,0] neg_hi:[0,1,0]
	v_pk_fma_f32 v[94:95], v[114:115], v[106:107], v[94:95] op_sel:[0,0,0] op_sel_hi:[0,1,1] neg_lo:[0,0,1] neg_hi:[0,0,0]
	v_pk_fma_f32 v[96:97], v[116:117], v[106:107], v[96:97] op_sel:[0,1,0] op_sel_hi:[0,0,1] neg_lo:[0,0,0] neg_hi:[0,1,0]
	v_pk_add_f32 v[110:111], v[82:83], v[84:85] neg_lo:[0,1] neg_hi:[0,1]
	v_pk_add_f32 v[112:113], v[86:87], v[88:89] neg_lo:[0,1] neg_hi:[0,1]
	v_pk_add_f32 v[114:115], v[90:91], v[92:93] neg_lo:[0,1] neg_hi:[0,1]
	v_pk_add_f32 v[116:117], v[94:95], v[96:97] neg_lo:[0,1] neg_hi:[0,1]
	v_pk_add_f32 v[82:83], v[82:83], v[84:85]
	v_pk_add_f32 v[86:87], v[86:87], v[88:89]
	v_pk_add_f32 v[90:91], v[90:91], v[92:93]
	v_pk_add_f32 v[94:95], v[94:95], v[96:97]
	v_pk_mul_f32 v[84:85], v[110:111], v[108:109] op_sel:[1,1] op_sel_hi:[1,0]
	v_pk_mul_f32 v[88:89], v[112:113], v[108:109] op_sel:[1,1] op_sel_hi:[1,0]
	v_pk_mul_f32 v[92:93], v[114:115], v[108:109] op_sel:[1,1] op_sel_hi:[1,0]
	v_pk_mul_f32 v[96:97], v[116:117], v[108:109] op_sel:[1,1] op_sel_hi:[1,0]
	v_pk_fma_f32 v[84:85], v[110:111], v[108:109], v[84:85] op_sel:[0,0,0] op_sel_hi:[0,1,1] neg_lo:[0,0,1] neg_hi:[0,0,0]
	v_pk_fma_f32 v[88:89], v[112:113], v[108:109], v[88:89] op_sel:[0,0,0] op_sel_hi:[0,1,1] neg_lo:[0,0,1] neg_hi:[0,0,0]
	v_pk_fma_f32 v[92:93], v[114:115], v[108:109], v[92:93] op_sel:[0,0,0] op_sel_hi:[0,1,1] neg_lo:[0,0,1] neg_hi:[0,0,0]
	v_pk_fma_f32 v[96:97], v[116:117], v[108:109], v[96:97] op_sel:[0,0,0] op_sel_hi:[0,1,1] neg_lo:[0,0,1] neg_hi:[0,0,0]
	ds_write2_b64 v81, v[82:83], v[84:85] offset1:17
	ds_write2_b64 v81, v[86:87], v[88:89] offset0:34 offset1:51
	ds_write2_b64 v81, v[90:91], v[92:93] offset0:68 offset1:85
	ds_write2_b64 v81, v[94:95], v[96:97] offset0:102 offset1:119
	s_movk_i32 s0, 0x200
	s_and_b64 vcc, exec, s[10:11]
	s_mov_b64 s[10:11], 0
	s_cbranch_vccnz .LBB0_363
; __device__ __forceinline__ int otid() { int t = threadIdx.x; asm volatile("" : "+v"(t)); return t; }
; __device__ __forceinline__ cf twc(cf ws, int k16) { if (k16 == 0) return ws; if (k16 == 4) return cf{ws.y, -ws.x}; return cmul(ws, cf{c16(k16), -s16(k16)}); }
; template <int LR> __device__ __forceinline__ void dif_reg(cf (&x)[1 << LR], cf w) {
;     constexpr int R = 1 << LR; cf ws = w;
; #pragma unroll
;     for (int s = 0; s < LR; ++s) { const int half = R >> (s + 1);
; #pragma unroll
;         for (int m0 = 0; m0 < R; m0 += 2 * half)
; #pragma unroll
;             for (int mm = 0; mm < half; ++mm) { const int ia = m0 + mm, ib = ia + half; const cf a = x[ia], b = x[ib];
;                 x[ia] = cf{a.x + b.x, a.y + b.y}; const cf d{a.x - b.x, a.y - b.y};
;                 x[ib] = cmul(d, twc(ws, (mm << s) * (16 / R))); }
;         ws = cmul(ws, ws); }
; }
; __device__ __forceinline__ void fft_conv(ldsf2 buf, const LAS unsigned* spec) {
;     ...
;     { const int tid = otid(); cf x[16];
; #pragma unroll
;       for (int m = 0; m < 16; ++m) { const v2f v = buf[tid * 17 + m]; x[m] = cf{v.x, v.y}; }
;       dif_reg<4>(x, cf{1.0f, 0.0f});
; #pragma unroll
;       for (int m = 0; m < 16; ++m) { const h2_t hv = __builtin_bit_cast(h2_t, spec[tid * 17 + m]); x[m] = cmul(x[m], cf{(float)hv.x, (float)hv.y}); }
;       dit_reg<4>(x, cf{1.0f, 0.0f});
	v_mov_b32_e32 v162, v195
	s_movk_i32 s0, 0x88
	s_waitcnt lgkmcnt(0)
	s_mov_b32 s86, s63
	v_mul_lo_u32 v78, v162, s0
	v_add_u32_e32 v151, 0, v78
	ds_read2_b64 v[80:83], v151 offset1:1
	ds_read2_b64 v[84:87], v151 offset0:2 offset1:3
	ds_read2_b64 v[98:101], v151 offset0:4 offset1:5
	ds_read2_b64 v[102:105], v151 offset0:6 offset1:7
	ds_read2_b64 v[106:109], v151 offset0:8 offset1:9
	ds_read2_b64 v[110:113], v151 offset0:10 offset1:11
	ds_read2_b64 v[126:129], v151 offset0:12 offset1:13
	ds_read2_b64 v[134:137], v151 offset0:14 offset1:15
	s_mov_b32 s10, s63
	s_mov_b32 s11, s16
	s_mov_b32 s17, s5
	s_mov_b32 s0, s16
	s_mov_b32 s1, s4
	s_mov_b32 s0, s63
	s_mov_b32 s1, s5
	s_mov_b32 s0, s87
	s_mov_b32 s1, s4
	s_mov_b32 s1, s5
	s_mov_b32 s35, s4
	s_mov_b32 s12, s63
	s_movk_i32 s0, 0x44
	v_mul_lo_u32 v114, v162, s0
	v_add_u32_e32 v114, 0, v114
	v_add_u32_e32 v114, 0x19800, v114
	ds_read2_b32 v[160:161], v114 offset1:1
	ds_read2_b32 v[162:163], v114 offset0:2 offset1:3
	ds_read2_b32 v[164:165], v114 offset0:4 offset1:5
	ds_read2_b32 v[166:167], v114 offset0:6 offset1:7
	ds_read2_b32 v[168:169], v114 offset0:8 offset1:9
	ds_read2_b32 v[142:143], v114 offset0:10 offset1:11
	ds_read2_b32 v[138:139], v114 offset0:12 offset1:13
	ds_read2_b32 v[172:173], v114 offset0:14 offset1:15
	s_mov_b32 s0, s5
	s_mov_b64 s[14:15], -1
	s_mov_b32 s35, s13
	s_mov_b32 s0, s13
	s_waitcnt lgkmcnt(8)
	v_pk_add_f32 v[88:89], v[80:81], v[106:107]
	v_pk_add_f32 v[90:91], v[82:83], v[108:109]
	v_pk_add_f32 v[92:93], v[84:85], v[110:111]
	v_pk_add_f32 v[94:95], v[86:87], v[112:113]
	v_pk_add_f32 v[80:81], v[80:81], v[106:107] neg_lo:[0,1] neg_hi:[0,1]
	v_pk_add_f32 v[82:83], v[82:83], v[108:109] neg_lo:[0,1] neg_hi:[0,1]
	v_pk_add_f32 v[84:85], v[84:85], v[110:111] neg_lo:[0,1] neg_hi:[0,1]
	v_pk_add_f32 v[86:87], v[86:87], v[112:113] neg_lo:[0,1] neg_hi:[0,1]
	v_pk_mul_f32 v[108:109], v[82:83], s[4:5] op_sel:[1,1] op_sel_hi:[1,0] neg_lo:[0,1] neg_hi:[0,0]
	v_pk_mul_f32 v[110:111], v[84:85], s[16:17] op_sel:[1,0] op_sel_hi:[1,0] neg_lo:[0,1] neg_hi:[0,0]
	v_pk_mul_f32 v[112:113], v[86:87], s[4:5] op_sel:[1,0] op_sel_hi:[1,1] neg_lo:[0,1] neg_hi:[0,0]
	v_pk_fma_f32 v[108:109], v[82:83], s[4:5], v[108:109] op_sel:[0,0,0] op_sel_hi:[0,1,1] neg_lo:[0,0,1] neg_hi:[0,1,0]
	v_pk_fma_f32 v[110:111], v[84:85], s[16:17], v[110:111] op_sel:[0,0,0] op_sel_hi:[0,0,1] neg_lo:[0,0,1] neg_hi:[0,1,0]
	v_pk_fma_f32 v[112:113], v[86:87], s[4:5], v[112:113] op_sel:[0,1,0] op_sel_hi:[0,0,1] neg_lo:[0,0,1] neg_hi:[0,1,0]
	v_pk_add_f32 v[96:97], v[98:99], v[126:127]
	v_pk_add_f32 v[116:117], v[100:101], v[128:129]
	v_pk_add_f32 v[118:119], v[102:103], v[134:135]
	v_pk_add_f32 v[120:121], v[104:105], v[136:137]
	v_pk_add_f32 v[98:99], v[98:99], v[126:127] op_sel:[1,1] op_sel_hi:[0,0] neg_lo:[0,1] neg_hi:[1,0]
	v_pk_add_f32 v[100:101], v[100:101], v[128:129] neg_lo:[0,1] neg_hi:[0,1]
	v_pk_add_f32 v[102:103], v[102:103], v[134:135] neg_lo:[0,1] neg_hi:[0,1]
	v_pk_add_f32 v[104:105], v[104:105], v[136:137] neg_lo:[0,1] neg_hi:[0,1]
	v_pk_mul_f32 v[128:129], v[100:101], s[4:5] op_sel:[1,0] op_sel_hi:[1,1] neg_lo:[0,1] neg_hi:[0,1]
	v_pk_mul_f32 v[134:135], v[102:103], s[16:17] op_sel:[1,0] op_sel_hi:[1,0] neg_lo:[0,1] neg_hi:[0,1]
	v_pk_mul_f32 v[136:137], v[104:105], s[4:5] op_sel:[1,1] op_sel_hi:[1,0] neg_lo:[0,1] neg_hi:[0,1]
	v_pk_fma_f32 v[128:129], v[100:101], s[4:5], v[128:129] op_sel:[0,1,0] op_sel_hi:[0,0,1] neg_lo:[0,1,1] neg_hi:[0,1,0]
	v_pk_fma_f32 v[134:135], v[102:103], s[16:17], v[134:135] op_sel:[0,0,0] op_sel_hi:[0,0,1] neg_lo:[0,1,1] neg_hi:[0,1,0]
	v_pk_fma_f32 v[136:137], v[104:105], s[4:5], v[136:137] op_sel:[0,0,0] op_sel_hi:[0,1,1] neg_lo:[0,1,1] neg_hi:[0,1,0]
	v_pk_add_f32 v[122:123], v[88:89], v[96:97]
	v_pk_add_f32 v[124:125], v[90:91], v[116:117]
	v_pk_add_f32 v[130:131], v[92:93], v[118:119]
	v_pk_add_f32 v[132:133], v[94:95], v[120:121]
	v_pk_add_f32 v[88:89], v[88:89], v[96:97] neg_lo:[0,1] neg_hi:[0,1]
	v_pk_add_f32 v[90:91], v[90:91], v[116:117] neg_lo:[0,1] neg_hi:[0,1]
	v_pk_add_f32 v[92:93], v[92:93], v[118:119] op_sel:[1,1] op_sel_hi:[0,0] neg_lo:[0,1] neg_hi:[1,0]
	v_pk_add_f32 v[94:95], v[94:95], v[120:121] neg_lo:[0,1] neg_hi:[0,1]
	v_pk_mul_f32 v[116:117], v[90:91], s[16:17] op_sel:[1,0] op_sel_hi:[1,0] neg_lo:[0,1] neg_hi:[0,0]
	v_pk_mul_f32 v[120:121], v[94:95], s[16:17] op_sel:[1,0] op_sel_hi:[1,0] neg_lo:[0,1] neg_hi:[0,1]
	v_pk_fma_f32 v[116:117], v[90:91], s[16:17], v[116:117] op_sel:[0,0,0] op_sel_hi:[0,0,1] neg_lo:[0,0,1] neg_hi:[0,1,0]
	v_pk_fma_f32 v[120:121], v[94:95], s[16:17], v[120:121] op_sel:[0,0,0] op_sel_hi:[0,0,1] neg_lo:[0,1,1] neg_hi:[0,1,0]
	v_pk_add_f32 v[140:141], v[80:81], v[98:99]
	v_pk_add_f32 v[152:153], v[108:109], v[128:129]
	v_pk_add_f32 v[154:155], v[110:111], v[134:135]
	v_pk_add_f32 v[156:157], v[112:113], v[136:137]
	v_pk_add_f32 v[80:81], v[80:81], v[98:99] neg_lo:[0,1] neg_hi:[0,1]
	v_pk_add_f32 v[108:109], v[108:109], v[128:129] neg_lo:[0,1] neg_hi:[0,1]
	v_pk_add_f32 v[110:111], v[110:111], v[134:135] op_sel:[1,1] op_sel_hi:[0,0] neg_lo:[0,1] neg_hi:[1,0]
	v_pk_add_f32 v[112:113], v[112:113], v[136:137] neg_lo:[0,1] neg_hi:[0,1]
	v_pk_mul_f32 v[128:129], v[108:109], s[16:17] op_sel:[1,0] op_sel_hi:[1,0] neg_lo:[0,1] neg_hi:[0,0]
	v_pk_mul_f32 v[136:137], v[112:113], s[16:17] op_sel:[1,0] op_sel_hi:[1,0] neg_lo:[0,1] neg_hi:[0,1]
	v_pk_fma_f32 v[128:129], v[108:109], s[16:17], v[128:129] op_sel:[0,0,0] op_sel_hi:[0,0,1] neg_lo:[0,0,1] neg_hi:[0,1,0]
	v_pk_fma_f32 v[136:137], v[112:113], s[16:17], v[136:137] op_sel:[0,0,0] op_sel_hi:[0,0,1] neg_lo:[0,1,1] neg_hi:[0,1,0]
	v_pk_add_f32 v[158:159], v[122:123], v[130:131]
; __device__ __forceinline__ cf twc(cf ws, int k16) { if (k16 == 0) return ws; if (k16 == 4) return cf{ws.y, -ws.x}; return cmul(ws, cf{c16(k16), -s16(k16)}); }
; template <int LR> __device__ __forceinline__ void dif_reg(cf (&x)[1 << LR], cf w) {
;     constexpr int R = 1 << LR; cf ws = w;
; #pragma unroll
;     for (int s = 0; s < LR; ++s) { const int half = R >> (s + 1);
; #pragma unroll
;         for (int m0 = 0; m0 < R; m0 += 2 * half)
; #pragma unroll
;             for (int mm = 0; mm < half; ++mm) { const int ia = m0 + mm, ib = ia + half; const cf a = x[ia], b = x[ib];
;                 x[ia] = cf{a.x + b.x, a.y + b.y}; const cf d{a.x - b.x, a.y - b.y};
;                 x[ib] = cmul(d, twc(ws, (mm << s) * (16 / R))); }
;         ws = cmul(ws, ws); }
; }
; __device__ __forceinline__ void fft_conv(ldsf2 buf, const LAS unsigned* spec) {
;     ...
;       dif_reg<4>(x, cf{1.0f, 0.0f});
; #pragma unroll
;       for (int m = 0; m < 16; ++m) { const h2_t hv = __builtin_bit_cast(h2_t, spec[tid * 17 + m]); x[m] = cmul(x[m], cf{(float)hv.x, (float)hv.y}); }
	v_pk_add_f32 v[170:171], v[124:125], v[132:133]
	v_pk_add_f32 v[106:107], v[88:89], v[92:93]
	v_pk_add_f32 v[82:83], v[116:117], v[120:121]
	v_pk_add_f32 v[122:123], v[122:123], v[130:131] neg_lo:[0,1] neg_hi:[0,1]
	v_pk_add_f32 v[124:125], v[124:125], v[132:133] op_sel:[1,1] op_sel_hi:[0,0] neg_lo:[0,1] neg_hi:[1,0]
	v_pk_add_f32 v[88:89], v[88:89], v[92:93] neg_lo:[0,1] neg_hi:[0,1]
	v_pk_add_f32 v[116:117], v[116:117], v[120:121] op_sel:[1,1] op_sel_hi:[0,0] neg_lo:[0,1] neg_hi:[1,0]
	v_pk_add_f32 v[84:85], v[140:141], v[154:155]
	v_pk_add_f32 v[86:87], v[152:153], v[156:157]
	v_pk_add_f32 v[126:127], v[80:81], v[110:111]
	v_pk_add_f32 v[100:101], v[128:129], v[136:137]
	v_pk_add_f32 v[140:141], v[140:141], v[154:155] neg_lo:[0,1] neg_hi:[0,1]
	v_pk_add_f32 v[152:153], v[152:153], v[156:157] op_sel:[1,1] op_sel_hi:[0,0] neg_lo:[0,1] neg_hi:[1,0]
	v_pk_add_f32 v[80:81], v[80:81], v[110:111] neg_lo:[0,1] neg_hi:[0,1]
	v_pk_add_f32 v[128:129], v[128:129], v[136:137] op_sel:[1,1] op_sel_hi:[0,0] neg_lo:[0,1] neg_hi:[1,0]
	v_pk_add_f32 v[102:103], v[158:159], v[170:171]
	v_pk_add_f32 v[104:105], v[122:123], v[124:125]
	v_pk_add_f32 v[96:97], v[106:107], v[82:83]
	v_pk_add_f32 v[90:91], v[88:89], v[116:117]
	v_pk_add_f32 v[158:159], v[158:159], v[170:171] neg_lo:[0,1] neg_hi:[0,1]
	v_pk_add_f32 v[122:123], v[122:123], v[124:125] neg_lo:[0,1] neg_hi:[0,1]
	v_pk_add_f32 v[106:107], v[106:107], v[82:83] neg_lo:[0,1] neg_hi:[0,1]
	v_pk_add_f32 v[88:89], v[88:89], v[116:117] neg_lo:[0,1] neg_hi:[0,1]
	v_pk_add_f32 v[118:119], v[84:85], v[86:87]
	v_pk_add_f32 v[94:95], v[140:141], v[152:153]
	v_pk_add_f32 v[98:99], v[126:127], v[100:101]
	v_pk_add_f32 v[108:109], v[80:81], v[128:129]
	v_pk_add_f32 v[84:85], v[84:85], v[86:87] neg_lo:[0,1] neg_hi:[0,1]
	v_pk_add_f32 v[140:141], v[140:141], v[152:153] neg_lo:[0,1] neg_hi:[0,1]
	v_pk_add_f32 v[126:127], v[126:127], v[100:101] neg_lo:[0,1] neg_hi:[0,1]
	v_pk_add_f32 v[80:81], v[80:81], v[128:129] neg_lo:[0,1] neg_hi:[0,1]
	s_waitcnt lgkmcnt(0)
	v_cvt_f32_f16_e32 v134, v160
	v_cvt_f32_f16_e32 v130, v161
	v_cvt_f32_f16_e32 v92, v162
	v_cvt_f32_f16_e32 v154, v163
	v_cvt_f32_f16_sdwa v135, v160 dst_sel:DWORD dst_unused:UNUSED_PAD src0_sel:WORD_1
	v_cvt_f32_f16_sdwa v131, v161 dst_sel:DWORD dst_unused:UNUSED_PAD src0_sel:WORD_1
	v_cvt_f32_f16_sdwa v93, v162 dst_sel:DWORD dst_unused:UNUSED_PAD src0_sel:WORD_1
	v_cvt_f32_f16_sdwa v155, v163 dst_sel:DWORD dst_unused:UNUSED_PAD src0_sel:WORD_1
	v_pk_mul_f32 v[112:113], v[102:103], v[134:135] op_sel:[1,1] op_sel_hi:[1,0]
	v_pk_mul_f32 v[132:133], v[158:159], v[130:131] op_sel:[1,1] op_sel_hi:[1,0]
	v_pk_mul_f32 v[120:121], v[104:105], v[92:93] op_sel:[1,1] op_sel_hi:[1,0]
	v_pk_mul_f32 v[156:157], v[122:123], v[154:155] op_sel:[1,1] op_sel_hi:[1,0]
	v_pk_fma_f32 v[134:135], v[102:103], v[134:135], v[112:113] op_sel:[0,0,0] op_sel_hi:[0,1,1] neg_lo:[0,0,1] neg_hi:[0,0,0]
	v_pk_fma_f32 v[130:131], v[158:159], v[130:131], v[132:133] op_sel:[0,0,0] op_sel_hi:[0,1,1] neg_lo:[0,0,1] neg_hi:[0,0,0]
	v_pk_fma_f32 v[92:93], v[104:105], v[92:93], v[120:121] op_sel:[0,0,0] op_sel_hi:[0,1,1] neg_lo:[0,0,1] neg_hi:[0,0,0]
	v_pk_fma_f32 v[154:155], v[122:123], v[154:155], v[156:157] op_sel:[0,0,0] op_sel_hi:[0,1,1] neg_lo:[0,0,1] neg_hi:[0,0,0]
	v_cvt_f32_f16_e32 v110, v164
	v_cvt_f32_f16_e32 v170, v165
	v_cvt_f32_f16_e32 v82, v166
	v_cvt_f32_f16_e32 v86, v167
	v_cvt_f32_f16_sdwa v111, v164 dst_sel:DWORD dst_unused:UNUSED_PAD src0_sel:WORD_1
	v_cvt_f32_f16_sdwa v171, v165 dst_sel:DWORD dst_unused:UNUSED_PAD src0_sel:WORD_1
	v_cvt_f32_f16_sdwa v83, v166 dst_sel:DWORD dst_unused:UNUSED_PAD src0_sel:WORD_1
	v_cvt_f32_f16_sdwa v87, v167 dst_sel:DWORD dst_unused:UNUSED_PAD src0_sel:WORD_1
	v_pk_mul_f32 v[136:137], v[96:97], v[110:111] op_sel:[1,1] op_sel_hi:[1,0]
	v_pk_mul_f32 v[124:125], v[106:107], v[170:171] op_sel:[1,1] op_sel_hi:[1,0]
	v_pk_mul_f32 v[116:117], v[90:91], v[82:83] op_sel:[1,1] op_sel_hi:[1,0]
	v_pk_mul_f32 v[152:153], v[88:89], v[86:87] op_sel:[1,1] op_sel_hi:[1,0]
	v_pk_fma_f32 v[110:111], v[96:97], v[110:111], v[136:137] op_sel:[0,0,0] op_sel_hi:[0,1,1] neg_lo:[0,0,1] neg_hi:[0,0,0]
	v_pk_fma_f32 v[170:171], v[106:107], v[170:171], v[124:125] op_sel:[0,0,0] op_sel_hi:[0,1,1] neg_lo:[0,0,1] neg_hi:[0,0,0]
	v_pk_fma_f32 v[82:83], v[90:91], v[82:83], v[116:117] op_sel:[0,0,0] op_sel_hi:[0,1,1] neg_lo:[0,0,1] neg_hi:[0,0,0]
	v_pk_fma_f32 v[86:87], v[88:89], v[86:87], v[152:153] op_sel:[0,0,0] op_sel_hi:[0,1,1] neg_lo:[0,0,1] neg_hi:[0,0,0]
	v_cvt_f32_f16_e32 v100, v168
	v_cvt_f32_f16_e32 v112, v169
	v_cvt_f32_f16_e32 v132, v142
	v_cvt_f32_f16_e32 v120, v143
	v_cvt_f32_f16_sdwa v101, v168 dst_sel:DWORD dst_unused:UNUSED_PAD src0_sel:WORD_1
	v_cvt_f32_f16_sdwa v113, v169 dst_sel:DWORD dst_unused:UNUSED_PAD src0_sel:WORD_1
	v_cvt_f32_f16_sdwa v133, v142 dst_sel:DWORD dst_unused:UNUSED_PAD src0_sel:WORD_1
	v_cvt_f32_f16_sdwa v121, v143 dst_sel:DWORD dst_unused:UNUSED_PAD src0_sel:WORD_1
	v_pk_mul_f32 v[128:129], v[118:119], v[100:101] op_sel:[1,1] op_sel_hi:[1,0]
	v_pk_mul_f32 v[102:103], v[84:85], v[112:113] op_sel:[1,1] op_sel_hi:[1,0]
	v_pk_mul_f32 v[158:159], v[94:95], v[132:133] op_sel:[1,1] op_sel_hi:[1,0]
	v_pk_mul_f32 v[104:105], v[140:141], v[120:121] op_sel:[1,1] op_sel_hi:[1,0]
	v_pk_fma_f32 v[100:101], v[118:119], v[100:101], v[128:129] op_sel:[0,0,0] op_sel_hi:[0,1,1] neg_lo:[0,0,1] neg_hi:[0,0,0]
	v_pk_fma_f32 v[112:113], v[84:85], v[112:113], v[102:103] op_sel:[0,0,0] op_sel_hi:[0,1,1] neg_lo:[0,0,1] neg_hi:[0,0,0]
	v_pk_fma_f32 v[132:133], v[94:95], v[132:133], v[158:159] op_sel:[0,0,0] op_sel_hi:[0,1,1] neg_lo:[0,0,1] neg_hi:[0,0,0]
; __device__ __forceinline__ cf twc(cf ws, int k16) { if (k16 == 0) return ws; if (k16 == 4) return cf{ws.y, -ws.x}; return cmul(ws, cf{c16(k16), -s16(k16)}); }
; template <int LR> __device__ __forceinline__ void dit_reg(cf (&x)[1 << LR], cf w) {
;     constexpr int R = 1 << LR; cf wsv[LR]; wsv[0] = w;
; #pragma unroll
;     for (int s = 1; s < LR; ++s) wsv[s] = cmul(wsv[s - 1], wsv[s - 1]);
; #pragma unroll
;     for (int s = LR - 1; s >= 0; --s) { const int half = R >> (s + 1);
; #pragma unroll
;         for (int m0 = 0; m0 < R; m0 += 2 * half)
; #pragma unroll
;             for (int mm = 0; mm < half; ++mm) { const int ia = m0 + mm, ib = ia + half; const cf a = x[ia];
;                 const cf b = cmulc(x[ib], twc(wsv[s], (mm << s) * (16 / R)));
;                 x[ia] = cf{a.x + b.x, a.y + b.y}; x[ib] = cf{a.x - b.x, a.y - b.y}; } }
; }
; __device__ __forceinline__ void fft_conv(ldsf2 buf, const LAS unsigned* spec) {
;     ...
;       for (int m = 0; m < 16; ++m) { const h2_t hv = __builtin_bit_cast(h2_t, spec[tid * 17 + m]); x[m] = cmul(x[m], cf{(float)hv.x, (float)hv.y}); }
;       dit_reg<4>(x, cf{1.0f, 0.0f});
	v_pk_fma_f32 v[120:121], v[140:141], v[120:121], v[104:105] op_sel:[0,0,0] op_sel_hi:[0,1,1] neg_lo:[0,0,1] neg_hi:[0,0,0]
	v_cvt_f32_f16_e32 v156, v138
	v_cvt_f32_f16_e32 v136, v139
	v_cvt_f32_f16_e32 v124, v172
	v_cvt_f32_f16_e32 v116, v173
	v_cvt_f32_f16_sdwa v157, v138 dst_sel:DWORD dst_unused:UNUSED_PAD src0_sel:WORD_1
	v_cvt_f32_f16_sdwa v137, v139 dst_sel:DWORD dst_unused:UNUSED_PAD src0_sel:WORD_1
	v_cvt_f32_f16_sdwa v125, v172 dst_sel:DWORD dst_unused:UNUSED_PAD src0_sel:WORD_1
	v_cvt_f32_f16_sdwa v117, v173 dst_sel:DWORD dst_unused:UNUSED_PAD src0_sel:WORD_1
	v_pk_mul_f32 v[122:123], v[98:99], v[156:157] op_sel:[1,1] op_sel_hi:[1,0]
	v_pk_mul_f32 v[96:97], v[126:127], v[136:137] op_sel:[1,1] op_sel_hi:[1,0]
	v_pk_mul_f32 v[106:107], v[108:109], v[124:125] op_sel:[1,1] op_sel_hi:[1,0]
	v_pk_mul_f32 v[90:91], v[80:81], v[116:117] op_sel:[1,1] op_sel_hi:[1,0]
	v_pk_fma_f32 v[156:157], v[98:99], v[156:157], v[122:123] op_sel:[0,0,0] op_sel_hi:[0,1,1] neg_lo:[0,0,1] neg_hi:[0,0,0]
	v_pk_fma_f32 v[136:137], v[126:127], v[136:137], v[96:97] op_sel:[0,0,0] op_sel_hi:[0,1,1] neg_lo:[0,0,1] neg_hi:[0,0,0]
	v_pk_fma_f32 v[124:125], v[108:109], v[124:125], v[106:107] op_sel:[0,0,0] op_sel_hi:[0,1,1] neg_lo:[0,0,1] neg_hi:[0,0,0]
	v_pk_fma_f32 v[116:117], v[80:81], v[116:117], v[90:91] op_sel:[0,0,0] op_sel_hi:[0,1,1] neg_lo:[0,0,1] neg_hi:[0,0,0]
	v_pk_add_f32 v[152:153], v[134:135], v[130:131]
	v_pk_add_f32 v[88:89], v[92:93], v[154:155]
	v_pk_add_f32 v[128:129], v[110:111], v[170:171]
	v_pk_add_f32 v[118:119], v[82:83], v[86:87]
	v_pk_add_f32 v[134:135], v[134:135], v[130:131] neg_lo:[0,1] neg_hi:[0,1]
	v_pk_add_f32 v[92:93], v[92:93], v[154:155] neg_lo:[0,1] neg_hi:[0,1]
	v_pk_add_f32 v[110:111], v[110:111], v[170:171] neg_lo:[0,1] neg_hi:[0,1]
	v_pk_add_f32 v[82:83], v[82:83], v[86:87] neg_lo:[0,1] neg_hi:[0,1]
	v_pk_add_f32 v[102:103], v[100:101], v[112:113]
	v_pk_add_f32 v[84:85], v[132:133], v[120:121]
	v_pk_add_f32 v[158:159], v[156:157], v[136:137]
	v_pk_add_f32 v[94:95], v[124:125], v[116:117]
	v_pk_add_f32 v[100:101], v[100:101], v[112:113] neg_lo:[0,1] neg_hi:[0,1]
	v_pk_add_f32 v[132:133], v[132:133], v[120:121] neg_lo:[0,1] neg_hi:[0,1]
	v_pk_add_f32 v[156:157], v[156:157], v[136:137] neg_lo:[0,1] neg_hi:[0,1]
	v_pk_add_f32 v[124:125], v[124:125], v[116:117] neg_lo:[0,1] neg_hi:[0,1]
	v_pk_add_f32 v[104:105], v[152:153], v[88:89]
	v_pk_add_f32 v[140:141], v[134:135], v[92:93] op_sel:[0,1] op_sel_hi:[1,0] neg_lo:[0,1] neg_hi:[0,0]
	v_pk_add_f32 v[122:123], v[128:129], v[118:119]
	v_pk_add_f32 v[98:99], v[110:111], v[82:83] op_sel:[0,1] op_sel_hi:[1,0] neg_lo:[0,1] neg_hi:[0,0]
	v_pk_add_f32 v[152:153], v[152:153], v[88:89] neg_lo:[0,1] neg_hi:[0,1]
	v_pk_add_f32 v[134:135], v[134:135], v[92:93] op_sel:[0,1] op_sel_hi:[1,0] neg_lo:[0,0] neg_hi:[0,1]
	v_pk_add_f32 v[128:129], v[128:129], v[118:119] neg_lo:[0,1] neg_hi:[0,1]
	v_pk_add_f32 v[110:111], v[110:111], v[82:83] op_sel:[0,1] op_sel_hi:[1,0] neg_lo:[0,0] neg_hi:[0,1]
	v_pk_add_f32 v[96:97], v[102:103], v[84:85]
	v_pk_add_f32 v[126:127], v[100:101], v[132:133] op_sel:[0,1] op_sel_hi:[1,0] neg_lo:[0,1] neg_hi:[0,0]
	v_pk_add_f32 v[106:107], v[158:159], v[94:95]
	v_pk_add_f32 v[108:109], v[156:157], v[124:125] op_sel:[0,1] op_sel_hi:[1,0] neg_lo:[0,1] neg_hi:[0,0]
	v_pk_add_f32 v[102:103], v[102:103], v[84:85] neg_lo:[0,1] neg_hi:[0,1]
	v_pk_add_f32 v[100:101], v[100:101], v[132:133] op_sel:[0,1] op_sel_hi:[1,0] neg_lo:[0,0] neg_hi:[0,1]
	v_pk_add_f32 v[158:159], v[158:159], v[94:95] neg_lo:[0,1] neg_hi:[0,1]
	v_pk_add_f32 v[156:157], v[156:157], v[124:125] op_sel:[0,1] op_sel_hi:[1,0] neg_lo:[0,0] neg_hi:[0,1]
	v_pk_add_f32 v[90:91], v[104:105], v[122:123]
	v_pk_mul_f32 v[80:81], v[98:99], s[16:17] op_sel:[1,0] op_sel_hi:[1,0] neg_lo:[0,1] neg_hi:[0,0]
	v_pk_add_f32 v[130:131], v[152:153], v[128:129] op_sel:[0,1] op_sel_hi:[1,0] neg_lo:[0,1] neg_hi:[0,0]
	v_pk_mul_f32 v[154:155], v[110:111], s[16:17] op_sel:[1,0] op_sel_hi:[1,0] neg_lo:[0,1] neg_hi:[0,1]
	v_pk_add_f32 v[104:105], v[104:105], v[122:123] neg_lo:[0,1] neg_hi:[0,1]
	v_pk_fma_f32 v[80:81], v[98:99], s[16:17], v[80:81] op_sel:[0,0,0] op_sel_hi:[0,0,1] neg_lo:[0,0,0] neg_hi:[0,0,0]
	v_pk_add_f32 v[152:153], v[152:153], v[128:129] op_sel:[0,1] op_sel_hi:[1,0] neg_lo:[0,0] neg_hi:[0,1]
	v_pk_fma_f32 v[154:155], v[110:111], s[16:17], v[154:155] op_sel:[0,0,0] op_sel_hi:[0,0,1] neg_lo:[0,1,0] neg_hi:[0,0,0]
; __device__ __forceinline__ cf twc(cf ws, int k16) { if (k16 == 0) return ws; if (k16 == 4) return cf{ws.y, -ws.x}; return cmul(ws, cf{c16(k16), -s16(k16)}); }
; __device__ __forceinline__ void wave_lds_fence() { asm volatile("s_waitcnt lgkmcnt(0)" ::: "memory"); }
; template <int LR> __device__ __forceinline__ void dit_reg(cf (&x)[1 << LR], cf w) {
;     constexpr int R = 1 << LR; cf wsv[LR]; wsv[0] = w;
; #pragma unroll
;     for (int s = 1; s < LR; ++s) wsv[s] = cmul(wsv[s - 1], wsv[s - 1]);
; #pragma unroll
;     for (int s = LR - 1; s >= 0; --s) { const int half = R >> (s + 1);
; #pragma unroll
;         for (int m0 = 0; m0 < R; m0 += 2 * half)
; #pragma unroll
;             for (int mm = 0; mm < half; ++mm) { const int ia = m0 + mm, ib = ia + half; const cf a = x[ia];
;                 const cf b = cmulc(x[ib], twc(wsv[s], (mm << s) * (16 / R)));
;                 x[ia] = cf{a.x + b.x, a.y + b.y}; x[ib] = cf{a.x - b.x, a.y - b.y}; } }
; }
; __device__ __forceinline__ void fft_conv(ldsf2 buf, const LAS unsigned* spec) {
;     ...
;       dit_reg<4>(x, cf{1.0f, 0.0f});
; #pragma unroll
;       for (int m = 0; m < 16; ++m) buf[tid * 17 + m] = mkv2(x[m].x, x[m].y); }
;     wave_lds_fence();
;     fft_inv_cba(buf);
	v_pk_add_f32 v[98:99], v[140:141], v[80:81] neg_lo:[0,1] neg_hi:[0,1]
	v_pk_add_f32 v[110:111], v[134:135], v[154:155] neg_lo:[0,1] neg_hi:[0,1]
	v_pk_add_f32 v[140:141], v[140:141], v[80:81]
	v_pk_add_f32 v[134:135], v[134:135], v[154:155]
	v_pk_add_f32 v[170:171], v[96:97], v[106:107]
	v_pk_mul_f32 v[86:87], v[108:109], s[16:17] op_sel:[1,0] op_sel_hi:[1,0] neg_lo:[0,1] neg_hi:[0,0]
	v_pk_add_f32 v[112:113], v[102:103], v[158:159] op_sel:[0,1] op_sel_hi:[1,0] neg_lo:[0,1] neg_hi:[0,0]
	v_pk_mul_f32 v[120:121], v[156:157], s[16:17] op_sel:[1,0] op_sel_hi:[1,0] neg_lo:[0,1] neg_hi:[0,1]
	v_pk_add_f32 v[96:97], v[96:97], v[106:107] neg_lo:[0,1] neg_hi:[0,1]
	v_pk_fma_f32 v[86:87], v[108:109], s[16:17], v[86:87] op_sel:[0,0,0] op_sel_hi:[0,0,1] neg_lo:[0,0,0] neg_hi:[0,0,0]
	v_pk_add_f32 v[102:103], v[102:103], v[158:159] op_sel:[0,1] op_sel_hi:[1,0] neg_lo:[0,0] neg_hi:[0,1]
	v_pk_fma_f32 v[120:121], v[156:157], s[16:17], v[120:121] op_sel:[0,0,0] op_sel_hi:[0,0,1] neg_lo:[0,1,0] neg_hi:[0,0,0]
	v_pk_add_f32 v[108:109], v[126:127], v[86:87] neg_lo:[0,1] neg_hi:[0,1]
	v_pk_add_f32 v[156:157], v[100:101], v[120:121] neg_lo:[0,1] neg_hi:[0,1]
	v_pk_add_f32 v[126:127], v[126:127], v[86:87]
	v_pk_add_f32 v[100:101], v[100:101], v[120:121]
	v_pk_add_f32 v[136:137], v[90:91], v[170:171]
	v_pk_mul_f32 v[116:117], v[126:127], s[4:5] op_sel:[1,1] op_sel_hi:[1,0] neg_lo:[0,1] neg_hi:[0,0]
	v_pk_mul_f32 v[88:89], v[112:113], s[16:17] op_sel:[1,0] op_sel_hi:[1,0] neg_lo:[0,1] neg_hi:[0,0]
	v_pk_mul_f32 v[92:93], v[100:101], s[4:5] op_sel:[1,0] op_sel_hi:[1,1] neg_lo:[0,1] neg_hi:[0,0]
	v_pk_add_f32 v[90:91], v[90:91], v[170:171] neg_lo:[0,1] neg_hi:[0,1]
	v_pk_fma_f32 v[116:117], v[126:127], s[4:5], v[116:117] op_sel:[0,0,0] op_sel_hi:[0,1,1] neg_lo:[0,0,0] neg_hi:[0,0,0]
	v_pk_fma_f32 v[88:89], v[112:113], s[16:17], v[88:89] op_sel:[0,0,0] op_sel_hi:[0,0,1] neg_lo:[0,0,0] neg_hi:[0,0,0]
	v_pk_fma_f32 v[92:93], v[100:101], s[4:5], v[92:93] op_sel:[0,1,0] op_sel_hi:[0,0,1] neg_lo:[0,0,0] neg_hi:[0,0,0]
	v_pk_add_f32 v[126:127], v[140:141], v[116:117] neg_lo:[0,1] neg_hi:[0,1]
	v_pk_add_f32 v[112:113], v[130:131], v[88:89] neg_lo:[0,1] neg_hi:[0,1]
	v_pk_add_f32 v[100:101], v[134:135], v[92:93] neg_lo:[0,1] neg_hi:[0,1]
	v_pk_add_f32 v[140:141], v[140:141], v[116:117]
	v_pk_add_f32 v[130:131], v[130:131], v[88:89]
	v_pk_add_f32 v[134:135], v[134:135], v[92:93]
	v_pk_add_f32 v[118:119], v[104:105], v[96:97] op_sel:[0,1] op_sel_hi:[1,0] neg_lo:[0,1] neg_hi:[0,0]
	v_pk_mul_f32 v[82:83], v[108:109], s[4:5] op_sel:[1,0] op_sel_hi:[1,1] neg_lo:[0,1] neg_hi:[0,1]
	v_pk_mul_f32 v[84:85], v[102:103], s[16:17] op_sel:[1,0] op_sel_hi:[1,0] neg_lo:[0,1] neg_hi:[0,1]
	v_pk_mul_f32 v[132:133], v[156:157], s[4:5] op_sel:[1,1] op_sel_hi:[1,0] neg_lo:[0,1] neg_hi:[0,1]
	v_pk_add_f32 v[104:105], v[104:105], v[96:97] op_sel:[0,1] op_sel_hi:[1,0] neg_lo:[0,0] neg_hi:[0,1]
	v_pk_fma_f32 v[82:83], v[108:109], s[4:5], v[82:83] op_sel:[0,1,0] op_sel_hi:[0,0,1] neg_lo:[0,1,0] neg_hi:[0,0,0]
	v_pk_fma_f32 v[84:85], v[102:103], s[16:17], v[84:85] op_sel:[0,0,0] op_sel_hi:[0,0,1] neg_lo:[0,1,0] neg_hi:[0,0,0]
	v_pk_fma_f32 v[132:133], v[156:157], s[4:5], v[132:133] op_sel:[0,0,0] op_sel_hi:[0,1,1] neg_lo:[0,1,0] neg_hi:[0,0,0]
	v_pk_add_f32 v[108:109], v[98:99], v[82:83] neg_lo:[0,1] neg_hi:[0,1]
	v_pk_add_f32 v[102:103], v[152:153], v[84:85] neg_lo:[0,1] neg_hi:[0,1]
	v_pk_add_f32 v[156:157], v[110:111], v[132:133] neg_lo:[0,1] neg_hi:[0,1]
	v_pk_add_f32 v[98:99], v[98:99], v[82:83]
	v_pk_add_f32 v[152:153], v[152:153], v[84:85]
	v_pk_add_f32 v[110:111], v[110:111], v[132:133]
	ds_write2_b64 v151, v[136:137], v[140:141] offset1:1
	ds_write2_b64 v151, v[130:131], v[134:135] offset0:2 offset1:3
	ds_write2_b64 v151, v[118:119], v[98:99] offset0:4 offset1:5
	ds_write2_b64 v151, v[152:153], v[110:111] offset0:6 offset1:7
	ds_write2_b64 v151, v[90:91], v[126:127] offset0:8 offset1:9
	ds_write2_b64 v151, v[112:113], v[100:101] offset0:10 offset1:11
	ds_write2_b64 v151, v[104:105], v[108:109] offset0:12 offset1:13
	ds_write2_b64 v151, v[102:103], v[156:157] offset0:14 offset1:15
	v_mov_b32_e32 v78, v195
	s_waitcnt lgkmcnt(0)
	s_mov_b32 s0, 0
	v_and_b32_e32 v81, 15, v78
	v_lshlrev_b32_e32 v80, 4, v78
	v_lshlrev_b32_e32 v83, 9, v81
	v_and_b32_e32 v80, 0xfffffc00, v80
	v_lshlrev_b32_e32 v82, 3, v78
	v_add_u32_e32 v83, 0, v83
	v_and_b32_e32 v79, 63, v78
	v_lshl_add_u32 v81, v81, 3, 0
	v_and_or_b32 v82, v82, s90, v80
	v_add_u32_e32 v83, 0x22000, v83
